# MFMA order variant KZ (per-cluster zigzag; accumulator pairs, alternating SrcB/SrcA reuse), all 12 loops
# speedup vs baseline: 1.0233x; 1.0233x over previous
.LBB0_272:
	s_add_u32 s58, s22, 0xfff00000
	s_addc_u32 s59, s23, -1
	s_mov_b32 m0, s36
	ds_read_b128 v[154:157], v148
	global_load_lds_dwordx4 v130, s[58:59]
	s_mov_b32 m0, s37
	ds_read_b128 v[158:161], v148 offset:1024
	global_load_lds_dwordx4 v134, s[58:59]
	s_mov_b32 m0, s40
	ds_read_b128 v[164:167], v148 offset:2048
	global_load_lds_dwordx4 v142, s[22:23]
	s_mov_b32 m0, s41
	ds_read_b128 v[168:171], v148 offset:3072
	global_load_lds_dwordx4 v144, s[22:23]
	ds_read_b128 v[172:175], v149
	ds_read_b128 v[176:179], v149 offset:1024
	ds_read_b128 v[180:183], v149 offset:2048
	ds_read_b128 v[184:187], v149 offset:3072
	s_add_u32 s24, s22, 0xfff00080
	s_addc_u32 s25, s23, -1
	s_cmp_eq_u32 s56, 60
	s_cselect_b32 s27, s51, s25
	s_cselect_b32 s26, s52, s24
	s_cselect_b32 s25, s7, s55
	s_cselect_b32 s24, s53, s54
	ds_read_b128 v[188:191], v150
	ds_read_b128 v[192:195], v150 offset:1024
	ds_read_b128 v[196:199], v150 offset:2048
	ds_read_b128 v[200:203], v150 offset:3072
	ds_read_b128 v[204:207], v150 offset:4096
	ds_read_b128 v[208:211], v150 offset:5120
	ds_read_b128 v[212:215], v150 offset:6144
	ds_read_b128 v[216:219], v150 offset:7168
	s_waitcnt vmcnt(8)
	s_waitcnt lgkmcnt(0)
	s_barrier
	s_setprio 1
	s_waitcnt lgkmcnt(0)
	v_mfma_f32_16x16x32_bf16 v[126:129], v[154:157], v[188:191], v[126:129]
	v_mfma_f32_16x16x32_bf16 v[126:129], v[158:161], v[192:195], v[126:129]
	v_mfma_f32_16x16x32_bf16 v[122:125], v[168:171], v[192:195], v[122:125]
	v_mfma_f32_16x16x32_bf16 v[122:125], v[164:167], v[188:191], v[122:125]
	v_mfma_f32_16x16x32_bf16 v[114:117], v[164:167], v[196:199], v[114:117]
	v_mfma_f32_16x16x32_bf16 v[114:117], v[168:171], v[200:203], v[114:117]
	v_mfma_f32_16x16x32_bf16 v[118:121], v[158:161], v[200:203], v[118:121]
	v_mfma_f32_16x16x32_bf16 v[118:121], v[154:157], v[196:199], v[118:121]
	v_mfma_f32_16x16x32_bf16 v[102:105], v[154:157], v[204:207], v[102:105]
	v_mfma_f32_16x16x32_bf16 v[102:105], v[158:161], v[208:211], v[102:105]
	v_mfma_f32_16x16x32_bf16 v[98:101], v[168:171], v[208:211], v[98:101]
	v_mfma_f32_16x16x32_bf16 v[98:101], v[164:167], v[204:207], v[98:101]
	v_mfma_f32_16x16x32_bf16 v[82:85], v[164:167], v[212:215], v[82:85]
	v_mfma_f32_16x16x32_bf16 v[82:85], v[168:171], v[216:219], v[82:85]
	v_mfma_f32_16x16x32_bf16 v[86:89], v[158:161], v[216:219], v[86:89]
	v_mfma_f32_16x16x32_bf16 v[86:89], v[154:157], v[212:215], v[86:89]
	v_mfma_f32_16x16x32_bf16 v[70:73], v[172:175], v[212:215], v[70:73]
	v_mfma_f32_16x16x32_bf16 v[70:73], v[176:179], v[216:219], v[70:73]
	v_mfma_f32_16x16x32_bf16 v[66:69], v[184:187], v[216:219], v[66:69]
	v_mfma_f32_16x16x32_bf16 v[66:69], v[180:183], v[212:215], v[66:69]
	v_mfma_f32_16x16x32_bf16 v[74:77], v[180:183], v[204:207], v[74:77]
	v_mfma_f32_16x16x32_bf16 v[74:77], v[184:187], v[208:211], v[74:77]
	v_mfma_f32_16x16x32_bf16 v[78:81], v[176:179], v[208:211], v[78:81]
	v_mfma_f32_16x16x32_bf16 v[78:81], v[172:175], v[204:207], v[78:81]
	v_mfma_f32_16x16x32_bf16 v[94:97], v[172:175], v[196:199], v[94:97]
	v_mfma_f32_16x16x32_bf16 v[94:97], v[176:179], v[200:203], v[94:97]
	v_mfma_f32_16x16x32_bf16 v[90:93], v[184:187], v[200:203], v[90:93]
	v_mfma_f32_16x16x32_bf16 v[90:93], v[180:183], v[196:199], v[90:93]
	v_mfma_f32_16x16x32_bf16 v[106:109], v[180:183], v[188:191], v[106:109]
	v_mfma_f32_16x16x32_bf16 v[106:109], v[184:187], v[192:195], v[106:109]
	v_mfma_f32_16x16x32_bf16 v[110:113], v[176:179], v[192:195], v[110:113]
	v_mfma_f32_16x16x32_bf16 v[110:113], v[172:175], v[188:191], v[110:113]
	s_setprio 0
	s_barrier
	s_mov_b32 m0, s42
	s_add_u32 s58, s24, 0x100000
	global_load_lds_dwordx4 v132, s[24:25]
	s_mov_b32 m0, s43
	s_addc_u32 s59, s25, 0
	global_load_lds_dwordx4 v136, s[24:25]
	s_mov_b32 m0, s44
	ds_read_b128 v[188:191], v150 offset:16384
	global_load_lds_dwordx4 v132, s[58:59]
	s_mov_b32 m0, s45
	ds_read_b128 v[192:195], v150 offset:17408
	global_load_lds_dwordx4 v136, s[58:59]
	ds_read_b128 v[196:199], v150 offset:18432
	ds_read_b128 v[200:203], v150 offset:19456
	ds_read_b128 v[204:207], v150 offset:20480
	ds_read_b128 v[208:211], v150 offset:21504
	ds_read_b128 v[212:215], v150 offset:22528
	ds_read_b128 v[216:219], v150 offset:23552
	s_waitcnt vmcnt(6)
	s_waitcnt lgkmcnt(0)
	s_barrier
	s_setprio 1
	s_waitcnt lgkmcnt(0)
	v_mfma_f32_16x16x32_bf16 v[62:65], v[154:157], v[188:191], v[62:65]
	v_mfma_f32_16x16x32_bf16 v[62:65], v[158:161], v[192:195], v[62:65]
	v_mfma_f32_16x16x32_bf16 v[58:61], v[168:171], v[192:195], v[58:61]
	v_mfma_f32_16x16x32_bf16 v[58:61], v[164:167], v[188:191], v[58:61]
	v_mfma_f32_16x16x32_bf16 v[50:53], v[164:167], v[196:199], v[50:53]
	v_mfma_f32_16x16x32_bf16 v[50:53], v[168:171], v[200:203], v[50:53]
	v_mfma_f32_16x16x32_bf16 v[54:57], v[158:161], v[200:203], v[54:57]
	v_mfma_f32_16x16x32_bf16 v[54:57], v[154:157], v[196:199], v[54:57]
	v_mfma_f32_16x16x32_bf16 v[38:41], v[154:157], v[204:207], v[38:41]
	v_mfma_f32_16x16x32_bf16 v[38:41], v[158:161], v[208:211], v[38:41]
	v_mfma_f32_16x16x32_bf16 v[34:37], v[168:171], v[208:211], v[34:37]
	v_mfma_f32_16x16x32_bf16 v[34:37], v[164:167], v[204:207], v[34:37]
	v_mfma_f32_16x16x32_bf16 v[18:21], v[164:167], v[212:215], v[18:21]
	v_mfma_f32_16x16x32_bf16 v[18:21], v[168:171], v[216:219], v[18:21]
	v_mfma_f32_16x16x32_bf16 v[22:25], v[158:161], v[216:219], v[22:25]
	v_mfma_f32_16x16x32_bf16 v[22:25], v[154:157], v[212:215], v[22:25]
	v_mfma_f32_16x16x32_bf16 v[6:9], v[172:175], v[212:215], v[6:9]
	v_mfma_f32_16x16x32_bf16 v[6:9], v[176:179], v[216:219], v[6:9]
	v_mfma_f32_16x16x32_bf16 v[2:5], v[184:187], v[216:219], v[2:5]
	v_mfma_f32_16x16x32_bf16 v[2:5], v[180:183], v[212:215], v[2:5]
	v_mfma_f32_16x16x32_bf16 v[10:13], v[180:183], v[204:207], v[10:13]
	v_mfma_f32_16x16x32_bf16 v[10:13], v[184:187], v[208:211], v[10:13]
	v_mfma_f32_16x16x32_bf16 v[14:17], v[176:179], v[208:211], v[14:17]
	v_mfma_f32_16x16x32_bf16 v[14:17], v[172:175], v[204:207], v[14:17]
	v_mfma_f32_16x16x32_bf16 v[30:33], v[172:175], v[196:199], v[30:33]
	v_mfma_f32_16x16x32_bf16 v[30:33], v[176:179], v[200:203], v[30:33]
	v_mfma_f32_16x16x32_bf16 v[26:29], v[184:187], v[200:203], v[26:29]
	v_mfma_f32_16x16x32_bf16 v[26:29], v[180:183], v[196:199], v[26:29]
	v_mfma_f32_16x16x32_bf16 v[42:45], v[180:183], v[188:191], v[42:45]
	v_mfma_f32_16x16x32_bf16 v[42:45], v[184:187], v[192:195], v[42:45]
	v_mfma_f32_16x16x32_bf16 v[46:49], v[176:179], v[192:195], v[46:49]
	v_mfma_f32_16x16x32_bf16 v[46:49], v[172:175], v[188:191], v[46:49]
	s_setprio 0
	s_barrier
	s_mov_b32 m0, s30
	ds_read_b128 v[154:157], v151
	global_load_lds_dwordx4 v130, s[26:27]
	s_mov_b32 m0, s31
	ds_read_b128 v[158:161], v151 offset:1024
	global_load_lds_dwordx4 v134, s[26:27]
	s_add_u32 s26, s26, 0x100000
	s_addc_u32 s27, s27, 0
	s_mov_b32 m0, s33
	ds_read_b128 v[164:167], v151 offset:2048
	global_load_lds_dwordx4 v130, s[26:27]
	s_mov_b32 m0, s34
	ds_read_b128 v[168:171], v151 offset:3072
	global_load_lds_dwordx4 v134, s[26:27]
	ds_read_b128 v[172:175], v152
	ds_read_b128 v[176:179], v152 offset:1024
	ds_read_b128 v[180:183], v152 offset:2048
	ds_read_b128 v[184:187], v152 offset:3072
	ds_read_b128 v[188:191], v150 offset:32768
	ds_read_b128 v[192:195], v150 offset:33792
	ds_read_b128 v[196:199], v150 offset:34816
	ds_read_b128 v[200:203], v150 offset:35840
	ds_read_b128 v[204:207], v150 offset:36864
	ds_read_b128 v[208:211], v150 offset:37888
	ds_read_b128 v[212:215], v150 offset:38912
	ds_read_b128 v[216:219], v150 offset:39936
	s_waitcnt vmcnt(8)
	s_waitcnt lgkmcnt(0)
	s_barrier
	s_setprio 1
	s_waitcnt lgkmcnt(0)
	v_mfma_f32_16x16x32_bf16 v[126:129], v[154:157], v[188:191], v[126:129]
	v_mfma_f32_16x16x32_bf16 v[126:129], v[158:161], v[192:195], v[126:129]
	v_mfma_f32_16x16x32_bf16 v[122:125], v[168:171], v[192:195], v[122:125]
	v_mfma_f32_16x16x32_bf16 v[122:125], v[164:167], v[188:191], v[122:125]
	v_mfma_f32_16x16x32_bf16 v[114:117], v[164:167], v[196:199], v[114:117]
	v_mfma_f32_16x16x32_bf16 v[114:117], v[168:171], v[200:203], v[114:117]
	v_mfma_f32_16x16x32_bf16 v[118:121], v[158:161], v[200:203], v[118:121]
	v_mfma_f32_16x16x32_bf16 v[118:121], v[154:157], v[196:199], v[118:121]
	v_mfma_f32_16x16x32_bf16 v[102:105], v[154:157], v[204:207], v[102:105]
	v_mfma_f32_16x16x32_bf16 v[102:105], v[158:161], v[208:211], v[102:105]
	v_mfma_f32_16x16x32_bf16 v[98:101], v[168:171], v[208:211], v[98:101]
	v_mfma_f32_16x16x32_bf16 v[98:101], v[164:167], v[204:207], v[98:101]
	v_mfma_f32_16x16x32_bf16 v[82:85], v[164:167], v[212:215], v[82:85]
	v_mfma_f32_16x16x32_bf16 v[82:85], v[168:171], v[216:219], v[82:85]
	v_mfma_f32_16x16x32_bf16 v[86:89], v[158:161], v[216:219], v[86:89]
	v_mfma_f32_16x16x32_bf16 v[86:89], v[154:157], v[212:215], v[86:89]
	v_mfma_f32_16x16x32_bf16 v[70:73], v[172:175], v[212:215], v[70:73]
	v_mfma_f32_16x16x32_bf16 v[70:73], v[176:179], v[216:219], v[70:73]
	v_mfma_f32_16x16x32_bf16 v[66:69], v[184:187], v[216:219], v[66:69]
	v_mfma_f32_16x16x32_bf16 v[66:69], v[180:183], v[212:215], v[66:69]
	v_mfma_f32_16x16x32_bf16 v[74:77], v[180:183], v[204:207], v[74:77]
	v_mfma_f32_16x16x32_bf16 v[74:77], v[184:187], v[208:211], v[74:77]
	v_mfma_f32_16x16x32_bf16 v[78:81], v[176:179], v[208:211], v[78:81]
	v_mfma_f32_16x16x32_bf16 v[78:81], v[172:175], v[204:207], v[78:81]
	v_mfma_f32_16x16x32_bf16 v[94:97], v[172:175], v[196:199], v[94:97]
	v_mfma_f32_16x16x32_bf16 v[94:97], v[176:179], v[200:203], v[94:97]
	v_mfma_f32_16x16x32_bf16 v[90:93], v[184:187], v[200:203], v[90:93]
	v_mfma_f32_16x16x32_bf16 v[90:93], v[180:183], v[196:199], v[90:93]
	v_mfma_f32_16x16x32_bf16 v[106:109], v[180:183], v[188:191], v[106:109]
	v_mfma_f32_16x16x32_bf16 v[106:109], v[184:187], v[192:195], v[106:109]
	v_mfma_f32_16x16x32_bf16 v[110:113], v[176:179], v[192:195], v[110:113]
	v_mfma_f32_16x16x32_bf16 v[110:113], v[172:175], v[188:191], v[110:113]
	s_setprio 0
	s_barrier
	s_mov_b32 m0, s47
	s_add_u32 s24, s24, 0x80
	s_addc_u32 s25, s25, 0
	global_load_lds_dwordx4 v132, s[24:25]
	s_mov_b32 m0, s48
	ds_read_b128 v[188:191], v150 offset:49152
	global_load_lds_dwordx4 v136, s[24:25]
	s_add_i32 s26, s46, s29
	s_mov_b32 m0, s26
	s_add_u32 s24, s24, 0x100000
	s_addc_u32 s25, s25, 0
	global_load_lds_dwordx4 v132, s[24:25]
	s_add_i32 m0, s26, 0x2000
	ds_read_b128 v[192:195], v150 offset:50176
	global_load_lds_dwordx4 v136, s[24:25]
	ds_read_b128 v[196:199], v150 offset:51200
	ds_read_b128 v[200:203], v150 offset:52224
	ds_read_b128 v[204:207], v150 offset:53248
	ds_read_b128 v[208:211], v150 offset:54272
	ds_read_b128 v[212:215], v150 offset:55296
	ds_read_b128 v[216:219], v150 offset:56320
	s_waitcnt vmcnt(6)
	s_waitcnt lgkmcnt(0)
	s_barrier
	s_setprio 1
	s_waitcnt lgkmcnt(0)
	v_mfma_f32_16x16x32_bf16 v[62:65], v[154:157], v[188:191], v[62:65]
	v_mfma_f32_16x16x32_bf16 v[62:65], v[158:161], v[192:195], v[62:65]
	v_mfma_f32_16x16x32_bf16 v[58:61], v[168:171], v[192:195], v[58:61]
	v_mfma_f32_16x16x32_bf16 v[58:61], v[164:167], v[188:191], v[58:61]
	v_mfma_f32_16x16x32_bf16 v[50:53], v[164:167], v[196:199], v[50:53]
	v_mfma_f32_16x16x32_bf16 v[50:53], v[168:171], v[200:203], v[50:53]
	v_mfma_f32_16x16x32_bf16 v[54:57], v[158:161], v[200:203], v[54:57]
	v_mfma_f32_16x16x32_bf16 v[54:57], v[154:157], v[196:199], v[54:57]
	v_mfma_f32_16x16x32_bf16 v[38:41], v[154:157], v[204:207], v[38:41]
	v_mfma_f32_16x16x32_bf16 v[38:41], v[158:161], v[208:211], v[38:41]
	v_mfma_f32_16x16x32_bf16 v[34:37], v[168:171], v[208:211], v[34:37]
	v_mfma_f32_16x16x32_bf16 v[34:37], v[164:167], v[204:207], v[34:37]
	v_mfma_f32_16x16x32_bf16 v[18:21], v[164:167], v[212:215], v[18:21]
	v_mfma_f32_16x16x32_bf16 v[18:21], v[168:171], v[216:219], v[18:21]
	v_mfma_f32_16x16x32_bf16 v[22:25], v[158:161], v[216:219], v[22:25]
	v_mfma_f32_16x16x32_bf16 v[22:25], v[154:157], v[212:215], v[22:25]
	v_mfma_f32_16x16x32_bf16 v[6:9], v[172:175], v[212:215], v[6:9]
	v_mfma_f32_16x16x32_bf16 v[6:9], v[176:179], v[216:219], v[6:9]
	v_mfma_f32_16x16x32_bf16 v[2:5], v[184:187], v[216:219], v[2:5]
	v_mfma_f32_16x16x32_bf16 v[2:5], v[180:183], v[212:215], v[2:5]
	v_mfma_f32_16x16x32_bf16 v[10:13], v[180:183], v[204:207], v[10:13]
	v_mfma_f32_16x16x32_bf16 v[10:13], v[184:187], v[208:211], v[10:13]
	v_mfma_f32_16x16x32_bf16 v[14:17], v[176:179], v[208:211], v[14:17]
	v_mfma_f32_16x16x32_bf16 v[14:17], v[172:175], v[204:207], v[14:17]
	v_mfma_f32_16x16x32_bf16 v[30:33], v[172:175], v[196:199], v[30:33]
	v_mfma_f32_16x16x32_bf16 v[30:33], v[176:179], v[200:203], v[30:33]
	v_mfma_f32_16x16x32_bf16 v[26:29], v[184:187], v[200:203], v[26:29]
	v_mfma_f32_16x16x32_bf16 v[26:29], v[180:183], v[196:199], v[26:29]
	v_mfma_f32_16x16x32_bf16 v[42:45], v[180:183], v[188:191], v[42:45]
	v_mfma_f32_16x16x32_bf16 v[42:45], v[184:187], v[192:195], v[42:45]
	v_mfma_f32_16x16x32_bf16 v[46:49], v[176:179], v[192:195], v[46:49]
	v_mfma_f32_16x16x32_bf16 v[46:49], v[172:175], v[188:191], v[46:49]
	s_setprio 0
	s_barrier
	s_add_i32 s56, s56, 2
	s_add_u32 s22, s22, 0x100
	s_addc_u32 s23, s23, 0
	s_add_u32 s54, s54, 0x100
	s_addc_u32 s55, s55, 0
	s_cmp_gt_u32 s56, 61
	s_cbranch_scc0 .LBB0_272
	s_and_b64 vcc, exec, s[16:17]
	s_cbranch_vccz .LBB0_277
	s_barrier
	v_lshl_add_u32 v138, s50, 8, v1
	s_cmp_gt_i32 s49, 63
	s_mov_b64 s[22:23], -1
	s_cbranch_scc1 .LBB0_278

.LBB0_1009:
	ds_read_b128 v[142:145], v155
	ds_read_b128 v[158:161], v155 offset:1024
	ds_read_b128 v[168:171], v155 offset:2048
	ds_read_b128 v[176:179], v155 offset:3072
	ds_read_b128 v[180:183], v156
	ds_read_b128 v[184:187], v156 offset:1024
	ds_read_b128 v[188:191], v156 offset:2048
	ds_read_b128 v[192:195], v156 offset:3072
	s_add_u32 s24, s22, 0xfff00080
	s_addc_u32 s25, s23, -1
	s_cmp_eq_u32 s51, 60
	s_cselect_b32 s27, s19, s25
	s_cselect_b32 s26, s47, s24
	s_cselect_b32 s25, s7, s50
	s_cselect_b32 s24, s48, s49
	s_mov_b32 m0, s40
	v_lshl_add_u64 v[146:147], s[22:23], 0, v[138:139]
	ds_read_b128 v[202:205], v157
	ds_read_b128 v[206:209], v157 offset:1024
	ds_read_b128 v[210:213], v157 offset:2048
	ds_read_b128 v[214:217], v157 offset:3072
	ds_read_b128 v[218:221], v157 offset:4096
	ds_read_b128 v[222:225], v157 offset:5120
	ds_read_b128 v[226:229], v157 offset:6144
	ds_read_b128 v[230:233], v157 offset:7168
	global_load_lds_dwordx4 v[146:147], off
	v_lshl_add_u64 v[146:147], s[22:23], 0, v[140:141]
	s_mov_b32 m0, s41
	s_nop 0
	global_load_lds_dwordx4 v[146:147], off
	s_waitcnt vmcnt(8)
	s_waitcnt lgkmcnt(0)
	s_barrier
	s_setprio 1
	s_waitcnt lgkmcnt(0)
	v_mfma_f32_16x16x32_bf16 v[126:129], v[142:145], v[202:205], v[126:129]
	v_mfma_f32_16x16x32_bf16 v[126:129], v[158:161], v[206:209], v[126:129]
	v_mfma_f32_16x16x32_bf16 v[122:125], v[176:179], v[206:209], v[122:125]
	v_mfma_f32_16x16x32_bf16 v[122:125], v[168:171], v[202:205], v[122:125]
	v_mfma_f32_16x16x32_bf16 v[106:109], v[168:171], v[210:213], v[106:109]
	v_mfma_f32_16x16x32_bf16 v[106:109], v[176:179], v[214:217], v[106:109]
	v_mfma_f32_16x16x32_bf16 v[110:113], v[158:161], v[214:217], v[110:113]
	v_mfma_f32_16x16x32_bf16 v[110:113], v[142:145], v[210:213], v[110:113]
	v_mfma_f32_16x16x32_bf16 v[94:97], v[142:145], v[218:221], v[94:97]
	v_mfma_f32_16x16x32_bf16 v[94:97], v[158:161], v[222:225], v[94:97]
	v_mfma_f32_16x16x32_bf16 v[90:93], v[176:179], v[222:225], v[90:93]
	v_mfma_f32_16x16x32_bf16 v[90:93], v[168:171], v[218:221], v[90:93]
	v_mfma_f32_16x16x32_bf16 v[74:77], v[168:171], v[226:229], v[74:77]
	v_mfma_f32_16x16x32_bf16 v[74:77], v[176:179], v[230:233], v[74:77]
	v_mfma_f32_16x16x32_bf16 v[78:81], v[158:161], v[230:233], v[78:81]
	v_mfma_f32_16x16x32_bf16 v[78:81], v[142:145], v[226:229], v[78:81]
	v_mfma_f32_16x16x32_bf16 v[70:73], v[180:183], v[226:229], v[70:73]
	v_mfma_f32_16x16x32_bf16 v[70:73], v[184:187], v[230:233], v[70:73]
	v_mfma_f32_16x16x32_bf16 v[66:69], v[192:195], v[230:233], v[66:69]
	v_mfma_f32_16x16x32_bf16 v[66:69], v[188:191], v[226:229], v[66:69]
	v_mfma_f32_16x16x32_bf16 v[82:85], v[188:191], v[218:221], v[82:85]
	v_mfma_f32_16x16x32_bf16 v[82:85], v[192:195], v[222:225], v[82:85]
	v_mfma_f32_16x16x32_bf16 v[86:89], v[184:187], v[222:225], v[86:89]
	v_mfma_f32_16x16x32_bf16 v[86:89], v[180:183], v[218:221], v[86:89]
	v_mfma_f32_16x16x32_bf16 v[102:105], v[180:183], v[210:213], v[102:105]
	v_mfma_f32_16x16x32_bf16 v[102:105], v[184:187], v[214:217], v[102:105]
	v_mfma_f32_16x16x32_bf16 v[98:101], v[192:195], v[214:217], v[98:101]
	v_mfma_f32_16x16x32_bf16 v[98:101], v[188:191], v[210:213], v[98:101]
	v_mfma_f32_16x16x32_bf16 v[114:117], v[188:191], v[202:205], v[114:117]
	v_mfma_f32_16x16x32_bf16 v[114:117], v[192:195], v[206:209], v[114:117]
	v_mfma_f32_16x16x32_bf16 v[118:121], v[184:187], v[206:209], v[118:121]
	v_mfma_f32_16x16x32_bf16 v[118:121], v[180:183], v[202:205], v[118:121]
	s_setprio 0
	s_barrier
	s_mov_b32 m0, s42
	v_lshl_add_u64 v[146:147], s[24:25], 0, v[132:133]
	s_add_u32 s52, s24, 0x100000
	ds_read_b128 v[202:205], v157 offset:16384
	ds_read_b128 v[206:209], v157 offset:17408
	ds_read_b128 v[210:213], v157 offset:18432
	ds_read_b128 v[214:217], v157 offset:19456
	ds_read_b128 v[218:221], v157 offset:20480
	ds_read_b128 v[222:225], v157 offset:21504
	ds_read_b128 v[226:229], v157 offset:22528
	ds_read_b128 v[230:233], v157 offset:23552
	global_load_lds_dwordx4 v[146:147], off
	v_lshl_add_u64 v[172:173], s[24:25], 0, v[136:137]
	s_mov_b32 m0, s43
	s_addc_u32 s53, s25, 0
	global_load_lds_dwordx4 v[172:173], off
	v_lshl_add_u64 v[196:197], s[52:53], 0, v[132:133]
	s_mov_b32 m0, s44
	v_lshl_add_u64 v[234:235], s[26:27], 0, v[134:135]
	global_load_lds_dwordx4 v[196:197], off
	v_lshl_add_u64 v[196:197], s[52:53], 0, v[136:137]
	s_add_i32 m0, s44, 0x2000
	s_nop 0
	global_load_lds_dwordx4 v[196:197], off
	v_lshl_add_u64 v[196:197], s[26:27], 0, v[130:131]
	s_mov_b32 m0, s33
	s_nop 0
	global_load_lds_dwordx4 v[196:197], off
	s_mov_b32 m0, s34
	s_nop 0
	global_load_lds_dwordx4 v[234:235], off
	s_waitcnt vmcnt(8)
	s_waitcnt lgkmcnt(0)
	s_barrier
	s_setprio 1
	s_waitcnt lgkmcnt(0)
	v_mfma_f32_16x16x32_bf16 v[62:65], v[142:145], v[202:205], v[62:65]
	v_mfma_f32_16x16x32_bf16 v[62:65], v[158:161], v[206:209], v[62:65]
	v_mfma_f32_16x16x32_bf16 v[58:61], v[176:179], v[206:209], v[58:61]
	v_mfma_f32_16x16x32_bf16 v[58:61], v[168:171], v[202:205], v[58:61]
	v_mfma_f32_16x16x32_bf16 v[42:45], v[168:171], v[210:213], v[42:45]
	v_mfma_f32_16x16x32_bf16 v[42:45], v[176:179], v[214:217], v[42:45]
	v_mfma_f32_16x16x32_bf16 v[46:49], v[158:161], v[214:217], v[46:49]
	v_mfma_f32_16x16x32_bf16 v[46:49], v[142:145], v[210:213], v[46:49]
	v_mfma_f32_16x16x32_bf16 v[30:33], v[142:145], v[218:221], v[30:33]
	v_mfma_f32_16x16x32_bf16 v[30:33], v[158:161], v[222:225], v[30:33]
	v_mfma_f32_16x16x32_bf16 v[26:29], v[176:179], v[222:225], v[26:29]
	v_mfma_f32_16x16x32_bf16 v[26:29], v[168:171], v[218:221], v[26:29]
	v_mfma_f32_16x16x32_bf16 v[10:13], v[168:171], v[226:229], v[10:13]
	v_mfma_f32_16x16x32_bf16 v[10:13], v[176:179], v[230:233], v[10:13]
	v_mfma_f32_16x16x32_bf16 v[14:17], v[158:161], v[230:233], v[14:17]
	v_mfma_f32_16x16x32_bf16 v[14:17], v[142:145], v[226:229], v[14:17]
	v_mfma_f32_16x16x32_bf16 v[6:9], v[180:183], v[226:229], v[6:9]
	v_mfma_f32_16x16x32_bf16 v[6:9], v[184:187], v[230:233], v[6:9]
	v_mfma_f32_16x16x32_bf16 v[2:5], v[192:195], v[230:233], v[2:5]
	v_mfma_f32_16x16x32_bf16 v[2:5], v[188:191], v[226:229], v[2:5]
	v_mfma_f32_16x16x32_bf16 v[18:21], v[188:191], v[218:221], v[18:21]
	v_mfma_f32_16x16x32_bf16 v[18:21], v[192:195], v[222:225], v[18:21]
	v_mfma_f32_16x16x32_bf16 v[22:25], v[184:187], v[222:225], v[22:25]
	v_mfma_f32_16x16x32_bf16 v[22:25], v[180:183], v[218:221], v[22:25]
	v_mfma_f32_16x16x32_bf16 v[38:41], v[180:183], v[210:213], v[38:41]
	v_mfma_f32_16x16x32_bf16 v[38:41], v[184:187], v[214:217], v[38:41]
	v_mfma_f32_16x16x32_bf16 v[34:37], v[192:195], v[214:217], v[34:37]
	v_mfma_f32_16x16x32_bf16 v[34:37], v[188:191], v[210:213], v[34:37]
	v_mfma_f32_16x16x32_bf16 v[50:53], v[188:191], v[202:205], v[50:53]
	v_mfma_f32_16x16x32_bf16 v[50:53], v[192:195], v[206:209], v[50:53]
	v_mfma_f32_16x16x32_bf16 v[54:57], v[184:187], v[206:209], v[54:57]
	v_mfma_f32_16x16x32_bf16 v[54:57], v[180:183], v[202:205], v[54:57]
	s_setprio 0
	s_barrier
	s_add_i32 s52, 0, 0x18000
	v_add_u32_e32 v166, s52, v153
	s_add_i32 s53, 0, 0x1c000
	ds_read_b128 v[142:145], v166
	ds_read_b128 v[158:161], v166 offset:1024
	ds_read_b128 v[168:171], v166 offset:2048
	ds_read_b128 v[176:179], v166 offset:3072
	v_add_u32_e32 v166, s53, v153
	ds_read_b128 v[180:183], v166
	ds_read_b128 v[184:187], v166 offset:1024
	ds_read_b128 v[188:191], v166 offset:2048
	ds_read_b128 v[192:195], v166 offset:3072
	s_add_u32 s26, s26, 0x100000
	s_addc_u32 s27, s27, 0
	s_mov_b32 m0, s35
	v_lshl_add_u64 v[236:237], s[26:27], 0, v[130:131]
	ds_read_b128 v[202:205], v157 offset:32768
	ds_read_b128 v[206:209], v157 offset:33792
	ds_read_b128 v[210:213], v157 offset:34816
	ds_read_b128 v[214:217], v157 offset:35840
	ds_read_b128 v[218:221], v157 offset:36864
	ds_read_b128 v[222:225], v157 offset:37888
	ds_read_b128 v[226:229], v157 offset:38912
	ds_read_b128 v[230:233], v157 offset:39936
	global_load_lds_dwordx4 v[236:237], off
	v_lshl_add_u64 v[236:237], s[26:27], 0, v[134:135]
	s_mov_b32 m0, s36
	s_nop 0
	global_load_lds_dwordx4 v[236:237], off
	s_waitcnt vmcnt(8)
	s_waitcnt lgkmcnt(0)
	s_barrier
	s_setprio 1
	s_waitcnt lgkmcnt(0)
	v_mfma_f32_16x16x32_bf16 v[126:129], v[142:145], v[202:205], v[126:129]
	v_mfma_f32_16x16x32_bf16 v[126:129], v[158:161], v[206:209], v[126:129]
	v_mfma_f32_16x16x32_bf16 v[122:125], v[176:179], v[206:209], v[122:125]
	v_mfma_f32_16x16x32_bf16 v[122:125], v[168:171], v[202:205], v[122:125]
	v_mfma_f32_16x16x32_bf16 v[106:109], v[168:171], v[210:213], v[106:109]
	v_mfma_f32_16x16x32_bf16 v[106:109], v[176:179], v[214:217], v[106:109]
	v_mfma_f32_16x16x32_bf16 v[110:113], v[158:161], v[214:217], v[110:113]
	v_mfma_f32_16x16x32_bf16 v[110:113], v[142:145], v[210:213], v[110:113]
	v_mfma_f32_16x16x32_bf16 v[94:97], v[142:145], v[218:221], v[94:97]
	v_mfma_f32_16x16x32_bf16 v[94:97], v[158:161], v[222:225], v[94:97]
	v_mfma_f32_16x16x32_bf16 v[90:93], v[176:179], v[222:225], v[90:93]
	v_mfma_f32_16x16x32_bf16 v[90:93], v[168:171], v[218:221], v[90:93]
	v_mfma_f32_16x16x32_bf16 v[74:77], v[168:171], v[226:229], v[74:77]
	v_mfma_f32_16x16x32_bf16 v[74:77], v[176:179], v[230:233], v[74:77]
	v_mfma_f32_16x16x32_bf16 v[78:81], v[158:161], v[230:233], v[78:81]
	v_mfma_f32_16x16x32_bf16 v[78:81], v[142:145], v[226:229], v[78:81]
	v_mfma_f32_16x16x32_bf16 v[70:73], v[180:183], v[226:229], v[70:73]
	v_mfma_f32_16x16x32_bf16 v[70:73], v[184:187], v[230:233], v[70:73]
	v_mfma_f32_16x16x32_bf16 v[66:69], v[192:195], v[230:233], v[66:69]
	v_mfma_f32_16x16x32_bf16 v[66:69], v[188:191], v[226:229], v[66:69]
	v_mfma_f32_16x16x32_bf16 v[82:85], v[188:191], v[218:221], v[82:85]
	v_mfma_f32_16x16x32_bf16 v[82:85], v[192:195], v[222:225], v[82:85]
	v_mfma_f32_16x16x32_bf16 v[86:89], v[184:187], v[222:225], v[86:89]
	v_mfma_f32_16x16x32_bf16 v[86:89], v[180:183], v[218:221], v[86:89]
	v_mfma_f32_16x16x32_bf16 v[102:105], v[180:183], v[210:213], v[102:105]
	v_mfma_f32_16x16x32_bf16 v[102:105], v[184:187], v[214:217], v[102:105]
	v_mfma_f32_16x16x32_bf16 v[98:101], v[192:195], v[214:217], v[98:101]
	v_mfma_f32_16x16x32_bf16 v[98:101], v[188:191], v[210:213], v[98:101]
	v_mfma_f32_16x16x32_bf16 v[114:117], v[188:191], v[202:205], v[114:117]
	v_mfma_f32_16x16x32_bf16 v[114:117], v[192:195], v[206:209], v[114:117]
	v_mfma_f32_16x16x32_bf16 v[118:121], v[184:187], v[206:209], v[118:121]
	v_mfma_f32_16x16x32_bf16 v[118:121], v[180:183], v[202:205], v[118:121]
	s_setprio 0
	s_barrier
	s_add_i32 s26, s52, s30
	v_lshl_add_u64 v[146:147], v[146:147], 0, s[14:15]
	s_mov_b32 m0, s26
	ds_read_b128 v[202:205], v157 offset:49152
	ds_read_b128 v[206:209], v157 offset:50176
	ds_read_b128 v[210:213], v157 offset:51200
	ds_read_b128 v[214:217], v157 offset:52224
	ds_read_b128 v[218:221], v157 offset:53248
	ds_read_b128 v[222:225], v157 offset:54272
	ds_read_b128 v[226:229], v157 offset:55296
	ds_read_b128 v[230:233], v157 offset:56320
	global_load_lds_dwordx4 v[146:147], off
	s_add_i32 m0, s26, 0x2000
	s_add_u32 s24, s24, 0x100080
	v_lshl_add_u64 v[146:147], v[172:173], 0, s[14:15]
	s_addc_u32 s25, s25, 0
	s_add_i32 s26, s53, s30
	global_load_lds_dwordx4 v[146:147], off
	v_lshl_add_u64 v[146:147], s[24:25], 0, v[132:133]
	s_mov_b32 m0, s26
	s_nop 0
	global_load_lds_dwordx4 v[146:147], off
	v_lshl_add_u64 v[146:147], s[24:25], 0, v[136:137]
	s_add_i32 m0, s26, 0x2000
	s_nop 0
	global_load_lds_dwordx4 v[146:147], off
	v_lshl_add_u64 v[146:147], v[196:197], 0, s[14:15]
	s_mov_b32 m0, s38
	s_nop 0
	global_load_lds_dwordx4 v[146:147], off
	v_lshl_add_u64 v[146:147], v[234:235], 0, s[14:15]
	s_mov_b32 m0, s39
	s_nop 0
	global_load_lds_dwordx4 v[146:147], off
	s_waitcnt vmcnt(8)
	s_waitcnt lgkmcnt(0)
	s_barrier
	s_setprio 1
	s_waitcnt lgkmcnt(0)
	v_mfma_f32_16x16x32_bf16 v[62:65], v[142:145], v[202:205], v[62:65]
	v_mfma_f32_16x16x32_bf16 v[62:65], v[158:161], v[206:209], v[62:65]
	v_mfma_f32_16x16x32_bf16 v[58:61], v[176:179], v[206:209], v[58:61]
	v_mfma_f32_16x16x32_bf16 v[58:61], v[168:171], v[202:205], v[58:61]
	v_mfma_f32_16x16x32_bf16 v[42:45], v[168:171], v[210:213], v[42:45]
	v_mfma_f32_16x16x32_bf16 v[42:45], v[176:179], v[214:217], v[42:45]
	v_mfma_f32_16x16x32_bf16 v[46:49], v[158:161], v[214:217], v[46:49]
	v_mfma_f32_16x16x32_bf16 v[46:49], v[142:145], v[210:213], v[46:49]
	v_mfma_f32_16x16x32_bf16 v[30:33], v[142:145], v[218:221], v[30:33]
	v_mfma_f32_16x16x32_bf16 v[30:33], v[158:161], v[222:225], v[30:33]
	v_mfma_f32_16x16x32_bf16 v[26:29], v[176:179], v[222:225], v[26:29]
	v_mfma_f32_16x16x32_bf16 v[26:29], v[168:171], v[218:221], v[26:29]
	v_mfma_f32_16x16x32_bf16 v[10:13], v[168:171], v[226:229], v[10:13]
	v_mfma_f32_16x16x32_bf16 v[10:13], v[176:179], v[230:233], v[10:13]
	v_mfma_f32_16x16x32_bf16 v[14:17], v[158:161], v[230:233], v[14:17]
	v_mfma_f32_16x16x32_bf16 v[14:17], v[142:145], v[226:229], v[14:17]
	v_mfma_f32_16x16x32_bf16 v[6:9], v[180:183], v[226:229], v[6:9]
	v_mfma_f32_16x16x32_bf16 v[6:9], v[184:187], v[230:233], v[6:9]
	v_mfma_f32_16x16x32_bf16 v[2:5], v[192:195], v[230:233], v[2:5]
	v_mfma_f32_16x16x32_bf16 v[2:5], v[188:191], v[226:229], v[2:5]
	v_mfma_f32_16x16x32_bf16 v[18:21], v[188:191], v[218:221], v[18:21]
	v_mfma_f32_16x16x32_bf16 v[18:21], v[192:195], v[222:225], v[18:21]
	v_mfma_f32_16x16x32_bf16 v[22:25], v[184:187], v[222:225], v[22:25]
	v_mfma_f32_16x16x32_bf16 v[22:25], v[180:183], v[218:221], v[22:25]
	v_mfma_f32_16x16x32_bf16 v[38:41], v[180:183], v[210:213], v[38:41]
	v_mfma_f32_16x16x32_bf16 v[38:41], v[184:187], v[214:217], v[38:41]
	v_mfma_f32_16x16x32_bf16 v[34:37], v[192:195], v[214:217], v[34:37]
	v_mfma_f32_16x16x32_bf16 v[34:37], v[188:191], v[210:213], v[34:37]
	v_mfma_f32_16x16x32_bf16 v[50:53], v[188:191], v[202:205], v[50:53]
	v_mfma_f32_16x16x32_bf16 v[50:53], v[192:195], v[206:209], v[50:53]
	v_mfma_f32_16x16x32_bf16 v[54:57], v[184:187], v[206:209], v[54:57]
	v_mfma_f32_16x16x32_bf16 v[54:57], v[180:183], v[202:205], v[54:57]
	s_setprio 0
	s_barrier
	s_add_i32 s51, s51, 2
	s_add_u32 s22, s22, 0x100
	s_addc_u32 s23, s23, 0
	s_add_u32 s49, s49, 0x100
	s_addc_u32 s50, s50, 0
	s_cmp_gt_u32 s51, 61
	s_cbranch_scc0 .LBB0_1009
	s_and_b64 vcc, exec, s[16:17]
	s_cbranch_vccz .LBB0_1012
	s_barrier

.LBB0_1019:
	s_add_i32 s21, s20, 0x100
	s_and_b64 s[18:19], s[18:19], exec
	s_cselect_b32 s19, 0, s21
	s_cselect_b32 s18, 0, 0
	s_add_u32 s22, s8, s19
	s_addc_u32 s23, s9, s18
	ds_read_b128 v[144:147], v139
	ds_read_b128 v[150:153], v139 offset:1024
	ds_read_b128 v[154:157], v139 offset:2048
	ds_read_b128 v[158:161], v139 offset:3072
	ds_read_b128 v[168:171], v140
	ds_read_b128 v[176:179], v140 offset:1024
	ds_read_b128 v[180:183], v140 offset:2048
	ds_read_b128 v[184:187], v140 offset:3072
	s_add_u32 s24, s10, s19
	s_addc_u32 s25, s11, s18
	s_add_u32 s30, s12, s20
	s_addc_u32 s31, s13, 0
	s_add_u32 s26, s24, 0x100000
	s_addc_u32 s27, s25, 0
	s_add_u32 s20, s22, 0x100000
	s_addc_u32 s21, s23, 0
	s_add_u32 s18, s24, 0x100080
	s_addc_u32 s19, s25, 0
	v_lshl_add_u64 v[172:173], s[30:31], 0, v[130:131]
	s_mov_b32 m0, s40
	v_lshl_add_u64 v[172:173], v[172:173], 0, s[14:15]
	ds_read_b128 v[188:191], v141
	ds_read_b128 v[192:195], v141 offset:1024
	ds_read_b128 v[202:205], v141 offset:2048
	ds_read_b128 v[206:209], v141 offset:3072
	ds_read_b128 v[210:213], v141 offset:4096
	ds_read_b128 v[214:217], v141 offset:5120
	ds_read_b128 v[218:221], v141 offset:6144
	ds_read_b128 v[222:225], v141 offset:7168
	global_load_lds_dwordx4 v[172:173], off
	v_lshl_add_u64 v[172:173], s[30:31], 0, v[134:135]
	v_lshl_add_u64 v[172:173], v[172:173], 0, s[14:15]
	s_mov_b32 m0, s41
	s_nop 0
	global_load_lds_dwordx4 v[172:173], off
	s_waitcnt vmcnt(8)
	s_waitcnt lgkmcnt(0)
	s_barrier
	s_setprio 1
	s_waitcnt lgkmcnt(0)
	v_mfma_f32_16x16x32_bf16 v[126:129], v[144:147], v[188:191], v[126:129]
	v_mfma_f32_16x16x32_bf16 v[126:129], v[150:153], v[192:195], v[126:129]
	v_mfma_f32_16x16x32_bf16 v[122:125], v[158:161], v[192:195], v[122:125]
	v_mfma_f32_16x16x32_bf16 v[122:125], v[154:157], v[188:191], v[122:125]
	v_mfma_f32_16x16x32_bf16 v[114:117], v[154:157], v[202:205], v[114:117]
	v_mfma_f32_16x16x32_bf16 v[114:117], v[158:161], v[206:209], v[114:117]
	v_mfma_f32_16x16x32_bf16 v[118:121], v[150:153], v[206:209], v[118:121]
	v_mfma_f32_16x16x32_bf16 v[118:121], v[144:147], v[202:205], v[118:121]
	v_mfma_f32_16x16x32_bf16 v[102:105], v[144:147], v[210:213], v[102:105]
	v_mfma_f32_16x16x32_bf16 v[102:105], v[150:153], v[214:217], v[102:105]
	v_mfma_f32_16x16x32_bf16 v[98:101], v[158:161], v[214:217], v[98:101]
	v_mfma_f32_16x16x32_bf16 v[98:101], v[154:157], v[210:213], v[98:101]
	v_mfma_f32_16x16x32_bf16 v[82:85], v[154:157], v[218:221], v[82:85]
	v_mfma_f32_16x16x32_bf16 v[82:85], v[158:161], v[222:225], v[82:85]
	v_mfma_f32_16x16x32_bf16 v[86:89], v[150:153], v[222:225], v[86:89]
	v_mfma_f32_16x16x32_bf16 v[86:89], v[144:147], v[218:221], v[86:89]
	v_mfma_f32_16x16x32_bf16 v[70:73], v[168:171], v[218:221], v[70:73]
	v_mfma_f32_16x16x32_bf16 v[70:73], v[176:179], v[222:225], v[70:73]
	v_mfma_f32_16x16x32_bf16 v[66:69], v[184:187], v[222:225], v[66:69]
	v_mfma_f32_16x16x32_bf16 v[66:69], v[180:183], v[218:221], v[66:69]
	v_mfma_f32_16x16x32_bf16 v[74:77], v[180:183], v[210:213], v[74:77]
	v_mfma_f32_16x16x32_bf16 v[74:77], v[184:187], v[214:217], v[74:77]
	v_mfma_f32_16x16x32_bf16 v[78:81], v[176:179], v[214:217], v[78:81]
	v_mfma_f32_16x16x32_bf16 v[78:81], v[168:171], v[210:213], v[78:81]
	v_mfma_f32_16x16x32_bf16 v[94:97], v[168:171], v[202:205], v[94:97]
	v_mfma_f32_16x16x32_bf16 v[94:97], v[176:179], v[206:209], v[94:97]
	v_mfma_f32_16x16x32_bf16 v[90:93], v[184:187], v[206:209], v[90:93]
	v_mfma_f32_16x16x32_bf16 v[90:93], v[180:183], v[202:205], v[90:93]
	v_mfma_f32_16x16x32_bf16 v[106:109], v[180:183], v[188:191], v[106:109]
	v_mfma_f32_16x16x32_bf16 v[106:109], v[184:187], v[192:195], v[106:109]
	v_mfma_f32_16x16x32_bf16 v[110:113], v[176:179], v[192:195], v[110:113]
	v_mfma_f32_16x16x32_bf16 v[110:113], v[168:171], v[188:191], v[110:113]
	s_setprio 0
	s_barrier
	s_mov_b32 m0, s42
	v_lshl_add_u64 v[172:173], s[24:25], 0, v[132:133]
	ds_read_b128 v[188:191], v141 offset:16384
	ds_read_b128 v[192:195], v141 offset:17408
	ds_read_b128 v[202:205], v141 offset:18432
	ds_read_b128 v[206:209], v141 offset:19456
	ds_read_b128 v[210:213], v141 offset:20480
	ds_read_b128 v[214:217], v141 offset:21504
	ds_read_b128 v[218:221], v141 offset:22528
	ds_read_b128 v[222:225], v141 offset:23552
	global_load_lds_dwordx4 v[172:173], off
	v_lshl_add_u64 v[196:197], s[24:25], 0, v[136:137]
	s_mov_b32 m0, s43
	v_lshl_add_u64 v[226:227], s[26:27], 0, v[132:133]
	global_load_lds_dwordx4 v[196:197], off
	s_mov_b32 m0, s44
	v_lshl_add_u64 v[228:229], s[22:23], 0, v[134:135]
	global_load_lds_dwordx4 v[226:227], off
	v_lshl_add_u64 v[226:227], s[26:27], 0, v[136:137]
	s_mov_b32 m0, s45
	s_nop 0
	global_load_lds_dwordx4 v[226:227], off
	v_lshl_add_u64 v[226:227], s[22:23], 0, v[130:131]
	s_mov_b32 m0, s7
	s_nop 0
	global_load_lds_dwordx4 v[226:227], off
	s_mov_b32 m0, s34
	s_nop 0
	global_load_lds_dwordx4 v[228:229], off
	s_waitcnt vmcnt(8)
	s_waitcnt lgkmcnt(0)
	s_barrier
	s_setprio 1
	s_waitcnt lgkmcnt(0)
	v_mfma_f32_16x16x32_bf16 v[62:65], v[144:147], v[188:191], v[62:65]
	v_mfma_f32_16x16x32_bf16 v[62:65], v[150:153], v[192:195], v[62:65]
	v_mfma_f32_16x16x32_bf16 v[58:61], v[158:161], v[192:195], v[58:61]
	v_mfma_f32_16x16x32_bf16 v[58:61], v[154:157], v[188:191], v[58:61]
	v_mfma_f32_16x16x32_bf16 v[50:53], v[154:157], v[202:205], v[50:53]
	v_mfma_f32_16x16x32_bf16 v[50:53], v[158:161], v[206:209], v[50:53]
	v_mfma_f32_16x16x32_bf16 v[54:57], v[150:153], v[206:209], v[54:57]
	v_mfma_f32_16x16x32_bf16 v[54:57], v[144:147], v[202:205], v[54:57]
	v_mfma_f32_16x16x32_bf16 v[38:41], v[144:147], v[210:213], v[38:41]
	v_mfma_f32_16x16x32_bf16 v[38:41], v[150:153], v[214:217], v[38:41]
	v_mfma_f32_16x16x32_bf16 v[34:37], v[158:161], v[214:217], v[34:37]
	v_mfma_f32_16x16x32_bf16 v[34:37], v[154:157], v[210:213], v[34:37]
	v_mfma_f32_16x16x32_bf16 v[18:21], v[154:157], v[218:221], v[18:21]
	v_mfma_f32_16x16x32_bf16 v[18:21], v[158:161], v[222:225], v[18:21]
	v_mfma_f32_16x16x32_bf16 v[22:25], v[150:153], v[222:225], v[22:25]
	v_mfma_f32_16x16x32_bf16 v[22:25], v[144:147], v[218:221], v[22:25]
	v_mfma_f32_16x16x32_bf16 v[6:9], v[168:171], v[218:221], v[6:9]
	v_mfma_f32_16x16x32_bf16 v[6:9], v[176:179], v[222:225], v[6:9]
	v_mfma_f32_16x16x32_bf16 v[2:5], v[184:187], v[222:225], v[2:5]
	v_mfma_f32_16x16x32_bf16 v[2:5], v[180:183], v[218:221], v[2:5]
	v_mfma_f32_16x16x32_bf16 v[10:13], v[180:183], v[210:213], v[10:13]
	v_mfma_f32_16x16x32_bf16 v[10:13], v[184:187], v[214:217], v[10:13]
	v_mfma_f32_16x16x32_bf16 v[14:17], v[176:179], v[214:217], v[14:17]
	v_mfma_f32_16x16x32_bf16 v[14:17], v[168:171], v[210:213], v[14:17]
	v_mfma_f32_16x16x32_bf16 v[30:33], v[168:171], v[202:205], v[30:33]
	v_mfma_f32_16x16x32_bf16 v[30:33], v[176:179], v[206:209], v[30:33]
	v_mfma_f32_16x16x32_bf16 v[26:29], v[184:187], v[206:209], v[26:29]
	v_mfma_f32_16x16x32_bf16 v[26:29], v[180:183], v[202:205], v[26:29]
	v_mfma_f32_16x16x32_bf16 v[42:45], v[180:183], v[188:191], v[42:45]
	v_mfma_f32_16x16x32_bf16 v[42:45], v[184:187], v[192:195], v[42:45]
	v_mfma_f32_16x16x32_bf16 v[46:49], v[176:179], v[192:195], v[46:49]
	v_mfma_f32_16x16x32_bf16 v[46:49], v[168:171], v[188:191], v[46:49]
	s_setprio 0
	s_barrier
	ds_read_b128 v[144:147], v142
	ds_read_b128 v[150:153], v142 offset:1024
	ds_read_b128 v[154:157], v142 offset:2048
	ds_read_b128 v[158:161], v142 offset:3072
	ds_read_b128 v[168:171], v143
	ds_read_b128 v[176:179], v143 offset:1024
	ds_read_b128 v[180:183], v143 offset:2048
	ds_read_b128 v[184:187], v143 offset:3072
	s_mov_b32 m0, s35
	v_lshl_add_u64 v[230:231], s[20:21], 0, v[130:131]
	ds_read_b128 v[188:191], v141 offset:32768
	ds_read_b128 v[192:195], v141 offset:33792
	ds_read_b128 v[202:205], v141 offset:34816
	ds_read_b128 v[206:209], v141 offset:35840
	ds_read_b128 v[210:213], v141 offset:36864
	ds_read_b128 v[214:217], v141 offset:37888
	ds_read_b128 v[218:221], v141 offset:38912
	ds_read_b128 v[222:225], v141 offset:39936
	global_load_lds_dwordx4 v[230:231], off
	v_lshl_add_u64 v[230:231], s[20:21], 0, v[134:135]
	s_mov_b32 m0, s36
	s_nop 0
	global_load_lds_dwordx4 v[230:231], off
	s_waitcnt vmcnt(8)
	s_waitcnt lgkmcnt(0)
	s_barrier
	s_setprio 1
	s_waitcnt lgkmcnt(0)
	v_mfma_f32_16x16x32_bf16 v[126:129], v[144:147], v[188:191], v[126:129]
	v_mfma_f32_16x16x32_bf16 v[126:129], v[150:153], v[192:195], v[126:129]
	v_mfma_f32_16x16x32_bf16 v[122:125], v[158:161], v[192:195], v[122:125]
	v_mfma_f32_16x16x32_bf16 v[122:125], v[154:157], v[188:191], v[122:125]
	v_mfma_f32_16x16x32_bf16 v[114:117], v[154:157], v[202:205], v[114:117]
	v_mfma_f32_16x16x32_bf16 v[114:117], v[158:161], v[206:209], v[114:117]
	v_mfma_f32_16x16x32_bf16 v[118:121], v[150:153], v[206:209], v[118:121]
	v_mfma_f32_16x16x32_bf16 v[118:121], v[144:147], v[202:205], v[118:121]
	v_mfma_f32_16x16x32_bf16 v[102:105], v[144:147], v[210:213], v[102:105]
	v_mfma_f32_16x16x32_bf16 v[102:105], v[150:153], v[214:217], v[102:105]
	v_mfma_f32_16x16x32_bf16 v[98:101], v[158:161], v[214:217], v[98:101]
	v_mfma_f32_16x16x32_bf16 v[98:101], v[154:157], v[210:213], v[98:101]
	v_mfma_f32_16x16x32_bf16 v[82:85], v[154:157], v[218:221], v[82:85]
	v_mfma_f32_16x16x32_bf16 v[82:85], v[158:161], v[222:225], v[82:85]
	v_mfma_f32_16x16x32_bf16 v[86:89], v[150:153], v[222:225], v[86:89]
	v_mfma_f32_16x16x32_bf16 v[86:89], v[144:147], v[218:221], v[86:89]
	v_mfma_f32_16x16x32_bf16 v[70:73], v[168:171], v[218:221], v[70:73]
	v_mfma_f32_16x16x32_bf16 v[70:73], v[176:179], v[222:225], v[70:73]
	v_mfma_f32_16x16x32_bf16 v[66:69], v[184:187], v[222:225], v[66:69]
	v_mfma_f32_16x16x32_bf16 v[66:69], v[180:183], v[218:221], v[66:69]
	v_mfma_f32_16x16x32_bf16 v[74:77], v[180:183], v[210:213], v[74:77]
	v_mfma_f32_16x16x32_bf16 v[74:77], v[184:187], v[214:217], v[74:77]
	v_mfma_f32_16x16x32_bf16 v[78:81], v[176:179], v[214:217], v[78:81]
	v_mfma_f32_16x16x32_bf16 v[78:81], v[168:171], v[210:213], v[78:81]
	v_mfma_f32_16x16x32_bf16 v[94:97], v[168:171], v[202:205], v[94:97]
	v_mfma_f32_16x16x32_bf16 v[94:97], v[176:179], v[206:209], v[94:97]
	v_mfma_f32_16x16x32_bf16 v[90:93], v[184:187], v[206:209], v[90:93]
	v_mfma_f32_16x16x32_bf16 v[90:93], v[180:183], v[202:205], v[90:93]
	v_mfma_f32_16x16x32_bf16 v[106:109], v[180:183], v[188:191], v[106:109]
	v_mfma_f32_16x16x32_bf16 v[106:109], v[184:187], v[192:195], v[106:109]
	v_mfma_f32_16x16x32_bf16 v[110:113], v[176:179], v[192:195], v[110:113]
	v_mfma_f32_16x16x32_bf16 v[110:113], v[168:171], v[188:191], v[110:113]
	s_setprio 0
	s_barrier
	s_mov_b32 m0, s46
	v_lshl_add_u64 v[172:173], v[172:173], 0, s[14:15]
	ds_read_b128 v[188:191], v141 offset:49152
	ds_read_b128 v[192:195], v141 offset:50176
	ds_read_b128 v[202:205], v141 offset:51200
	ds_read_b128 v[206:209], v141 offset:52224
	ds_read_b128 v[210:213], v141 offset:53248
	ds_read_b128 v[214:217], v141 offset:54272
	ds_read_b128 v[218:221], v141 offset:55296
	ds_read_b128 v[222:225], v141 offset:56320
	global_load_lds_dwordx4 v[172:173], off
	v_lshl_add_u64 v[172:173], v[196:197], 0, s[14:15]
	s_mov_b32 m0, s47
	s_nop 0
	global_load_lds_dwordx4 v[172:173], off
	v_lshl_add_u64 v[172:173], s[18:19], 0, v[132:133]
	s_mov_b32 m0, s48
	s_nop 0
	global_load_lds_dwordx4 v[172:173], off
	v_lshl_add_u64 v[172:173], s[18:19], 0, v[136:137]
	s_mov_b32 m0, s49
	s_nop 0
	global_load_lds_dwordx4 v[172:173], off
	v_lshl_add_u64 v[172:173], v[226:227], 0, s[14:15]
	s_mov_b32 m0, s38
	s_nop 0
	global_load_lds_dwordx4 v[172:173], off
	v_lshl_add_u64 v[172:173], v[228:229], 0, s[14:15]
	s_mov_b32 m0, s39
	s_nop 0
	global_load_lds_dwordx4 v[172:173], off
	s_waitcnt vmcnt(8)
	s_waitcnt lgkmcnt(0)
	s_barrier
	s_setprio 1
	s_waitcnt lgkmcnt(0)
	v_mfma_f32_16x16x32_bf16 v[62:65], v[144:147], v[188:191], v[62:65]
	v_mfma_f32_16x16x32_bf16 v[62:65], v[150:153], v[192:195], v[62:65]
	v_mfma_f32_16x16x32_bf16 v[58:61], v[158:161], v[192:195], v[58:61]
	v_mfma_f32_16x16x32_bf16 v[58:61], v[154:157], v[188:191], v[58:61]
	v_mfma_f32_16x16x32_bf16 v[50:53], v[154:157], v[202:205], v[50:53]
	v_mfma_f32_16x16x32_bf16 v[50:53], v[158:161], v[206:209], v[50:53]
	v_mfma_f32_16x16x32_bf16 v[54:57], v[150:153], v[206:209], v[54:57]
	v_mfma_f32_16x16x32_bf16 v[54:57], v[144:147], v[202:205], v[54:57]
	v_mfma_f32_16x16x32_bf16 v[38:41], v[144:147], v[210:213], v[38:41]
	v_mfma_f32_16x16x32_bf16 v[38:41], v[150:153], v[214:217], v[38:41]
	v_mfma_f32_16x16x32_bf16 v[34:37], v[158:161], v[214:217], v[34:37]
	v_mfma_f32_16x16x32_bf16 v[34:37], v[154:157], v[210:213], v[34:37]
	v_mfma_f32_16x16x32_bf16 v[18:21], v[154:157], v[218:221], v[18:21]
	v_mfma_f32_16x16x32_bf16 v[18:21], v[158:161], v[222:225], v[18:21]
	v_mfma_f32_16x16x32_bf16 v[22:25], v[150:153], v[222:225], v[22:25]
	v_mfma_f32_16x16x32_bf16 v[22:25], v[144:147], v[218:221], v[22:25]
	v_mfma_f32_16x16x32_bf16 v[6:9], v[168:171], v[218:221], v[6:9]
	v_mfma_f32_16x16x32_bf16 v[6:9], v[176:179], v[222:225], v[6:9]
	v_mfma_f32_16x16x32_bf16 v[2:5], v[184:187], v[222:225], v[2:5]
	v_mfma_f32_16x16x32_bf16 v[2:5], v[180:183], v[218:221], v[2:5]
	v_mfma_f32_16x16x32_bf16 v[10:13], v[180:183], v[210:213], v[10:13]
	v_mfma_f32_16x16x32_bf16 v[10:13], v[184:187], v[214:217], v[10:13]
	v_mfma_f32_16x16x32_bf16 v[14:17], v[176:179], v[214:217], v[14:17]
	v_mfma_f32_16x16x32_bf16 v[14:17], v[168:171], v[210:213], v[14:17]
	v_mfma_f32_16x16x32_bf16 v[30:33], v[168:171], v[202:205], v[30:33]
	v_mfma_f32_16x16x32_bf16 v[30:33], v[176:179], v[206:209], v[30:33]
	v_mfma_f32_16x16x32_bf16 v[26:29], v[184:187], v[206:209], v[26:29]
	v_mfma_f32_16x16x32_bf16 v[26:29], v[180:183], v[202:205], v[26:29]
	v_mfma_f32_16x16x32_bf16 v[42:45], v[180:183], v[188:191], v[42:45]
	v_mfma_f32_16x16x32_bf16 v[42:45], v[184:187], v[192:195], v[42:45]
	v_mfma_f32_16x16x32_bf16 v[46:49], v[176:179], v[192:195], v[46:49]
	v_mfma_f32_16x16x32_bf16 v[46:49], v[168:171], v[188:191], v[46:49]
	s_setprio 0
	s_barrier
	s_andn2_b64 vcc, exec, s[16:17]
	s_mov_b64 s[18:19], -1
	s_mov_b64 s[16:17], 0
	s_movk_i32 s20, 0x100
	s_cbranch_vccz .LBB0_1019
	s_lshl_b32 s7, s33, 21
	v_readlane_b32 s0, v249, 29
	v_lshl_or_b32 v130, s6, 8, v148
	v_mov_b32_e32 v139, 0
	s_add_u32 s8, s0, s7
	v_readlane_b32 s0, v249, 31
	v_or_b32_e32 v130, s37, v130
	v_cvt_pk_bf16_f32 v70, v70, v71
	v_cvt_pk_bf16_f32 v71, v72, v73
	v_cvt_pk_bf16_f32 v72, v66, v67
	v_add_u32_e32 v66, 0x80, v138
	v_mov_b32_e32 v67, v139
	s_addc_u32 s9, s0, 0
	v_ashrrev_i32_e32 v131, 31, v130
	v_lshlrev_b64 v[132:133], 13, v[138:139]
	v_cvt_pk_bf16_f32 v110, v110, v111
	v_cvt_pk_bf16_f32 v111, v112, v113
	v_cvt_pk_bf16_f32 v112, v106, v107
	v_or_b32_e32 v106, 16, v138
	v_mov_b32_e32 v107, v139
	v_lshlrev_b64 v[66:67], 13, v[66:67]
	v_cvt_pk_bf16_f32 v46, v46, v47
	v_cvt_pk_bf16_f32 v47, v48, v49
	v_cvt_pk_bf16_f32 v48, v42, v43
	v_add_u32_e32 v42, 0x90, v138
	v_mov_b32_e32 v43, v139
	v_lshl_add_u64 v[132:133], s[8:9], 0, v[132:133]
	v_lshlrev_b64 v[130:131], 1, v[130:131]
	v_lshlrev_b64 v[106:107], 13, v[106:107]
	v_cvt_pk_bf16_f32 v94, v94, v95
	v_cvt_pk_bf16_f32 v95, v96, v97
	v_cvt_pk_bf16_f32 v96, v90, v91
	v_or_b32_e32 v90, 32, v138
	v_mov_b32_e32 v91, v139
	v_lshl_add_u64 v[66:67], s[8:9], 0, v[66:67]
	v_lshlrev_b64 v[42:43], 13, v[42:43]
	v_cvt_pk_bf16_f32 v30, v30, v31
	v_cvt_pk_bf16_f32 v31, v32, v33
	v_cvt_pk_bf16_f32 v32, v26, v27
	v_add_u32_e32 v26, 0xa0, v138
	v_mov_b32_e32 v27, v139
	v_lshl_add_u64 v[132:133], v[132:133], 0, v[130:131]
	v_cvt_pk_bf16_f32 v113, v108, v109
	v_lshl_add_u64 v[106:107], s[8:9], 0, v[106:107]
	v_lshlrev_b64 v[90:91], 13, v[90:91]
	v_cvt_pk_bf16_f32 v78, v78, v79
	v_cvt_pk_bf16_f32 v79, v80, v81
	v_cvt_pk_bf16_f32 v80, v74, v75
	v_or_b32_e32 v74, 48, v138
	v_mov_b32_e32 v75, v139
	v_lshl_add_u64 v[66:67], v[66:67], 0, v[130:131]
	v_cvt_pk_bf16_f32 v49, v44, v45
	v_lshl_add_u64 v[42:43], s[8:9], 0, v[42:43]
	v_lshlrev_b64 v[26:27], 13, v[26:27]
	v_add_u32_e32 v138, 0xb0, v138
	global_store_dwordx4 v[132:133], v[110:113], off offset:256
	v_cvt_pk_bf16_f32 v97, v92, v93
	v_lshl_add_u64 v[90:91], s[8:9], 0, v[90:91]
	v_lshl_add_u64 v[110:111], v[106:107], 0, v[130:131]
	v_lshlrev_b64 v[74:75], 13, v[74:75]
	global_store_dwordx4 v[66:67], v[46:49], off offset:256
	v_cvt_pk_bf16_f32 v33, v28, v29
	v_lshl_add_u64 v[26:27], s[8:9], 0, v[26:27]
	v_lshl_add_u64 v[46:47], v[42:43], 0, v[130:131]
	v_cvt_pk_bf16_f32 v14, v14, v15
	v_cvt_pk_bf16_f32 v15, v16, v17
	v_cvt_pk_bf16_f32 v16, v10, v11
	v_lshlrev_b64 v[10:11], 13, v[138:139]
	global_store_dwordx4 v[110:111], v[94:97], off offset:256
	v_cvt_pk_bf16_f32 v81, v76, v77
	v_lshl_add_u64 v[74:75], s[8:9], 0, v[74:75]
	v_lshl_add_u64 v[94:95], v[90:91], 0, v[130:131]
	global_store_dwordx4 v[46:47], v[30:33], off offset:256
	v_cvt_pk_bf16_f32 v17, v12, v13
	v_lshl_add_u64 v[10:11], s[8:9], 0, v[10:11]
	v_lshl_add_u64 v[30:31], v[26:27], 0, v[130:131]
	v_cvt_pk_bf16_f32 v126, v126, v127
	v_cvt_pk_bf16_f32 v127, v128, v129
	v_cvt_pk_bf16_f32 v128, v122, v123
	v_cvt_pk_bf16_f32 v129, v124, v125
	v_cvt_pk_bf16_f32 v106, v118, v119
	v_cvt_pk_bf16_f32 v107, v120, v121
	v_cvt_pk_bf16_f32 v108, v114, v115
	v_cvt_pk_bf16_f32 v109, v116, v117
	v_cvt_pk_bf16_f32 v90, v102, v103
	v_cvt_pk_bf16_f32 v91, v104, v105
	v_cvt_pk_bf16_f32 v92, v98, v99
	v_cvt_pk_bf16_f32 v93, v100, v101
	global_store_dwordx4 v[94:95], v[78:81], off offset:256
	v_cvt_pk_bf16_f32 v76, v82, v83
	v_cvt_pk_bf16_f32 v77, v84, v85
	v_lshl_add_u64 v[78:79], v[74:75], 0, v[130:131]
	v_cvt_pk_bf16_f32 v74, v86, v87
	v_cvt_pk_bf16_f32 v75, v88, v89
	v_cvt_pk_bf16_f32 v73, v68, v69
	v_cvt_pk_bf16_f32 v62, v62, v63
	v_cvt_pk_bf16_f32 v63, v64, v65
	v_cvt_pk_bf16_f32 v64, v58, v59
	v_cvt_pk_bf16_f32 v65, v60, v61
	v_cvt_pk_bf16_f32 v42, v54, v55
	v_cvt_pk_bf16_f32 v43, v56, v57
	v_cvt_pk_bf16_f32 v44, v50, v51
	v_cvt_pk_bf16_f32 v45, v52, v53
	v_cvt_pk_bf16_f32 v26, v38, v39
	v_cvt_pk_bf16_f32 v27, v40, v41
	v_cvt_pk_bf16_f32 v28, v34, v35
	v_cvt_pk_bf16_f32 v29, v36, v37
	global_store_dwordx4 v[30:31], v[14:17], off offset:256
	v_cvt_pk_bf16_f32 v12, v18, v19
	v_cvt_pk_bf16_f32 v13, v20, v21
	v_lshl_add_u64 v[14:15], v[10:11], 0, v[130:131]
	v_cvt_pk_bf16_f32 v10, v22, v23
	v_cvt_pk_bf16_f32 v11, v24, v25
	v_cvt_pk_bf16_f32 v6, v6, v7
	v_cvt_pk_bf16_f32 v7, v8, v9
	v_cvt_pk_bf16_f32 v8, v2, v3
	v_cvt_pk_bf16_f32 v9, v4, v5
	global_store_dwordx4 v[132:133], v[126:129], off
	global_store_dwordx4 v[110:111], v[106:109], off
	global_store_dwordx4 v[94:95], v[90:93], off
	global_store_dwordx4 v[78:79], v[74:77], off
	global_store_dwordx4 v[78:79], v[70:73], off offset:256
	global_store_dwordx4 v[66:67], v[62:65], off
	global_store_dwordx4 v[46:47], v[42:45], off
	global_store_dwordx4 v[30:31], v[26:29], off
	global_store_dwordx4 v[14:15], v[10:13], off
	global_store_dwordx4 v[14:15], v[6:9], off offset:256
	s_waitcnt vmcnt(0)
	s_cmpk_lt_u32 s3, 0x100
	s_cbranch_scc0 .LBB0_1022
	s_barrier

.LBB0_1172:
	s_add_u32 s62, s20, 0xfff00000
	s_addc_u32 s63, s21, -1
	s_mov_b32 m0, s37
	ds_read_b128 v[142:145], v148
	global_load_lds_dwordx4 v130, s[62:63]
	s_mov_b32 m0, s38
	ds_read_b128 v[154:157], v148 offset:1024
	global_load_lds_dwordx4 v134, s[62:63]
	s_mov_b32 m0, s42
	ds_read_b128 v[158:161], v148 offset:2048
	global_load_lds_dwordx4 v138, s[20:21]
	s_mov_b32 m0, s43
	ds_read_b128 v[168:171], v148 offset:3072
	global_load_lds_dwordx4 v140, s[20:21]
	ds_read_b128 v[176:179], v149
	ds_read_b128 v[180:183], v149 offset:1024
	ds_read_b128 v[184:187], v149 offset:2048
	ds_read_b128 v[188:191], v149 offset:3072
	s_add_u32 s22, s20, 0xfff00080
	s_addc_u32 s23, s21, -1
	s_cmp_eq_u32 s61, 60
	s_cselect_b32 s25, s54, s23
	s_cselect_b32 s24, s55, s22
	s_cselect_b32 s23, s7, s60
	s_cselect_b32 s22, s56, s57
	ds_read_b128 v[192:195], v150
	ds_read_b128 v[202:205], v150 offset:1024
	ds_read_b128 v[206:209], v150 offset:2048
	ds_read_b128 v[210:213], v150 offset:3072
	ds_read_b128 v[214:217], v150 offset:4096
	ds_read_b128 v[218:221], v150 offset:5120
	ds_read_b128 v[222:225], v150 offset:6144
	ds_read_b128 v[226:229], v150 offset:7168
	s_waitcnt vmcnt(8)
	s_waitcnt lgkmcnt(0)
	s_barrier
	s_setprio 1
	s_waitcnt lgkmcnt(0)
	v_mfma_f32_16x16x32_bf16 v[126:129], v[142:145], v[192:195], v[126:129]
	v_mfma_f32_16x16x32_bf16 v[126:129], v[154:157], v[202:205], v[126:129]
	v_mfma_f32_16x16x32_bf16 v[118:121], v[168:171], v[202:205], v[118:121]
	v_mfma_f32_16x16x32_bf16 v[118:121], v[158:161], v[192:195], v[118:121]
	v_mfma_f32_16x16x32_bf16 v[102:105], v[158:161], v[206:209], v[102:105]
	v_mfma_f32_16x16x32_bf16 v[102:105], v[168:171], v[210:213], v[102:105]
	v_mfma_f32_16x16x32_bf16 v[110:113], v[154:157], v[210:213], v[110:113]
	v_mfma_f32_16x16x32_bf16 v[110:113], v[142:145], v[206:209], v[110:113]
	v_mfma_f32_16x16x32_bf16 v[94:97], v[142:145], v[214:217], v[94:97]
	v_mfma_f32_16x16x32_bf16 v[94:97], v[154:157], v[218:221], v[94:97]
	v_mfma_f32_16x16x32_bf16 v[86:89], v[168:171], v[218:221], v[86:89]
	v_mfma_f32_16x16x32_bf16 v[86:89], v[158:161], v[214:217], v[86:89]
	v_mfma_f32_16x16x32_bf16 v[70:73], v[158:161], v[222:225], v[70:73]
	v_mfma_f32_16x16x32_bf16 v[70:73], v[168:171], v[226:229], v[70:73]
	v_mfma_f32_16x16x32_bf16 v[78:81], v[154:157], v[226:229], v[78:81]
	v_mfma_f32_16x16x32_bf16 v[78:81], v[142:145], v[222:225], v[78:81]
	v_mfma_f32_16x16x32_bf16 v[74:77], v[176:179], v[222:225], v[74:77]
	v_mfma_f32_16x16x32_bf16 v[74:77], v[180:183], v[226:229], v[74:77]
	v_mfma_f32_16x16x32_bf16 v[66:69], v[188:191], v[226:229], v[66:69]
	v_mfma_f32_16x16x32_bf16 v[66:69], v[184:187], v[222:225], v[66:69]
	v_mfma_f32_16x16x32_bf16 v[82:85], v[184:187], v[214:217], v[82:85]
	v_mfma_f32_16x16x32_bf16 v[82:85], v[188:191], v[218:221], v[82:85]
	v_mfma_f32_16x16x32_bf16 v[90:93], v[180:183], v[218:221], v[90:93]
	v_mfma_f32_16x16x32_bf16 v[90:93], v[176:179], v[214:217], v[90:93]
	v_mfma_f32_16x16x32_bf16 v[106:109], v[176:179], v[206:209], v[106:109]
	v_mfma_f32_16x16x32_bf16 v[106:109], v[180:183], v[210:213], v[106:109]
	v_mfma_f32_16x16x32_bf16 v[98:101], v[188:191], v[210:213], v[98:101]
	v_mfma_f32_16x16x32_bf16 v[98:101], v[184:187], v[206:209], v[98:101]
	v_mfma_f32_16x16x32_bf16 v[114:117], v[184:187], v[192:195], v[114:117]
	v_mfma_f32_16x16x32_bf16 v[114:117], v[188:191], v[202:205], v[114:117]
	v_mfma_f32_16x16x32_bf16 v[122:125], v[180:183], v[202:205], v[122:125]
	v_mfma_f32_16x16x32_bf16 v[122:125], v[176:179], v[192:195], v[122:125]
	s_setprio 0
	s_barrier
	s_mov_b32 m0, s44
	s_add_u32 s62, s22, 0x100000
	global_load_lds_dwordx4 v132, s[22:23]
	s_mov_b32 m0, s45
	s_addc_u32 s63, s23, 0
	global_load_lds_dwordx4 v136, s[22:23]
	s_mov_b32 m0, s46
	ds_read_b128 v[192:195], v150 offset:16384
	global_load_lds_dwordx4 v132, s[62:63]
	s_mov_b32 m0, s47
	ds_read_b128 v[202:205], v150 offset:17408
	global_load_lds_dwordx4 v136, s[62:63]
	ds_read_b128 v[206:209], v150 offset:18432
	ds_read_b128 v[210:213], v150 offset:19456
	ds_read_b128 v[214:217], v150 offset:20480
	ds_read_b128 v[218:221], v150 offset:21504
	ds_read_b128 v[222:225], v150 offset:22528
	ds_read_b128 v[226:229], v150 offset:23552
	s_waitcnt vmcnt(6)
	s_waitcnt lgkmcnt(0)
	s_barrier
	s_setprio 1
	s_waitcnt lgkmcnt(0)
	v_mfma_f32_16x16x32_bf16 v[62:65], v[142:145], v[192:195], v[62:65]
	v_mfma_f32_16x16x32_bf16 v[62:65], v[154:157], v[202:205], v[62:65]
	v_mfma_f32_16x16x32_bf16 v[54:57], v[168:171], v[202:205], v[54:57]
	v_mfma_f32_16x16x32_bf16 v[54:57], v[158:161], v[192:195], v[54:57]
	v_mfma_f32_16x16x32_bf16 v[38:41], v[158:161], v[206:209], v[38:41]
	v_mfma_f32_16x16x32_bf16 v[38:41], v[168:171], v[210:213], v[38:41]
	v_mfma_f32_16x16x32_bf16 v[46:49], v[154:157], v[210:213], v[46:49]
	v_mfma_f32_16x16x32_bf16 v[46:49], v[142:145], v[206:209], v[46:49]
	v_mfma_f32_16x16x32_bf16 v[30:33], v[142:145], v[214:217], v[30:33]
	v_mfma_f32_16x16x32_bf16 v[30:33], v[154:157], v[218:221], v[30:33]
	v_mfma_f32_16x16x32_bf16 v[22:25], v[168:171], v[218:221], v[22:25]
	v_mfma_f32_16x16x32_bf16 v[22:25], v[158:161], v[214:217], v[22:25]
	v_mfma_f32_16x16x32_bf16 v[6:9], v[158:161], v[222:225], v[6:9]
	v_mfma_f32_16x16x32_bf16 v[6:9], v[168:171], v[226:229], v[6:9]
	v_mfma_f32_16x16x32_bf16 v[14:17], v[154:157], v[226:229], v[14:17]
	v_mfma_f32_16x16x32_bf16 v[14:17], v[142:145], v[222:225], v[14:17]
	v_mfma_f32_16x16x32_bf16 v[10:13], v[176:179], v[222:225], v[10:13]
	v_mfma_f32_16x16x32_bf16 v[10:13], v[180:183], v[226:229], v[10:13]
	v_mfma_f32_16x16x32_bf16 v[2:5], v[188:191], v[226:229], v[2:5]
	v_mfma_f32_16x16x32_bf16 v[2:5], v[184:187], v[222:225], v[2:5]
	v_mfma_f32_16x16x32_bf16 v[18:21], v[184:187], v[214:217], v[18:21]
	v_mfma_f32_16x16x32_bf16 v[18:21], v[188:191], v[218:221], v[18:21]
	v_mfma_f32_16x16x32_bf16 v[26:29], v[180:183], v[218:221], v[26:29]
	v_mfma_f32_16x16x32_bf16 v[26:29], v[176:179], v[214:217], v[26:29]
	v_mfma_f32_16x16x32_bf16 v[42:45], v[176:179], v[206:209], v[42:45]
	v_mfma_f32_16x16x32_bf16 v[42:45], v[180:183], v[210:213], v[42:45]
	v_mfma_f32_16x16x32_bf16 v[34:37], v[188:191], v[210:213], v[34:37]
	v_mfma_f32_16x16x32_bf16 v[34:37], v[184:187], v[206:209], v[34:37]
	v_mfma_f32_16x16x32_bf16 v[50:53], v[184:187], v[192:195], v[50:53]
	v_mfma_f32_16x16x32_bf16 v[50:53], v[188:191], v[202:205], v[50:53]
	v_mfma_f32_16x16x32_bf16 v[58:61], v[180:183], v[202:205], v[58:61]
	v_mfma_f32_16x16x32_bf16 v[58:61], v[176:179], v[192:195], v[58:61]
	s_setprio 0
	s_barrier
	s_mov_b32 m0, s31
	ds_read_b128 v[142:145], v151
	global_load_lds_dwordx4 v130, s[24:25]
	s_mov_b32 m0, s33
	ds_read_b128 v[154:157], v151 offset:1024
	global_load_lds_dwordx4 v134, s[24:25]
	s_add_u32 s24, s24, 0x100000
	s_addc_u32 s25, s25, 0
	s_mov_b32 m0, s34
	ds_read_b128 v[158:161], v151 offset:2048
	global_load_lds_dwordx4 v130, s[24:25]
	s_mov_b32 m0, s35
	ds_read_b128 v[168:171], v151 offset:3072
	global_load_lds_dwordx4 v134, s[24:25]
	ds_read_b128 v[176:179], v152
	ds_read_b128 v[180:183], v152 offset:1024
	ds_read_b128 v[184:187], v152 offset:2048
	ds_read_b128 v[188:191], v152 offset:3072
	ds_read_b128 v[192:195], v150 offset:32768
	ds_read_b128 v[202:205], v150 offset:33792
	ds_read_b128 v[206:209], v150 offset:34816
	ds_read_b128 v[210:213], v150 offset:35840
	ds_read_b128 v[214:217], v150 offset:36864
	ds_read_b128 v[218:221], v150 offset:37888
	ds_read_b128 v[222:225], v150 offset:38912
	ds_read_b128 v[226:229], v150 offset:39936
	s_waitcnt vmcnt(8)
	s_waitcnt lgkmcnt(0)
	s_barrier
	s_setprio 1
	s_waitcnt lgkmcnt(0)
	v_mfma_f32_16x16x32_bf16 v[126:129], v[142:145], v[192:195], v[126:129]
	v_mfma_f32_16x16x32_bf16 v[126:129], v[154:157], v[202:205], v[126:129]
	v_mfma_f32_16x16x32_bf16 v[118:121], v[168:171], v[202:205], v[118:121]
	v_mfma_f32_16x16x32_bf16 v[118:121], v[158:161], v[192:195], v[118:121]
	v_mfma_f32_16x16x32_bf16 v[102:105], v[158:161], v[206:209], v[102:105]
	v_mfma_f32_16x16x32_bf16 v[102:105], v[168:171], v[210:213], v[102:105]
	v_mfma_f32_16x16x32_bf16 v[110:113], v[154:157], v[210:213], v[110:113]
	v_mfma_f32_16x16x32_bf16 v[110:113], v[142:145], v[206:209], v[110:113]
	v_mfma_f32_16x16x32_bf16 v[94:97], v[142:145], v[214:217], v[94:97]
	v_mfma_f32_16x16x32_bf16 v[94:97], v[154:157], v[218:221], v[94:97]
	v_mfma_f32_16x16x32_bf16 v[86:89], v[168:171], v[218:221], v[86:89]
	v_mfma_f32_16x16x32_bf16 v[86:89], v[158:161], v[214:217], v[86:89]
	v_mfma_f32_16x16x32_bf16 v[70:73], v[158:161], v[222:225], v[70:73]
	v_mfma_f32_16x16x32_bf16 v[70:73], v[168:171], v[226:229], v[70:73]
	v_mfma_f32_16x16x32_bf16 v[78:81], v[154:157], v[226:229], v[78:81]
	v_mfma_f32_16x16x32_bf16 v[78:81], v[142:145], v[222:225], v[78:81]
	v_mfma_f32_16x16x32_bf16 v[74:77], v[176:179], v[222:225], v[74:77]
	v_mfma_f32_16x16x32_bf16 v[74:77], v[180:183], v[226:229], v[74:77]
	v_mfma_f32_16x16x32_bf16 v[66:69], v[188:191], v[226:229], v[66:69]
	v_mfma_f32_16x16x32_bf16 v[66:69], v[184:187], v[222:225], v[66:69]
	v_mfma_f32_16x16x32_bf16 v[82:85], v[184:187], v[214:217], v[82:85]
	v_mfma_f32_16x16x32_bf16 v[82:85], v[188:191], v[218:221], v[82:85]
	v_mfma_f32_16x16x32_bf16 v[90:93], v[180:183], v[218:221], v[90:93]
	v_mfma_f32_16x16x32_bf16 v[90:93], v[176:179], v[214:217], v[90:93]
	v_mfma_f32_16x16x32_bf16 v[106:109], v[176:179], v[206:209], v[106:109]
	v_mfma_f32_16x16x32_bf16 v[106:109], v[180:183], v[210:213], v[106:109]
	v_mfma_f32_16x16x32_bf16 v[98:101], v[188:191], v[210:213], v[98:101]
	v_mfma_f32_16x16x32_bf16 v[98:101], v[184:187], v[206:209], v[98:101]
	v_mfma_f32_16x16x32_bf16 v[114:117], v[184:187], v[192:195], v[114:117]
	v_mfma_f32_16x16x32_bf16 v[114:117], v[188:191], v[202:205], v[114:117]
	v_mfma_f32_16x16x32_bf16 v[122:125], v[180:183], v[202:205], v[122:125]
	v_mfma_f32_16x16x32_bf16 v[122:125], v[176:179], v[192:195], v[122:125]
	s_setprio 0
	s_barrier
	s_mov_b32 m0, s48
	s_add_u32 s22, s22, 0x80
	s_addc_u32 s23, s23, 0
	global_load_lds_dwordx4 v132, s[22:23]
	s_mov_b32 m0, s49
	ds_read_b128 v[192:195], v150 offset:49152
	global_load_lds_dwordx4 v136, s[22:23]
	s_mov_b32 m0, s50
	s_add_u32 s22, s22, 0x100000
	s_addc_u32 s23, s23, 0
	global_load_lds_dwordx4 v132, s[22:23]
	s_mov_b32 m0, s51
	ds_read_b128 v[202:205], v150 offset:50176
	global_load_lds_dwordx4 v136, s[22:23]
	ds_read_b128 v[206:209], v150 offset:51200
	ds_read_b128 v[210:213], v150 offset:52224
	ds_read_b128 v[214:217], v150 offset:53248
	ds_read_b128 v[218:221], v150 offset:54272
	ds_read_b128 v[222:225], v150 offset:55296
	ds_read_b128 v[226:229], v150 offset:56320
	s_waitcnt vmcnt(6)
	s_waitcnt lgkmcnt(0)
	s_barrier
	s_setprio 1
	s_waitcnt lgkmcnt(0)
	v_mfma_f32_16x16x32_bf16 v[62:65], v[142:145], v[192:195], v[62:65]
	v_mfma_f32_16x16x32_bf16 v[62:65], v[154:157], v[202:205], v[62:65]
	v_mfma_f32_16x16x32_bf16 v[54:57], v[168:171], v[202:205], v[54:57]
	v_mfma_f32_16x16x32_bf16 v[54:57], v[158:161], v[192:195], v[54:57]
	v_mfma_f32_16x16x32_bf16 v[38:41], v[158:161], v[206:209], v[38:41]
	v_mfma_f32_16x16x32_bf16 v[38:41], v[168:171], v[210:213], v[38:41]
	v_mfma_f32_16x16x32_bf16 v[46:49], v[154:157], v[210:213], v[46:49]
	v_mfma_f32_16x16x32_bf16 v[46:49], v[142:145], v[206:209], v[46:49]
	v_mfma_f32_16x16x32_bf16 v[30:33], v[142:145], v[214:217], v[30:33]
	v_mfma_f32_16x16x32_bf16 v[30:33], v[154:157], v[218:221], v[30:33]
	v_mfma_f32_16x16x32_bf16 v[22:25], v[168:171], v[218:221], v[22:25]
	v_mfma_f32_16x16x32_bf16 v[22:25], v[158:161], v[214:217], v[22:25]
	v_mfma_f32_16x16x32_bf16 v[6:9], v[158:161], v[222:225], v[6:9]
	v_mfma_f32_16x16x32_bf16 v[6:9], v[168:171], v[226:229], v[6:9]
	v_mfma_f32_16x16x32_bf16 v[14:17], v[154:157], v[226:229], v[14:17]
	v_mfma_f32_16x16x32_bf16 v[14:17], v[142:145], v[222:225], v[14:17]
	v_mfma_f32_16x16x32_bf16 v[10:13], v[176:179], v[222:225], v[10:13]
	v_mfma_f32_16x16x32_bf16 v[10:13], v[180:183], v[226:229], v[10:13]
	v_mfma_f32_16x16x32_bf16 v[2:5], v[188:191], v[226:229], v[2:5]
	v_mfma_f32_16x16x32_bf16 v[2:5], v[184:187], v[222:225], v[2:5]
	v_mfma_f32_16x16x32_bf16 v[18:21], v[184:187], v[214:217], v[18:21]
	v_mfma_f32_16x16x32_bf16 v[18:21], v[188:191], v[218:221], v[18:21]
	v_mfma_f32_16x16x32_bf16 v[26:29], v[180:183], v[218:221], v[26:29]
	v_mfma_f32_16x16x32_bf16 v[26:29], v[176:179], v[214:217], v[26:29]
	v_mfma_f32_16x16x32_bf16 v[42:45], v[176:179], v[206:209], v[42:45]
	v_mfma_f32_16x16x32_bf16 v[42:45], v[180:183], v[210:213], v[42:45]
	v_mfma_f32_16x16x32_bf16 v[34:37], v[188:191], v[210:213], v[34:37]
	v_mfma_f32_16x16x32_bf16 v[34:37], v[184:187], v[206:209], v[34:37]
	v_mfma_f32_16x16x32_bf16 v[50:53], v[184:187], v[192:195], v[50:53]
	v_mfma_f32_16x16x32_bf16 v[50:53], v[188:191], v[202:205], v[50:53]
	v_mfma_f32_16x16x32_bf16 v[58:61], v[180:183], v[202:205], v[58:61]
	v_mfma_f32_16x16x32_bf16 v[58:61], v[176:179], v[192:195], v[58:61]
	s_setprio 0
	s_barrier
	s_add_i32 s61, s61, 2
	s_add_u32 s20, s20, 0x100
	s_addc_u32 s21, s21, 0
	s_add_u32 s57, s57, 0x100
	s_addc_u32 s60, s60, 0
	s_cmp_gt_u32 s61, 61
	s_cbranch_scc0 .LBB0_1172
	s_and_b64 vcc, exec, s[16:17]
	s_cbranch_vccz .LBB0_1175
	s_barrier

.LBB0_1418:
	s_add_u32 s56, s22, 0xffd50000
	s_addc_u32 s57, s23, -1
	s_mov_b32 m0, s40
	ds_read_b128 v[142:145], v156
	global_load_lds_dwordx4 v130, s[56:57]
	s_mov_b32 m0, s41
	ds_read_b128 v[168:171], v156 offset:1024
	global_load_lds_dwordx4 v134, s[56:57]
	s_mov_b32 m0, s42
	ds_read_b128 v[176:179], v156 offset:2048
	global_load_lds_dwordx4 v138, s[22:23]
	s_mov_b32 m0, s43
	ds_read_b128 v[180:183], v156 offset:3072
	global_load_lds_dwordx4 v140, s[22:23]
	ds_read_b128 v[184:187], v157
	ds_read_b128 v[188:191], v157 offset:1024
	ds_read_b128 v[192:195], v157 offset:2048
	ds_read_b128 v[204:207], v157 offset:3072
	s_add_u32 s24, s22, 0xffd50080
	s_addc_u32 s25, s23, -1
	s_cmpk_eq_i32 s55, 0xa8
	s_cselect_b32 s27, s19, s25
	s_cselect_b32 s26, s18, s24
	s_cselect_b32 s25, s17, s54
	s_cselect_b32 s24, s16, s53
	ds_read_b128 v[208:211], v158
	ds_read_b128 v[212:215], v158 offset:1024
	ds_read_b128 v[216:219], v158 offset:2048
	ds_read_b128 v[220:223], v158 offset:3072
	ds_read_b128 v[224:227], v158 offset:4096
	ds_read_b128 v[228:231], v158 offset:5120
	ds_read_b128 v[232:235], v158 offset:6144
	ds_read_b128 v[236:239], v158 offset:7168
	s_waitcnt vmcnt(8)
	s_waitcnt lgkmcnt(0)
	s_barrier
	s_setprio 1
	s_waitcnt lgkmcnt(0)
	v_mfma_f32_16x16x32_bf16 v[126:129], v[142:145], v[208:211], v[126:129]
	v_mfma_f32_16x16x32_bf16 v[126:129], v[168:171], v[212:215], v[126:129]
	v_mfma_f32_16x16x32_bf16 v[122:125], v[180:183], v[212:215], v[122:125]
	v_mfma_f32_16x16x32_bf16 v[122:125], v[176:179], v[208:211], v[122:125]
	v_mfma_f32_16x16x32_bf16 v[106:109], v[176:179], v[216:219], v[106:109]
	v_mfma_f32_16x16x32_bf16 v[106:109], v[180:183], v[220:223], v[106:109]
	v_mfma_f32_16x16x32_bf16 v[110:113], v[168:171], v[220:223], v[110:113]
	v_mfma_f32_16x16x32_bf16 v[110:113], v[142:145], v[216:219], v[110:113]
	v_mfma_f32_16x16x32_bf16 v[94:97], v[142:145], v[224:227], v[94:97]
	v_mfma_f32_16x16x32_bf16 v[94:97], v[168:171], v[228:231], v[94:97]
	v_mfma_f32_16x16x32_bf16 v[90:93], v[180:183], v[228:231], v[90:93]
	v_mfma_f32_16x16x32_bf16 v[90:93], v[176:179], v[224:227], v[90:93]
	v_mfma_f32_16x16x32_bf16 v[74:77], v[176:179], v[232:235], v[74:77]
	v_mfma_f32_16x16x32_bf16 v[74:77], v[180:183], v[236:239], v[74:77]
	v_mfma_f32_16x16x32_bf16 v[78:81], v[168:171], v[236:239], v[78:81]
	v_mfma_f32_16x16x32_bf16 v[78:81], v[142:145], v[232:235], v[78:81]
	v_mfma_f32_16x16x32_bf16 v[70:73], v[184:187], v[232:235], v[70:73]
	v_mfma_f32_16x16x32_bf16 v[70:73], v[188:191], v[236:239], v[70:73]
	v_mfma_f32_16x16x32_bf16 v[66:69], v[204:207], v[236:239], v[66:69]
	v_mfma_f32_16x16x32_bf16 v[66:69], v[192:195], v[232:235], v[66:69]
	v_mfma_f32_16x16x32_bf16 v[82:85], v[192:195], v[224:227], v[82:85]
	v_mfma_f32_16x16x32_bf16 v[82:85], v[204:207], v[228:231], v[82:85]
	v_mfma_f32_16x16x32_bf16 v[86:89], v[188:191], v[228:231], v[86:89]
	v_mfma_f32_16x16x32_bf16 v[86:89], v[184:187], v[224:227], v[86:89]
	v_mfma_f32_16x16x32_bf16 v[102:105], v[184:187], v[216:219], v[102:105]
	v_mfma_f32_16x16x32_bf16 v[102:105], v[188:191], v[220:223], v[102:105]
	v_mfma_f32_16x16x32_bf16 v[98:101], v[204:207], v[220:223], v[98:101]
	v_mfma_f32_16x16x32_bf16 v[98:101], v[192:195], v[216:219], v[98:101]
	v_mfma_f32_16x16x32_bf16 v[114:117], v[192:195], v[208:211], v[114:117]
	v_mfma_f32_16x16x32_bf16 v[114:117], v[204:207], v[212:215], v[114:117]
	v_mfma_f32_16x16x32_bf16 v[118:121], v[188:191], v[212:215], v[118:121]
	v_mfma_f32_16x16x32_bf16 v[118:121], v[184:187], v[208:211], v[118:121]
	s_setprio 0
	s_barrier
	s_mov_b32 m0, s44
	s_add_u32 s56, s24, 0x2b0000
	global_load_lds_dwordx4 v132, s[24:25]
	s_mov_b32 m0, s45
	s_addc_u32 s57, s25, 0
	global_load_lds_dwordx4 v136, s[24:25]
	s_mov_b32 m0, s46
	ds_read_b128 v[208:211], v158 offset:16384
	global_load_lds_dwordx4 v132, s[56:57]
	s_mov_b32 m0, s47
	ds_read_b128 v[212:215], v158 offset:17408
	global_load_lds_dwordx4 v136, s[56:57]
	ds_read_b128 v[216:219], v158 offset:18432
	ds_read_b128 v[220:223], v158 offset:19456
	ds_read_b128 v[224:227], v158 offset:20480
	ds_read_b128 v[228:231], v158 offset:21504
	ds_read_b128 v[232:235], v158 offset:22528
	ds_read_b128 v[236:239], v158 offset:23552
	s_waitcnt vmcnt(6)
	s_waitcnt lgkmcnt(0)
	s_barrier
	s_setprio 1
	s_waitcnt lgkmcnt(0)
	v_mfma_f32_16x16x32_bf16 v[62:65], v[142:145], v[208:211], v[62:65]
	v_mfma_f32_16x16x32_bf16 v[62:65], v[168:171], v[212:215], v[62:65]
	v_mfma_f32_16x16x32_bf16 v[58:61], v[180:183], v[212:215], v[58:61]
	v_mfma_f32_16x16x32_bf16 v[58:61], v[176:179], v[208:211], v[58:61]
	v_mfma_f32_16x16x32_bf16 v[42:45], v[176:179], v[216:219], v[42:45]
	v_mfma_f32_16x16x32_bf16 v[42:45], v[180:183], v[220:223], v[42:45]
	v_mfma_f32_16x16x32_bf16 v[46:49], v[168:171], v[220:223], v[46:49]
	v_mfma_f32_16x16x32_bf16 v[46:49], v[142:145], v[216:219], v[46:49]
	v_mfma_f32_16x16x32_bf16 v[30:33], v[142:145], v[224:227], v[30:33]
	v_mfma_f32_16x16x32_bf16 v[30:33], v[168:171], v[228:231], v[30:33]
	v_mfma_f32_16x16x32_bf16 v[26:29], v[180:183], v[228:231], v[26:29]
	v_mfma_f32_16x16x32_bf16 v[26:29], v[176:179], v[224:227], v[26:29]
	v_mfma_f32_16x16x32_bf16 v[10:13], v[176:179], v[232:235], v[10:13]
	v_mfma_f32_16x16x32_bf16 v[10:13], v[180:183], v[236:239], v[10:13]
	v_mfma_f32_16x16x32_bf16 v[14:17], v[168:171], v[236:239], v[14:17]
	v_mfma_f32_16x16x32_bf16 v[14:17], v[142:145], v[232:235], v[14:17]
	v_mfma_f32_16x16x32_bf16 v[6:9], v[184:187], v[232:235], v[6:9]
	v_mfma_f32_16x16x32_bf16 v[6:9], v[188:191], v[236:239], v[6:9]
	v_mfma_f32_16x16x32_bf16 v[2:5], v[204:207], v[236:239], v[2:5]
	v_mfma_f32_16x16x32_bf16 v[2:5], v[192:195], v[232:235], v[2:5]
	v_mfma_f32_16x16x32_bf16 v[18:21], v[192:195], v[224:227], v[18:21]
	v_mfma_f32_16x16x32_bf16 v[18:21], v[204:207], v[228:231], v[18:21]
	v_mfma_f32_16x16x32_bf16 v[22:25], v[188:191], v[228:231], v[22:25]
	v_mfma_f32_16x16x32_bf16 v[22:25], v[184:187], v[224:227], v[22:25]
	v_mfma_f32_16x16x32_bf16 v[38:41], v[184:187], v[216:219], v[38:41]
	v_mfma_f32_16x16x32_bf16 v[38:41], v[188:191], v[220:223], v[38:41]
	v_mfma_f32_16x16x32_bf16 v[34:37], v[204:207], v[220:223], v[34:37]
	v_mfma_f32_16x16x32_bf16 v[34:37], v[192:195], v[216:219], v[34:37]
	v_mfma_f32_16x16x32_bf16 v[50:53], v[192:195], v[208:211], v[50:53]
	v_mfma_f32_16x16x32_bf16 v[50:53], v[204:207], v[212:215], v[50:53]
	v_mfma_f32_16x16x32_bf16 v[54:57], v[188:191], v[212:215], v[54:57]
	v_mfma_f32_16x16x32_bf16 v[54:57], v[184:187], v[208:211], v[54:57]
	s_setprio 0
	s_barrier
	s_mov_b32 m0, s35
	ds_read_b128 v[142:145], v159
	global_load_lds_dwordx4 v130, s[26:27]
	s_mov_b32 m0, s36
	ds_read_b128 v[168:171], v159 offset:1024
	global_load_lds_dwordx4 v134, s[26:27]
	s_add_u32 s26, s26, 0x2b0000
	s_addc_u32 s27, s27, 0
	s_mov_b32 m0, s37
	ds_read_b128 v[176:179], v159 offset:2048
	global_load_lds_dwordx4 v130, s[26:27]
	s_mov_b32 m0, s38
	ds_read_b128 v[180:183], v159 offset:3072
	global_load_lds_dwordx4 v134, s[26:27]
	ds_read_b128 v[184:187], v160
	ds_read_b128 v[188:191], v160 offset:1024
	ds_read_b128 v[192:195], v160 offset:2048
	ds_read_b128 v[204:207], v160 offset:3072
	ds_read_b128 v[208:211], v158 offset:32768
	ds_read_b128 v[212:215], v158 offset:33792
	ds_read_b128 v[216:219], v158 offset:34816
	ds_read_b128 v[220:223], v158 offset:35840
	ds_read_b128 v[224:227], v158 offset:36864
	ds_read_b128 v[228:231], v158 offset:37888
	ds_read_b128 v[232:235], v158 offset:38912
	ds_read_b128 v[236:239], v158 offset:39936
	s_waitcnt vmcnt(8)
	s_waitcnt lgkmcnt(0)
	s_barrier
	s_setprio 1
	s_waitcnt lgkmcnt(0)
	v_mfma_f32_16x16x32_bf16 v[126:129], v[142:145], v[208:211], v[126:129]
	v_mfma_f32_16x16x32_bf16 v[126:129], v[168:171], v[212:215], v[126:129]
	v_mfma_f32_16x16x32_bf16 v[122:125], v[180:183], v[212:215], v[122:125]
	v_mfma_f32_16x16x32_bf16 v[122:125], v[176:179], v[208:211], v[122:125]
	v_mfma_f32_16x16x32_bf16 v[106:109], v[176:179], v[216:219], v[106:109]
	v_mfma_f32_16x16x32_bf16 v[106:109], v[180:183], v[220:223], v[106:109]
	v_mfma_f32_16x16x32_bf16 v[110:113], v[168:171], v[220:223], v[110:113]
	v_mfma_f32_16x16x32_bf16 v[110:113], v[142:145], v[216:219], v[110:113]
	v_mfma_f32_16x16x32_bf16 v[94:97], v[142:145], v[224:227], v[94:97]
	v_mfma_f32_16x16x32_bf16 v[94:97], v[168:171], v[228:231], v[94:97]
	v_mfma_f32_16x16x32_bf16 v[90:93], v[180:183], v[228:231], v[90:93]
	v_mfma_f32_16x16x32_bf16 v[90:93], v[176:179], v[224:227], v[90:93]
	v_mfma_f32_16x16x32_bf16 v[74:77], v[176:179], v[232:235], v[74:77]
	v_mfma_f32_16x16x32_bf16 v[74:77], v[180:183], v[236:239], v[74:77]
	v_mfma_f32_16x16x32_bf16 v[78:81], v[168:171], v[236:239], v[78:81]
	v_mfma_f32_16x16x32_bf16 v[78:81], v[142:145], v[232:235], v[78:81]
	v_mfma_f32_16x16x32_bf16 v[70:73], v[184:187], v[232:235], v[70:73]
	v_mfma_f32_16x16x32_bf16 v[70:73], v[188:191], v[236:239], v[70:73]
	v_mfma_f32_16x16x32_bf16 v[66:69], v[204:207], v[236:239], v[66:69]
	v_mfma_f32_16x16x32_bf16 v[66:69], v[192:195], v[232:235], v[66:69]
	v_mfma_f32_16x16x32_bf16 v[82:85], v[192:195], v[224:227], v[82:85]
	v_mfma_f32_16x16x32_bf16 v[82:85], v[204:207], v[228:231], v[82:85]
	v_mfma_f32_16x16x32_bf16 v[86:89], v[188:191], v[228:231], v[86:89]
	v_mfma_f32_16x16x32_bf16 v[86:89], v[184:187], v[224:227], v[86:89]
	v_mfma_f32_16x16x32_bf16 v[102:105], v[184:187], v[216:219], v[102:105]
	v_mfma_f32_16x16x32_bf16 v[102:105], v[188:191], v[220:223], v[102:105]
	v_mfma_f32_16x16x32_bf16 v[98:101], v[204:207], v[220:223], v[98:101]
	v_mfma_f32_16x16x32_bf16 v[98:101], v[192:195], v[216:219], v[98:101]
	v_mfma_f32_16x16x32_bf16 v[114:117], v[192:195], v[208:211], v[114:117]
	v_mfma_f32_16x16x32_bf16 v[114:117], v[204:207], v[212:215], v[114:117]
	v_mfma_f32_16x16x32_bf16 v[118:121], v[188:191], v[212:215], v[118:121]
	v_mfma_f32_16x16x32_bf16 v[118:121], v[184:187], v[208:211], v[118:121]
	s_setprio 0
	s_barrier
	s_mov_b32 m0, s48
	s_add_u32 s24, s24, 0x80
	s_addc_u32 s25, s25, 0
	global_load_lds_dwordx4 v132, s[24:25]
	s_mov_b32 m0, s49
	ds_read_b128 v[208:211], v158 offset:49152
	global_load_lds_dwordx4 v136, s[24:25]
	s_mov_b32 m0, s50
	s_add_u32 s24, s24, 0x2b0000
	s_addc_u32 s25, s25, 0
	global_load_lds_dwordx4 v132, s[24:25]
	s_add_i32 m0, s50, 0x2000
	ds_read_b128 v[212:215], v158 offset:50176
	global_load_lds_dwordx4 v136, s[24:25]
	ds_read_b128 v[216:219], v158 offset:51200
	ds_read_b128 v[220:223], v158 offset:52224
	ds_read_b128 v[224:227], v158 offset:53248
	ds_read_b128 v[228:231], v158 offset:54272
	ds_read_b128 v[232:235], v158 offset:55296
	ds_read_b128 v[236:239], v158 offset:56320
	s_waitcnt vmcnt(6)
	s_waitcnt lgkmcnt(0)
	s_barrier
	s_setprio 1
	s_waitcnt lgkmcnt(0)
	v_mfma_f32_16x16x32_bf16 v[62:65], v[142:145], v[208:211], v[62:65]
	v_mfma_f32_16x16x32_bf16 v[62:65], v[168:171], v[212:215], v[62:65]
	v_mfma_f32_16x16x32_bf16 v[58:61], v[180:183], v[212:215], v[58:61]
	v_mfma_f32_16x16x32_bf16 v[58:61], v[176:179], v[208:211], v[58:61]
	v_mfma_f32_16x16x32_bf16 v[42:45], v[176:179], v[216:219], v[42:45]
	v_mfma_f32_16x16x32_bf16 v[42:45], v[180:183], v[220:223], v[42:45]
	v_mfma_f32_16x16x32_bf16 v[46:49], v[168:171], v[220:223], v[46:49]
	v_mfma_f32_16x16x32_bf16 v[46:49], v[142:145], v[216:219], v[46:49]
	v_mfma_f32_16x16x32_bf16 v[30:33], v[142:145], v[224:227], v[30:33]
	v_mfma_f32_16x16x32_bf16 v[30:33], v[168:171], v[228:231], v[30:33]
	v_mfma_f32_16x16x32_bf16 v[26:29], v[180:183], v[228:231], v[26:29]
	v_mfma_f32_16x16x32_bf16 v[26:29], v[176:179], v[224:227], v[26:29]
	v_mfma_f32_16x16x32_bf16 v[10:13], v[176:179], v[232:235], v[10:13]
	v_mfma_f32_16x16x32_bf16 v[10:13], v[180:183], v[236:239], v[10:13]
	v_mfma_f32_16x16x32_bf16 v[14:17], v[168:171], v[236:239], v[14:17]
	v_mfma_f32_16x16x32_bf16 v[14:17], v[142:145], v[232:235], v[14:17]
	v_mfma_f32_16x16x32_bf16 v[6:9], v[184:187], v[232:235], v[6:9]
	v_mfma_f32_16x16x32_bf16 v[6:9], v[188:191], v[236:239], v[6:9]
	v_mfma_f32_16x16x32_bf16 v[2:5], v[204:207], v[236:239], v[2:5]
	v_mfma_f32_16x16x32_bf16 v[2:5], v[192:195], v[232:235], v[2:5]
	v_mfma_f32_16x16x32_bf16 v[18:21], v[192:195], v[224:227], v[18:21]
	v_mfma_f32_16x16x32_bf16 v[18:21], v[204:207], v[228:231], v[18:21]
	v_mfma_f32_16x16x32_bf16 v[22:25], v[188:191], v[228:231], v[22:25]
	v_mfma_f32_16x16x32_bf16 v[22:25], v[184:187], v[224:227], v[22:25]
	v_mfma_f32_16x16x32_bf16 v[38:41], v[184:187], v[216:219], v[38:41]
	v_mfma_f32_16x16x32_bf16 v[38:41], v[188:191], v[220:223], v[38:41]
	v_mfma_f32_16x16x32_bf16 v[34:37], v[204:207], v[220:223], v[34:37]
	v_mfma_f32_16x16x32_bf16 v[34:37], v[192:195], v[216:219], v[34:37]
	v_mfma_f32_16x16x32_bf16 v[50:53], v[192:195], v[208:211], v[50:53]
	v_mfma_f32_16x16x32_bf16 v[50:53], v[204:207], v[212:215], v[50:53]
	v_mfma_f32_16x16x32_bf16 v[54:57], v[188:191], v[212:215], v[54:57]
	v_mfma_f32_16x16x32_bf16 v[54:57], v[184:187], v[208:211], v[54:57]
	s_setprio 0
	s_barrier
	s_add_i32 s55, s55, 2
	s_add_u32 s22, s22, 0x100
	s_addc_u32 s23, s23, 0
	s_add_u32 s53, s53, 0x100
	s_addc_u32 s54, s54, 0
	s_cmpk_gt_u32 s55, 0xa9
	s_cbranch_scc0 .LBB0_1418
	s_and_b64 vcc, exec, s[14:15]
	s_cbranch_vccz .LBB0_1421
	s_barrier

.LBB0_1432:
	ds_read_b128 v[150:153], v139
	ds_read_b128 v[154:157], v139 offset:1024
	ds_read_b128 v[158:161], v139 offset:2048
	ds_read_b128 v[168:171], v139 offset:3072
	ds_read_b128 v[176:179], v144
	ds_read_b128 v[180:183], v144 offset:1024
	ds_read_b128 v[184:187], v144 offset:2048
	ds_read_b128 v[188:191], v144 offset:3072
	s_add_i32 s42, s15, 2
	s_add_u32 s14, s12, 0xc2050080
	s_addc_u32 s16, s13, -1
	s_cmp_lg_u32 s30, s15
	s_cselect_b32 s14, s14, 0
	s_cselect_b32 s15, s16, 0
	s_add_u32 s16, s4, s14
	s_addc_u32 s17, s5, s15
	s_add_u32 s14, s8, s14
	s_addc_u32 s15, s9, s15
	s_mov_b32 m0, s31
	v_lshl_add_u64 v[172:173], v[140:141], 0, s[12:13]
	ds_read_b128 v[192:195], v145
	ds_read_b128 v[204:207], v145 offset:1024
	ds_read_b128 v[208:211], v145 offset:2048
	ds_read_b128 v[212:215], v145 offset:3072
	ds_read_b128 v[216:219], v145 offset:4096
	ds_read_b128 v[220:223], v145 offset:5120
	ds_read_b128 v[224:227], v145 offset:6144
	ds_read_b128 v[228:231], v145 offset:7168
	global_load_lds_dwordx4 v[172:173], off
	v_lshl_add_u64 v[172:173], v[142:143], 0, s[12:13]
	s_mov_b32 m0, s33
	s_nop 0
	global_load_lds_dwordx4 v[172:173], off
	s_waitcnt vmcnt(8)
	s_waitcnt lgkmcnt(0)
	s_barrier
	s_setprio 1
	s_waitcnt lgkmcnt(0)
	v_mfma_f32_16x16x32_bf16 v[126:129], v[150:153], v[192:195], v[126:129]
	v_mfma_f32_16x16x32_bf16 v[126:129], v[154:157], v[204:207], v[126:129]
	v_mfma_f32_16x16x32_bf16 v[122:125], v[168:171], v[204:207], v[122:125]
	v_mfma_f32_16x16x32_bf16 v[122:125], v[158:161], v[192:195], v[122:125]
	v_mfma_f32_16x16x32_bf16 v[114:117], v[158:161], v[208:211], v[114:117]
	v_mfma_f32_16x16x32_bf16 v[114:117], v[168:171], v[212:215], v[114:117]
	v_mfma_f32_16x16x32_bf16 v[118:121], v[154:157], v[212:215], v[118:121]
	v_mfma_f32_16x16x32_bf16 v[118:121], v[150:153], v[208:211], v[118:121]
	v_mfma_f32_16x16x32_bf16 v[102:105], v[150:153], v[216:219], v[102:105]
	v_mfma_f32_16x16x32_bf16 v[102:105], v[154:157], v[220:223], v[102:105]
	v_mfma_f32_16x16x32_bf16 v[98:101], v[168:171], v[220:223], v[98:101]
	v_mfma_f32_16x16x32_bf16 v[98:101], v[158:161], v[216:219], v[98:101]
	v_mfma_f32_16x16x32_bf16 v[82:85], v[158:161], v[224:227], v[82:85]
	v_mfma_f32_16x16x32_bf16 v[82:85], v[168:171], v[228:231], v[82:85]
	v_mfma_f32_16x16x32_bf16 v[86:89], v[154:157], v[228:231], v[86:89]
	v_mfma_f32_16x16x32_bf16 v[86:89], v[150:153], v[224:227], v[86:89]
	v_mfma_f32_16x16x32_bf16 v[70:73], v[176:179], v[224:227], v[70:73]
	v_mfma_f32_16x16x32_bf16 v[70:73], v[180:183], v[228:231], v[70:73]
	v_mfma_f32_16x16x32_bf16 v[66:69], v[188:191], v[228:231], v[66:69]
	v_mfma_f32_16x16x32_bf16 v[66:69], v[184:187], v[224:227], v[66:69]
	v_mfma_f32_16x16x32_bf16 v[74:77], v[184:187], v[216:219], v[74:77]
	v_mfma_f32_16x16x32_bf16 v[74:77], v[188:191], v[220:223], v[74:77]
	v_mfma_f32_16x16x32_bf16 v[78:81], v[180:183], v[220:223], v[78:81]
	v_mfma_f32_16x16x32_bf16 v[78:81], v[176:179], v[216:219], v[78:81]
	v_mfma_f32_16x16x32_bf16 v[94:97], v[176:179], v[208:211], v[94:97]
	v_mfma_f32_16x16x32_bf16 v[94:97], v[180:183], v[212:215], v[94:97]
	v_mfma_f32_16x16x32_bf16 v[90:93], v[188:191], v[212:215], v[90:93]
	v_mfma_f32_16x16x32_bf16 v[90:93], v[184:187], v[208:211], v[90:93]
	v_mfma_f32_16x16x32_bf16 v[106:109], v[184:187], v[192:195], v[106:109]
	v_mfma_f32_16x16x32_bf16 v[106:109], v[188:191], v[204:207], v[106:109]
	v_mfma_f32_16x16x32_bf16 v[110:113], v[180:183], v[204:207], v[110:113]
	v_mfma_f32_16x16x32_bf16 v[110:113], v[176:179], v[192:195], v[110:113]
	s_setprio 0
	s_barrier
	s_mov_b32 m0, s34
	v_lshl_add_u64 v[172:173], s[14:15], 0, v[132:133]
	s_add_u32 s44, s14, 0x2b0000
	ds_read_b128 v[192:195], v145 offset:16384
	ds_read_b128 v[204:207], v145 offset:17408
	ds_read_b128 v[208:211], v145 offset:18432
	ds_read_b128 v[212:215], v145 offset:19456
	ds_read_b128 v[216:219], v145 offset:20480
	ds_read_b128 v[220:223], v145 offset:21504
	ds_read_b128 v[224:227], v145 offset:22528
	ds_read_b128 v[228:231], v145 offset:23552
	global_load_lds_dwordx4 v[172:173], off
	v_lshl_add_u64 v[196:197], s[14:15], 0, v[136:137]
	s_mov_b32 m0, s35
	s_addc_u32 s45, s15, 0
	global_load_lds_dwordx4 v[196:197], off
	v_lshl_add_u64 v[232:233], s[44:45], 0, v[132:133]
	s_mov_b32 m0, s36
	v_lshl_add_u64 v[234:235], s[16:17], 0, v[134:135]
	global_load_lds_dwordx4 v[232:233], off
	v_lshl_add_u64 v[232:233], s[44:45], 0, v[136:137]
	s_mov_b32 m0, s37
	s_nop 0
	global_load_lds_dwordx4 v[232:233], off
	v_lshl_add_u64 v[232:233], s[16:17], 0, v[130:131]
	s_mov_b32 m0, s21
	s_nop 0
	global_load_lds_dwordx4 v[232:233], off
	s_mov_b32 m0, s22
	s_nop 0
	global_load_lds_dwordx4 v[234:235], off
	s_waitcnt vmcnt(8)
	s_waitcnt lgkmcnt(0)
	s_barrier
	s_setprio 1
	s_waitcnt lgkmcnt(0)
	v_mfma_f32_16x16x32_bf16 v[62:65], v[150:153], v[192:195], v[62:65]
	v_mfma_f32_16x16x32_bf16 v[62:65], v[154:157], v[204:207], v[62:65]
	v_mfma_f32_16x16x32_bf16 v[58:61], v[168:171], v[204:207], v[58:61]
	v_mfma_f32_16x16x32_bf16 v[58:61], v[158:161], v[192:195], v[58:61]
	v_mfma_f32_16x16x32_bf16 v[50:53], v[158:161], v[208:211], v[50:53]
	v_mfma_f32_16x16x32_bf16 v[50:53], v[168:171], v[212:215], v[50:53]
	v_mfma_f32_16x16x32_bf16 v[54:57], v[154:157], v[212:215], v[54:57]
	v_mfma_f32_16x16x32_bf16 v[54:57], v[150:153], v[208:211], v[54:57]
	v_mfma_f32_16x16x32_bf16 v[38:41], v[150:153], v[216:219], v[38:41]
	v_mfma_f32_16x16x32_bf16 v[38:41], v[154:157], v[220:223], v[38:41]
	v_mfma_f32_16x16x32_bf16 v[34:37], v[168:171], v[220:223], v[34:37]
	v_mfma_f32_16x16x32_bf16 v[34:37], v[158:161], v[216:219], v[34:37]
	v_mfma_f32_16x16x32_bf16 v[18:21], v[158:161], v[224:227], v[18:21]
	v_mfma_f32_16x16x32_bf16 v[18:21], v[168:171], v[228:231], v[18:21]
	v_mfma_f32_16x16x32_bf16 v[22:25], v[154:157], v[228:231], v[22:25]
	v_mfma_f32_16x16x32_bf16 v[22:25], v[150:153], v[224:227], v[22:25]
	v_mfma_f32_16x16x32_bf16 v[6:9], v[176:179], v[224:227], v[6:9]
	v_mfma_f32_16x16x32_bf16 v[6:9], v[180:183], v[228:231], v[6:9]
	v_mfma_f32_16x16x32_bf16 v[2:5], v[188:191], v[228:231], v[2:5]
	v_mfma_f32_16x16x32_bf16 v[2:5], v[184:187], v[224:227], v[2:5]
	v_mfma_f32_16x16x32_bf16 v[10:13], v[184:187], v[216:219], v[10:13]
	v_mfma_f32_16x16x32_bf16 v[10:13], v[188:191], v[220:223], v[10:13]
	v_mfma_f32_16x16x32_bf16 v[14:17], v[180:183], v[220:223], v[14:17]
	v_mfma_f32_16x16x32_bf16 v[14:17], v[176:179], v[216:219], v[14:17]
	v_mfma_f32_16x16x32_bf16 v[30:33], v[176:179], v[208:211], v[30:33]
	v_mfma_f32_16x16x32_bf16 v[30:33], v[180:183], v[212:215], v[30:33]
	v_mfma_f32_16x16x32_bf16 v[26:29], v[188:191], v[212:215], v[26:29]
	v_mfma_f32_16x16x32_bf16 v[26:29], v[184:187], v[208:211], v[26:29]
	v_mfma_f32_16x16x32_bf16 v[42:45], v[184:187], v[192:195], v[42:45]
	v_mfma_f32_16x16x32_bf16 v[42:45], v[188:191], v[204:207], v[42:45]
	v_mfma_f32_16x16x32_bf16 v[46:49], v[180:183], v[204:207], v[46:49]
	v_mfma_f32_16x16x32_bf16 v[46:49], v[176:179], v[192:195], v[46:49]
	s_setprio 0
	s_barrier
	ds_read_b128 v[150:153], v146
	ds_read_b128 v[154:157], v146 offset:1024
	ds_read_b128 v[158:161], v146 offset:2048
	ds_read_b128 v[168:171], v146 offset:3072
	ds_read_b128 v[176:179], v147
	ds_read_b128 v[180:183], v147 offset:1024
	ds_read_b128 v[184:187], v147 offset:2048
	ds_read_b128 v[188:191], v147 offset:3072
	s_add_u32 s16, s16, 0x2b0000
	s_addc_u32 s17, s17, 0
	s_mov_b32 m0, s23
	v_lshl_add_u64 v[236:237], s[16:17], 0, v[130:131]
	ds_read_b128 v[192:195], v145 offset:32768
	ds_read_b128 v[204:207], v145 offset:33792
	ds_read_b128 v[208:211], v145 offset:34816
	ds_read_b128 v[212:215], v145 offset:35840
	ds_read_b128 v[216:219], v145 offset:36864
	ds_read_b128 v[220:223], v145 offset:37888
	ds_read_b128 v[224:227], v145 offset:38912
	ds_read_b128 v[228:231], v145 offset:39936
	global_load_lds_dwordx4 v[236:237], off
	v_lshl_add_u64 v[236:237], s[16:17], 0, v[134:135]
	s_mov_b32 m0, s24
	s_nop 0
	global_load_lds_dwordx4 v[236:237], off
	s_waitcnt vmcnt(8)
	s_waitcnt lgkmcnt(0)
	s_barrier
	s_setprio 1
	s_waitcnt lgkmcnt(0)
	v_mfma_f32_16x16x32_bf16 v[126:129], v[150:153], v[192:195], v[126:129]
	v_mfma_f32_16x16x32_bf16 v[126:129], v[154:157], v[204:207], v[126:129]
	v_mfma_f32_16x16x32_bf16 v[122:125], v[168:171], v[204:207], v[122:125]
	v_mfma_f32_16x16x32_bf16 v[122:125], v[158:161], v[192:195], v[122:125]
	v_mfma_f32_16x16x32_bf16 v[114:117], v[158:161], v[208:211], v[114:117]
	v_mfma_f32_16x16x32_bf16 v[114:117], v[168:171], v[212:215], v[114:117]
	v_mfma_f32_16x16x32_bf16 v[118:121], v[154:157], v[212:215], v[118:121]
	v_mfma_f32_16x16x32_bf16 v[118:121], v[150:153], v[208:211], v[118:121]
	v_mfma_f32_16x16x32_bf16 v[102:105], v[150:153], v[216:219], v[102:105]
	v_mfma_f32_16x16x32_bf16 v[102:105], v[154:157], v[220:223], v[102:105]
	v_mfma_f32_16x16x32_bf16 v[98:101], v[168:171], v[220:223], v[98:101]
	v_mfma_f32_16x16x32_bf16 v[98:101], v[158:161], v[216:219], v[98:101]
	v_mfma_f32_16x16x32_bf16 v[82:85], v[158:161], v[224:227], v[82:85]
	v_mfma_f32_16x16x32_bf16 v[82:85], v[168:171], v[228:231], v[82:85]
	v_mfma_f32_16x16x32_bf16 v[86:89], v[154:157], v[228:231], v[86:89]
	v_mfma_f32_16x16x32_bf16 v[86:89], v[150:153], v[224:227], v[86:89]
	v_mfma_f32_16x16x32_bf16 v[70:73], v[176:179], v[224:227], v[70:73]
	v_mfma_f32_16x16x32_bf16 v[70:73], v[180:183], v[228:231], v[70:73]
	v_mfma_f32_16x16x32_bf16 v[66:69], v[188:191], v[228:231], v[66:69]
	v_mfma_f32_16x16x32_bf16 v[66:69], v[184:187], v[224:227], v[66:69]
	v_mfma_f32_16x16x32_bf16 v[74:77], v[184:187], v[216:219], v[74:77]
	v_mfma_f32_16x16x32_bf16 v[74:77], v[188:191], v[220:223], v[74:77]
	v_mfma_f32_16x16x32_bf16 v[78:81], v[180:183], v[220:223], v[78:81]
	v_mfma_f32_16x16x32_bf16 v[78:81], v[176:179], v[216:219], v[78:81]
	v_mfma_f32_16x16x32_bf16 v[94:97], v[176:179], v[208:211], v[94:97]
	v_mfma_f32_16x16x32_bf16 v[94:97], v[180:183], v[212:215], v[94:97]
	v_mfma_f32_16x16x32_bf16 v[90:93], v[188:191], v[212:215], v[90:93]
	v_mfma_f32_16x16x32_bf16 v[90:93], v[184:187], v[208:211], v[90:93]
	v_mfma_f32_16x16x32_bf16 v[106:109], v[184:187], v[192:195], v[106:109]
	v_mfma_f32_16x16x32_bf16 v[106:109], v[188:191], v[204:207], v[106:109]
	v_mfma_f32_16x16x32_bf16 v[110:113], v[180:183], v[204:207], v[110:113]
	v_mfma_f32_16x16x32_bf16 v[110:113], v[176:179], v[192:195], v[110:113]
	s_setprio 0
	s_barrier
	s_mov_b32 m0, s38
	v_lshl_add_u64 v[172:173], v[172:173], 0, s[10:11]
	s_add_u32 s14, s14, 0x2b0080
	ds_read_b128 v[192:195], v145 offset:49152
	ds_read_b128 v[204:207], v145 offset:50176
	ds_read_b128 v[208:211], v145 offset:51200
	ds_read_b128 v[212:215], v145 offset:52224
	ds_read_b128 v[216:219], v145 offset:53248
	ds_read_b128 v[220:223], v145 offset:54272
	ds_read_b128 v[224:227], v145 offset:55296
	ds_read_b128 v[228:231], v145 offset:56320
	global_load_lds_dwordx4 v[172:173], off
	v_lshl_add_u64 v[172:173], v[196:197], 0, s[10:11]
	s_mov_b32 m0, s39
	s_addc_u32 s15, s15, 0
	global_load_lds_dwordx4 v[172:173], off
	v_lshl_add_u64 v[172:173], s[14:15], 0, v[132:133]
	s_mov_b32 m0, s40
	s_nop 0
	global_load_lds_dwordx4 v[172:173], off
	v_lshl_add_u64 v[172:173], s[14:15], 0, v[136:137]
	s_mov_b32 m0, s41
	s_nop 0
	global_load_lds_dwordx4 v[172:173], off
	v_lshl_add_u64 v[172:173], v[232:233], 0, s[10:11]
	s_mov_b32 m0, s26
	s_nop 0
	global_load_lds_dwordx4 v[172:173], off
	v_lshl_add_u64 v[172:173], v[234:235], 0, s[10:11]
	s_mov_b32 m0, s27
	s_nop 0
	global_load_lds_dwordx4 v[172:173], off
	s_waitcnt vmcnt(8)
	s_waitcnt lgkmcnt(0)
	s_barrier
	s_setprio 1
	s_waitcnt lgkmcnt(0)
	v_mfma_f32_16x16x32_bf16 v[62:65], v[150:153], v[192:195], v[62:65]
	v_mfma_f32_16x16x32_bf16 v[62:65], v[154:157], v[204:207], v[62:65]
	v_mfma_f32_16x16x32_bf16 v[58:61], v[168:171], v[204:207], v[58:61]
	v_mfma_f32_16x16x32_bf16 v[58:61], v[158:161], v[192:195], v[58:61]
	v_mfma_f32_16x16x32_bf16 v[50:53], v[158:161], v[208:211], v[50:53]
	v_mfma_f32_16x16x32_bf16 v[50:53], v[168:171], v[212:215], v[50:53]
	v_mfma_f32_16x16x32_bf16 v[54:57], v[154:157], v[212:215], v[54:57]
	v_mfma_f32_16x16x32_bf16 v[54:57], v[150:153], v[208:211], v[54:57]
	v_mfma_f32_16x16x32_bf16 v[38:41], v[150:153], v[216:219], v[38:41]
	v_mfma_f32_16x16x32_bf16 v[38:41], v[154:157], v[220:223], v[38:41]
	v_mfma_f32_16x16x32_bf16 v[34:37], v[168:171], v[220:223], v[34:37]
	v_mfma_f32_16x16x32_bf16 v[34:37], v[158:161], v[216:219], v[34:37]
	v_mfma_f32_16x16x32_bf16 v[18:21], v[158:161], v[224:227], v[18:21]
	v_mfma_f32_16x16x32_bf16 v[18:21], v[168:171], v[228:231], v[18:21]
	v_mfma_f32_16x16x32_bf16 v[22:25], v[154:157], v[228:231], v[22:25]
	v_mfma_f32_16x16x32_bf16 v[22:25], v[150:153], v[224:227], v[22:25]
	v_mfma_f32_16x16x32_bf16 v[6:9], v[176:179], v[224:227], v[6:9]
	v_mfma_f32_16x16x32_bf16 v[6:9], v[180:183], v[228:231], v[6:9]
	v_mfma_f32_16x16x32_bf16 v[2:5], v[188:191], v[228:231], v[2:5]
	v_mfma_f32_16x16x32_bf16 v[2:5], v[184:187], v[224:227], v[2:5]
	v_mfma_f32_16x16x32_bf16 v[10:13], v[184:187], v[216:219], v[10:13]
	v_mfma_f32_16x16x32_bf16 v[10:13], v[188:191], v[220:223], v[10:13]
	v_mfma_f32_16x16x32_bf16 v[14:17], v[180:183], v[220:223], v[14:17]
	v_mfma_f32_16x16x32_bf16 v[14:17], v[176:179], v[216:219], v[14:17]
	v_mfma_f32_16x16x32_bf16 v[30:33], v[176:179], v[208:211], v[30:33]
	v_mfma_f32_16x16x32_bf16 v[30:33], v[180:183], v[212:215], v[30:33]
	v_mfma_f32_16x16x32_bf16 v[26:29], v[188:191], v[212:215], v[26:29]
	v_mfma_f32_16x16x32_bf16 v[26:29], v[184:187], v[208:211], v[26:29]
	v_mfma_f32_16x16x32_bf16 v[42:45], v[184:187], v[192:195], v[42:45]
	v_mfma_f32_16x16x32_bf16 v[42:45], v[188:191], v[204:207], v[42:45]
	v_mfma_f32_16x16x32_bf16 v[46:49], v[180:183], v[204:207], v[46:49]
	v_mfma_f32_16x16x32_bf16 v[46:49], v[176:179], v[192:195], v[46:49]
	s_setprio 0
	s_barrier
	s_add_u32 s12, s12, 0x100
	s_addc_u32 s13, s13, 0
	s_cmp_ge_u32 s42, s19
	s_mov_b32 s15, s42
	s_cbranch_scc0 .LBB0_1432
	s_lshl_b32 s4, s18, 21
	v_readlane_b32 s0, v249, 29
	v_lshl_or_b32 v130, s20, 8, v148
	v_mov_b32_e32 v139, 0
	s_add_u32 s4, s0, s4
	v_readlane_b32 s0, v249, 31
	v_or_b32_e32 v130, s25, v130
	v_cvt_pk_bf16_f32 v70, v70, v71
	v_cvt_pk_bf16_f32 v71, v72, v73
	v_cvt_pk_bf16_f32 v72, v66, v67
	v_add_u32_e32 v66, 0x80, v138
	v_mov_b32_e32 v67, v139
	s_addc_u32 s5, s0, 0
	v_ashrrev_i32_e32 v131, 31, v130
	v_lshlrev_b64 v[132:133], 13, v[138:139]
	v_cvt_pk_bf16_f32 v110, v110, v111
	v_cvt_pk_bf16_f32 v111, v112, v113
	v_cvt_pk_bf16_f32 v112, v106, v107
	v_or_b32_e32 v106, 16, v138
	v_mov_b32_e32 v107, v139
	v_lshlrev_b64 v[66:67], 13, v[66:67]
	v_cvt_pk_bf16_f32 v46, v46, v47
	v_cvt_pk_bf16_f32 v47, v48, v49
	v_cvt_pk_bf16_f32 v48, v42, v43
	v_add_u32_e32 v42, 0x90, v138
	v_mov_b32_e32 v43, v139
	v_lshl_add_u64 v[132:133], s[4:5], 0, v[132:133]
	v_lshlrev_b64 v[130:131], 1, v[130:131]
	v_lshlrev_b64 v[106:107], 13, v[106:107]
	v_cvt_pk_bf16_f32 v94, v94, v95
	v_cvt_pk_bf16_f32 v95, v96, v97
	v_cvt_pk_bf16_f32 v96, v90, v91
	v_or_b32_e32 v90, 32, v138
	v_mov_b32_e32 v91, v139
	v_lshl_add_u64 v[66:67], s[4:5], 0, v[66:67]
	v_lshlrev_b64 v[42:43], 13, v[42:43]
	v_cvt_pk_bf16_f32 v30, v30, v31
	v_cvt_pk_bf16_f32 v31, v32, v33
	v_cvt_pk_bf16_f32 v32, v26, v27
	v_add_u32_e32 v26, 0xa0, v138
	v_mov_b32_e32 v27, v139
	v_lshl_add_u64 v[132:133], v[132:133], 0, v[130:131]
	v_cvt_pk_bf16_f32 v113, v108, v109
	v_lshl_add_u64 v[106:107], s[4:5], 0, v[106:107]
	v_lshlrev_b64 v[90:91], 13, v[90:91]
	v_cvt_pk_bf16_f32 v78, v78, v79
	v_cvt_pk_bf16_f32 v79, v80, v81
	v_cvt_pk_bf16_f32 v80, v74, v75
	v_or_b32_e32 v74, 48, v138
	v_mov_b32_e32 v75, v139
	v_lshl_add_u64 v[66:67], v[66:67], 0, v[130:131]
	v_cvt_pk_bf16_f32 v49, v44, v45
	v_lshl_add_u64 v[42:43], s[4:5], 0, v[42:43]
	v_lshlrev_b64 v[26:27], 13, v[26:27]
	v_add_u32_e32 v138, 0xb0, v138
	global_store_dwordx4 v[132:133], v[110:113], off offset:256
	v_cvt_pk_bf16_f32 v97, v92, v93
	v_lshl_add_u64 v[90:91], s[4:5], 0, v[90:91]
	v_lshl_add_u64 v[110:111], v[106:107], 0, v[130:131]
	v_lshlrev_b64 v[74:75], 13, v[74:75]
	global_store_dwordx4 v[66:67], v[46:49], off offset:256
	v_cvt_pk_bf16_f32 v33, v28, v29
	v_lshl_add_u64 v[26:27], s[4:5], 0, v[26:27]
	v_lshl_add_u64 v[46:47], v[42:43], 0, v[130:131]
	v_cvt_pk_bf16_f32 v14, v14, v15
	v_cvt_pk_bf16_f32 v15, v16, v17
	v_cvt_pk_bf16_f32 v16, v10, v11
	v_lshlrev_b64 v[10:11], 13, v[138:139]
	global_store_dwordx4 v[110:111], v[94:97], off offset:256
	v_cvt_pk_bf16_f32 v81, v76, v77
	v_lshl_add_u64 v[74:75], s[4:5], 0, v[74:75]
	v_lshl_add_u64 v[94:95], v[90:91], 0, v[130:131]
	global_store_dwordx4 v[46:47], v[30:33], off offset:256
	v_cvt_pk_bf16_f32 v17, v12, v13
	v_lshl_add_u64 v[10:11], s[4:5], 0, v[10:11]
	v_lshl_add_u64 v[30:31], v[26:27], 0, v[130:131]
	v_cvt_pk_bf16_f32 v126, v126, v127
	v_cvt_pk_bf16_f32 v127, v128, v129
	v_cvt_pk_bf16_f32 v128, v122, v123
	v_cvt_pk_bf16_f32 v129, v124, v125
	v_cvt_pk_bf16_f32 v106, v118, v119
	v_cvt_pk_bf16_f32 v107, v120, v121
	v_cvt_pk_bf16_f32 v108, v114, v115
	v_cvt_pk_bf16_f32 v109, v116, v117
	v_cvt_pk_bf16_f32 v90, v102, v103
	v_cvt_pk_bf16_f32 v91, v104, v105
	v_cvt_pk_bf16_f32 v92, v98, v99
	v_cvt_pk_bf16_f32 v93, v100, v101
	global_store_dwordx4 v[94:95], v[78:81], off offset:256
	v_cvt_pk_bf16_f32 v76, v82, v83
	v_cvt_pk_bf16_f32 v77, v84, v85
	v_lshl_add_u64 v[78:79], v[74:75], 0, v[130:131]
	v_cvt_pk_bf16_f32 v74, v86, v87
	v_cvt_pk_bf16_f32 v75, v88, v89
	v_cvt_pk_bf16_f32 v73, v68, v69
	v_cvt_pk_bf16_f32 v62, v62, v63
	v_cvt_pk_bf16_f32 v63, v64, v65
	v_cvt_pk_bf16_f32 v64, v58, v59
	v_cvt_pk_bf16_f32 v65, v60, v61
	v_cvt_pk_bf16_f32 v42, v54, v55
	v_cvt_pk_bf16_f32 v43, v56, v57
	v_cvt_pk_bf16_f32 v44, v50, v51
	v_cvt_pk_bf16_f32 v45, v52, v53
	v_cvt_pk_bf16_f32 v26, v38, v39
	v_cvt_pk_bf16_f32 v27, v40, v41
	v_cvt_pk_bf16_f32 v28, v34, v35
	v_cvt_pk_bf16_f32 v29, v36, v37
	global_store_dwordx4 v[30:31], v[14:17], off offset:256
	v_cvt_pk_bf16_f32 v12, v18, v19
	v_cvt_pk_bf16_f32 v13, v20, v21
	v_lshl_add_u64 v[14:15], v[10:11], 0, v[130:131]
	v_cvt_pk_bf16_f32 v10, v22, v23
	v_cvt_pk_bf16_f32 v11, v24, v25
	v_cvt_pk_bf16_f32 v6, v6, v7
	v_cvt_pk_bf16_f32 v7, v8, v9
	v_cvt_pk_bf16_f32 v8, v2, v3
	v_cvt_pk_bf16_f32 v9, v4, v5
	global_store_dwordx4 v[132:133], v[126:129], off
	global_store_dwordx4 v[110:111], v[106:109], off
	global_store_dwordx4 v[94:95], v[90:93], off
	global_store_dwordx4 v[78:79], v[74:77], off
	global_store_dwordx4 v[78:79], v[70:73], off offset:256
	global_store_dwordx4 v[66:67], v[62:65], off
	global_store_dwordx4 v[46:47], v[42:45], off
	global_store_dwordx4 v[30:31], v[26:29], off
	global_store_dwordx4 v[14:15], v[10:13], off
	global_store_dwordx4 v[14:15], v[6:9], off offset:256
	s_waitcnt vmcnt(0)
	s_cmpk_lt_u32 s3, 0x100
	s_cbranch_scc0 .LBB0_1435
	s_barrier

.LBB0_1565:
	ds_read_b128 v[130:133], v204
	ds_read_b128 v[134:137], v204 offset:1024
	ds_read_b128 v[138:141], v204 offset:2048
	ds_read_b128 v[142:145], v204 offset:3072
	ds_read_b128 v[146:149], v205
	ds_read_b128 v[150:153], v205 offset:1024
	ds_read_b128 v[154:157], v205 offset:2048
	ds_read_b128 v[158:161], v205 offset:3072
	s_add_u32 s8, s6, 0xfff00080
	s_addc_u32 s9, s7, -1
	s_cmp_eq_u32 s66, 60
	s_cselect_b32 s73, s41, s9
	s_cselect_b32 s72, s50, s8
	s_cselect_b32 s9, s13, s57
	s_cselect_b32 s8, s51, s56
	v_lshl_add_u64 v[196:197], s[6:7], 0, v[180:181]
	s_add_i32 m0, s42, 0xc000
	ds_read_b128 v[184:187], v206
	ds_read_b128 v[188:191], v206 offset:1024
	ds_read_b128 v[192:195], v206 offset:2048
	ds_read_b128 v[210:213], v206 offset:3072
	ds_read_b128 v[214:217], v206 offset:4096
	ds_read_b128 v[218:221], v206 offset:5120
	ds_read_b128 v[222:225], v206 offset:6144
	ds_read_b128 v[226:229], v206 offset:7168
	global_load_lds_dwordx4 v[196:197], off
	v_lshl_add_u64 v[196:197], s[6:7], 0, v[182:183]
	s_add_i32 m0, s42, 0xe000
	s_nop 0
	global_load_lds_dwordx4 v[196:197], off
	s_waitcnt vmcnt(8)
	s_waitcnt lgkmcnt(0)
	s_barrier
	s_setprio 1
	s_waitcnt lgkmcnt(0)
	v_mfma_f32_16x16x32_bf16 v[126:129], v[130:133], v[184:187], v[126:129]
	v_mfma_f32_16x16x32_bf16 v[126:129], v[134:137], v[188:191], v[126:129]
	v_mfma_f32_16x16x32_bf16 v[122:125], v[142:145], v[188:191], v[122:125]
	v_mfma_f32_16x16x32_bf16 v[122:125], v[138:141], v[184:187], v[122:125]
	v_mfma_f32_16x16x32_bf16 v[106:109], v[138:141], v[192:195], v[106:109]
	v_mfma_f32_16x16x32_bf16 v[106:109], v[142:145], v[210:213], v[106:109]
	v_mfma_f32_16x16x32_bf16 v[110:113], v[134:137], v[210:213], v[110:113]
	v_mfma_f32_16x16x32_bf16 v[110:113], v[130:133], v[192:195], v[110:113]
	v_mfma_f32_16x16x32_bf16 v[94:97], v[130:133], v[214:217], v[94:97]
	v_mfma_f32_16x16x32_bf16 v[94:97], v[134:137], v[218:221], v[94:97]
	v_mfma_f32_16x16x32_bf16 v[90:93], v[142:145], v[218:221], v[90:93]
	v_mfma_f32_16x16x32_bf16 v[90:93], v[138:141], v[214:217], v[90:93]
	v_mfma_f32_16x16x32_bf16 v[74:77], v[138:141], v[222:225], v[74:77]
	v_mfma_f32_16x16x32_bf16 v[74:77], v[142:145], v[226:229], v[74:77]
	v_mfma_f32_16x16x32_bf16 v[78:81], v[134:137], v[226:229], v[78:81]
	v_mfma_f32_16x16x32_bf16 v[78:81], v[130:133], v[222:225], v[78:81]
	v_mfma_f32_16x16x32_bf16 v[70:73], v[146:149], v[222:225], v[70:73]
	v_mfma_f32_16x16x32_bf16 v[70:73], v[150:153], v[226:229], v[70:73]
	v_mfma_f32_16x16x32_bf16 v[66:69], v[158:161], v[226:229], v[66:69]
	v_mfma_f32_16x16x32_bf16 v[66:69], v[154:157], v[222:225], v[66:69]
	v_mfma_f32_16x16x32_bf16 v[82:85], v[154:157], v[214:217], v[82:85]
	v_mfma_f32_16x16x32_bf16 v[82:85], v[158:161], v[218:221], v[82:85]
	v_mfma_f32_16x16x32_bf16 v[86:89], v[150:153], v[218:221], v[86:89]
	v_mfma_f32_16x16x32_bf16 v[86:89], v[146:149], v[214:217], v[86:89]
	v_mfma_f32_16x16x32_bf16 v[102:105], v[146:149], v[192:195], v[102:105]
	v_mfma_f32_16x16x32_bf16 v[102:105], v[150:153], v[210:213], v[102:105]
	v_mfma_f32_16x16x32_bf16 v[98:101], v[158:161], v[210:213], v[98:101]
	v_mfma_f32_16x16x32_bf16 v[98:101], v[154:157], v[192:195], v[98:101]
	v_mfma_f32_16x16x32_bf16 v[114:117], v[154:157], v[184:187], v[114:117]
	v_mfma_f32_16x16x32_bf16 v[114:117], v[158:161], v[188:191], v[114:117]
	v_mfma_f32_16x16x32_bf16 v[118:121], v[150:153], v[188:191], v[118:121]
	v_mfma_f32_16x16x32_bf16 v[118:121], v[146:149], v[184:187], v[118:121]
	s_setprio 0
	s_barrier
	s_add_i32 s67, s54, s35
	v_lshl_add_u64 v[196:197], s[8:9], 0, v[168:169]
	s_mov_b32 m0, s67
	ds_read_b128 v[184:187], v206 offset:16384
	ds_read_b128 v[188:191], v206 offset:17408
	ds_read_b128 v[192:195], v206 offset:18432
	ds_read_b128 v[210:213], v206 offset:19456
	ds_read_b128 v[214:217], v206 offset:20480
	ds_read_b128 v[218:221], v206 offset:21504
	ds_read_b128 v[222:225], v206 offset:22528
	ds_read_b128 v[226:229], v206 offset:23552
	global_load_lds_dwordx4 v[196:197], off
	s_add_i32 m0, s67, 0x2000
	s_add_u32 s68, s8, 0x100000
	v_lshl_add_u64 v[230:231], s[8:9], 0, v[170:171]
	s_addc_u32 s69, s9, 0
	s_add_i32 s67, s55, s35
	global_load_lds_dwordx4 v[230:231], off
	v_lshl_add_u64 v[232:233], s[68:69], 0, v[168:169]
	s_mov_b32 m0, s67
	v_lshl_add_u64 v[234:235], s[72:73], 0, v[170:171]
	global_load_lds_dwordx4 v[232:233], off
	v_lshl_add_u64 v[232:233], s[68:69], 0, v[170:171]
	s_add_i32 m0, s67, 0x2000
	s_nop 0
	global_load_lds_dwordx4 v[232:233], off
	v_lshl_add_u64 v[232:233], s[72:73], 0, v[168:169]
	s_mov_b32 m0, s42
	s_nop 0
	global_load_lds_dwordx4 v[232:233], off
	s_mov_b32 m0, s43
	s_nop 0
	global_load_lds_dwordx4 v[234:235], off
	s_waitcnt vmcnt(8)
	s_waitcnt lgkmcnt(0)
	s_barrier
	s_setprio 1
	s_waitcnt lgkmcnt(0)
	v_mfma_f32_16x16x32_bf16 v[62:65], v[130:133], v[184:187], v[62:65]
	v_mfma_f32_16x16x32_bf16 v[62:65], v[134:137], v[188:191], v[62:65]
	v_mfma_f32_16x16x32_bf16 v[58:61], v[142:145], v[188:191], v[58:61]
	v_mfma_f32_16x16x32_bf16 v[58:61], v[138:141], v[184:187], v[58:61]
	v_mfma_f32_16x16x32_bf16 v[42:45], v[138:141], v[192:195], v[42:45]
	v_mfma_f32_16x16x32_bf16 v[42:45], v[142:145], v[210:213], v[42:45]
	v_mfma_f32_16x16x32_bf16 v[46:49], v[134:137], v[210:213], v[46:49]
	v_mfma_f32_16x16x32_bf16 v[46:49], v[130:133], v[192:195], v[46:49]
	v_mfma_f32_16x16x32_bf16 v[30:33], v[130:133], v[214:217], v[30:33]
	v_mfma_f32_16x16x32_bf16 v[30:33], v[134:137], v[218:221], v[30:33]
	v_mfma_f32_16x16x32_bf16 v[26:29], v[142:145], v[218:221], v[26:29]
	v_mfma_f32_16x16x32_bf16 v[26:29], v[138:141], v[214:217], v[26:29]
	v_mfma_f32_16x16x32_bf16 v[10:13], v[138:141], v[222:225], v[10:13]
	v_mfma_f32_16x16x32_bf16 v[10:13], v[142:145], v[226:229], v[10:13]
	v_mfma_f32_16x16x32_bf16 v[14:17], v[134:137], v[226:229], v[14:17]
	v_mfma_f32_16x16x32_bf16 v[14:17], v[130:133], v[222:225], v[14:17]
	v_mfma_f32_16x16x32_bf16 v[6:9], v[146:149], v[222:225], v[6:9]
	v_mfma_f32_16x16x32_bf16 v[6:9], v[150:153], v[226:229], v[6:9]
	v_mfma_f32_16x16x32_bf16 v[2:5], v[158:161], v[226:229], v[2:5]
	v_mfma_f32_16x16x32_bf16 v[2:5], v[154:157], v[222:225], v[2:5]
	v_mfma_f32_16x16x32_bf16 v[18:21], v[154:157], v[214:217], v[18:21]
	v_mfma_f32_16x16x32_bf16 v[18:21], v[158:161], v[218:221], v[18:21]
	v_mfma_f32_16x16x32_bf16 v[22:25], v[150:153], v[218:221], v[22:25]
	v_mfma_f32_16x16x32_bf16 v[22:25], v[146:149], v[214:217], v[22:25]
	v_mfma_f32_16x16x32_bf16 v[38:41], v[146:149], v[192:195], v[38:41]
	v_mfma_f32_16x16x32_bf16 v[38:41], v[150:153], v[210:213], v[38:41]
	v_mfma_f32_16x16x32_bf16 v[34:37], v[158:161], v[210:213], v[34:37]
	v_mfma_f32_16x16x32_bf16 v[34:37], v[154:157], v[192:195], v[34:37]
	v_mfma_f32_16x16x32_bf16 v[50:53], v[154:157], v[184:187], v[50:53]
	v_mfma_f32_16x16x32_bf16 v[50:53], v[158:161], v[188:191], v[50:53]
	v_mfma_f32_16x16x32_bf16 v[54:57], v[150:153], v[188:191], v[54:57]
	v_mfma_f32_16x16x32_bf16 v[54:57], v[146:149], v[184:187], v[54:57]
	s_setprio 0
	s_barrier
	s_add_i32 s67, 0, 0x18000
	s_add_i32 s70, 0, 0x1c000
	v_add_u32_e32 v142, s67, v203
	v_add_u32_e32 v158, s70, v203
	ds_read_b128 v[130:133], v142
	ds_read_b128 v[134:137], v142 offset:1024
	ds_read_b128 v[138:141], v142 offset:2048
	ds_read_b128 v[142:145], v142 offset:3072
	ds_read_b128 v[146:149], v158
	ds_read_b128 v[150:153], v158 offset:1024
	ds_read_b128 v[154:157], v158 offset:2048
	ds_read_b128 v[158:161], v158 offset:3072
	s_add_u32 s68, s72, 0x100000
	s_addc_u32 s69, s73, 0
	s_mov_b32 m0, s44
	v_lshl_add_u64 v[236:237], s[68:69], 0, v[168:169]
	ds_read_b128 v[184:187], v206 offset:32768
	ds_read_b128 v[188:191], v206 offset:33792
	ds_read_b128 v[192:195], v206 offset:34816
	ds_read_b128 v[210:213], v206 offset:35840
	ds_read_b128 v[214:217], v206 offset:36864
	ds_read_b128 v[218:221], v206 offset:37888
	ds_read_b128 v[222:225], v206 offset:38912
	ds_read_b128 v[226:229], v206 offset:39936
	global_load_lds_dwordx4 v[236:237], off
	v_lshl_add_u64 v[236:237], s[68:69], 0, v[170:171]
	s_mov_b32 m0, s45
	s_nop 0
	global_load_lds_dwordx4 v[236:237], off
	s_waitcnt vmcnt(8)
	s_waitcnt lgkmcnt(0)
	s_barrier
	s_setprio 1
	s_waitcnt lgkmcnt(0)
	v_mfma_f32_16x16x32_bf16 v[126:129], v[130:133], v[184:187], v[126:129]
	v_mfma_f32_16x16x32_bf16 v[126:129], v[134:137], v[188:191], v[126:129]
	v_mfma_f32_16x16x32_bf16 v[122:125], v[142:145], v[188:191], v[122:125]
	v_mfma_f32_16x16x32_bf16 v[122:125], v[138:141], v[184:187], v[122:125]
	v_mfma_f32_16x16x32_bf16 v[106:109], v[138:141], v[192:195], v[106:109]
	v_mfma_f32_16x16x32_bf16 v[106:109], v[142:145], v[210:213], v[106:109]
	v_mfma_f32_16x16x32_bf16 v[110:113], v[134:137], v[210:213], v[110:113]
	v_mfma_f32_16x16x32_bf16 v[110:113], v[130:133], v[192:195], v[110:113]
	v_mfma_f32_16x16x32_bf16 v[94:97], v[130:133], v[214:217], v[94:97]
	v_mfma_f32_16x16x32_bf16 v[94:97], v[134:137], v[218:221], v[94:97]
	v_mfma_f32_16x16x32_bf16 v[90:93], v[142:145], v[218:221], v[90:93]
	v_mfma_f32_16x16x32_bf16 v[90:93], v[138:141], v[214:217], v[90:93]
	v_mfma_f32_16x16x32_bf16 v[74:77], v[138:141], v[222:225], v[74:77]
	v_mfma_f32_16x16x32_bf16 v[74:77], v[142:145], v[226:229], v[74:77]
	v_mfma_f32_16x16x32_bf16 v[78:81], v[134:137], v[226:229], v[78:81]
	v_mfma_f32_16x16x32_bf16 v[78:81], v[130:133], v[222:225], v[78:81]
	v_mfma_f32_16x16x32_bf16 v[70:73], v[146:149], v[222:225], v[70:73]
	v_mfma_f32_16x16x32_bf16 v[70:73], v[150:153], v[226:229], v[70:73]
	v_mfma_f32_16x16x32_bf16 v[66:69], v[158:161], v[226:229], v[66:69]
	v_mfma_f32_16x16x32_bf16 v[66:69], v[154:157], v[222:225], v[66:69]
	v_mfma_f32_16x16x32_bf16 v[82:85], v[154:157], v[214:217], v[82:85]
	v_mfma_f32_16x16x32_bf16 v[82:85], v[158:161], v[218:221], v[82:85]
	v_mfma_f32_16x16x32_bf16 v[86:89], v[150:153], v[218:221], v[86:89]
	v_mfma_f32_16x16x32_bf16 v[86:89], v[146:149], v[214:217], v[86:89]
	v_mfma_f32_16x16x32_bf16 v[102:105], v[146:149], v[192:195], v[102:105]
	v_mfma_f32_16x16x32_bf16 v[102:105], v[150:153], v[210:213], v[102:105]
	v_mfma_f32_16x16x32_bf16 v[98:101], v[158:161], v[210:213], v[98:101]
	v_mfma_f32_16x16x32_bf16 v[98:101], v[154:157], v[192:195], v[98:101]
	v_mfma_f32_16x16x32_bf16 v[114:117], v[154:157], v[184:187], v[114:117]
	v_mfma_f32_16x16x32_bf16 v[114:117], v[158:161], v[188:191], v[114:117]
	v_mfma_f32_16x16x32_bf16 v[118:121], v[150:153], v[188:191], v[118:121]
	v_mfma_f32_16x16x32_bf16 v[118:121], v[146:149], v[184:187], v[118:121]
	s_setprio 0
	s_barrier
	s_add_i32 s67, s67, s35
	v_lshl_add_u64 v[196:197], v[196:197], 0, s[22:23]
	s_mov_b32 m0, s67
	ds_read_b128 v[184:187], v206 offset:49152
	ds_read_b128 v[188:191], v206 offset:50176
	ds_read_b128 v[192:195], v206 offset:51200
	ds_read_b128 v[210:213], v206 offset:52224
	ds_read_b128 v[214:217], v206 offset:53248
	ds_read_b128 v[218:221], v206 offset:54272
	ds_read_b128 v[222:225], v206 offset:55296
	ds_read_b128 v[226:229], v206 offset:56320
	global_load_lds_dwordx4 v[196:197], off
	s_add_i32 m0, s67, 0x2000
	s_add_u32 s8, s8, 0x100080
	v_lshl_add_u64 v[196:197], v[230:231], 0, s[22:23]
	s_addc_u32 s9, s9, 0
	s_add_i32 s67, s70, s35
	global_load_lds_dwordx4 v[196:197], off
	v_lshl_add_u64 v[196:197], s[8:9], 0, v[168:169]
	s_mov_b32 m0, s67
	s_nop 0
	global_load_lds_dwordx4 v[196:197], off
	v_lshl_add_u64 v[196:197], s[8:9], 0, v[170:171]
	s_add_i32 m0, s67, 0x2000
	s_nop 0
	global_load_lds_dwordx4 v[196:197], off
	v_lshl_add_u64 v[196:197], v[232:233], 0, s[22:23]
	s_mov_b32 m0, s48
	s_nop 0
	global_load_lds_dwordx4 v[196:197], off
	v_lshl_add_u64 v[196:197], v[234:235], 0, s[22:23]
	s_mov_b32 m0, s49
	s_nop 0
	global_load_lds_dwordx4 v[196:197], off
	s_waitcnt vmcnt(8)
	s_waitcnt lgkmcnt(0)
	s_barrier
	s_setprio 1
	s_waitcnt lgkmcnt(0)
	v_mfma_f32_16x16x32_bf16 v[62:65], v[130:133], v[184:187], v[62:65]
	v_mfma_f32_16x16x32_bf16 v[62:65], v[134:137], v[188:191], v[62:65]
	v_mfma_f32_16x16x32_bf16 v[58:61], v[142:145], v[188:191], v[58:61]
	v_mfma_f32_16x16x32_bf16 v[58:61], v[138:141], v[184:187], v[58:61]
	v_mfma_f32_16x16x32_bf16 v[42:45], v[138:141], v[192:195], v[42:45]
	v_mfma_f32_16x16x32_bf16 v[42:45], v[142:145], v[210:213], v[42:45]
	v_mfma_f32_16x16x32_bf16 v[46:49], v[134:137], v[210:213], v[46:49]
	v_mfma_f32_16x16x32_bf16 v[46:49], v[130:133], v[192:195], v[46:49]
	v_mfma_f32_16x16x32_bf16 v[30:33], v[130:133], v[214:217], v[30:33]
	v_mfma_f32_16x16x32_bf16 v[30:33], v[134:137], v[218:221], v[30:33]
	v_mfma_f32_16x16x32_bf16 v[26:29], v[142:145], v[218:221], v[26:29]
	v_mfma_f32_16x16x32_bf16 v[26:29], v[138:141], v[214:217], v[26:29]
	v_mfma_f32_16x16x32_bf16 v[10:13], v[138:141], v[222:225], v[10:13]
	v_mfma_f32_16x16x32_bf16 v[10:13], v[142:145], v[226:229], v[10:13]
	v_mfma_f32_16x16x32_bf16 v[14:17], v[134:137], v[226:229], v[14:17]
	v_mfma_f32_16x16x32_bf16 v[14:17], v[130:133], v[222:225], v[14:17]
	v_mfma_f32_16x16x32_bf16 v[6:9], v[146:149], v[222:225], v[6:9]
	v_mfma_f32_16x16x32_bf16 v[6:9], v[150:153], v[226:229], v[6:9]
	v_mfma_f32_16x16x32_bf16 v[2:5], v[158:161], v[226:229], v[2:5]
	v_mfma_f32_16x16x32_bf16 v[2:5], v[154:157], v[222:225], v[2:5]
	v_mfma_f32_16x16x32_bf16 v[18:21], v[154:157], v[214:217], v[18:21]
	v_mfma_f32_16x16x32_bf16 v[18:21], v[158:161], v[218:221], v[18:21]
	v_mfma_f32_16x16x32_bf16 v[22:25], v[150:153], v[218:221], v[22:25]
	v_mfma_f32_16x16x32_bf16 v[22:25], v[146:149], v[214:217], v[22:25]
	v_mfma_f32_16x16x32_bf16 v[38:41], v[146:149], v[192:195], v[38:41]
	v_mfma_f32_16x16x32_bf16 v[38:41], v[150:153], v[210:213], v[38:41]
	v_mfma_f32_16x16x32_bf16 v[34:37], v[158:161], v[210:213], v[34:37]
	v_mfma_f32_16x16x32_bf16 v[34:37], v[154:157], v[192:195], v[34:37]
	v_mfma_f32_16x16x32_bf16 v[50:53], v[154:157], v[184:187], v[50:53]
	v_mfma_f32_16x16x32_bf16 v[50:53], v[158:161], v[188:191], v[50:53]
	v_mfma_f32_16x16x32_bf16 v[54:57], v[150:153], v[188:191], v[54:57]
	v_mfma_f32_16x16x32_bf16 v[54:57], v[146:149], v[184:187], v[54:57]
	s_setprio 0
	s_barrier
	s_add_i32 s66, s66, 2
	s_add_u32 s6, s6, 0x100
	s_addc_u32 s7, s7, 0
	s_add_u32 s56, s56, 0x100
	s_addc_u32 s57, s57, 0
	s_cmp_gt_u32 s66, 61
	s_cbranch_scc0 .LBB0_1565
	s_and_b64 vcc, exec, s[24:25]
	s_cbranch_vccz .LBB0_1568
	s_barrier

.LBB0_2230:
	ds_read_b128 v[142:145], v154
	ds_read_b128 v[158:161], v154 offset:1024
	ds_read_b128 v[168:171], v154 offset:2048
	ds_read_b128 v[176:179], v154 offset:3072
	ds_read_b128 v[180:183], v155
	ds_read_b128 v[184:187], v155 offset:1024
	ds_read_b128 v[188:191], v155 offset:2048
	ds_read_b128 v[192:195], v155 offset:3072
	s_add_u32 s24, s22, 0xfff00080
	s_addc_u32 s25, s23, -1
	s_cmp_eq_u32 s48, 60
	s_cselect_b32 s27, s19, s25
	s_cselect_b32 s26, s44, s24
	s_cselect_b32 s25, s7, s47
	s_cselect_b32 s24, s45, s46
	s_mov_b32 m0, s40
	v_lshl_add_u64 v[146:147], s[22:23], 0, v[138:139]
	ds_read_b128 v[204:207], v156
	ds_read_b128 v[208:211], v156 offset:1024
	ds_read_b128 v[212:215], v156 offset:2048
	ds_read_b128 v[216:219], v156 offset:3072
	ds_read_b128 v[220:223], v156 offset:4096
	ds_read_b128 v[224:227], v156 offset:5120
	ds_read_b128 v[228:231], v156 offset:6144
	ds_read_b128 v[232:235], v156 offset:7168
	global_load_lds_dwordx4 v[146:147], off
	v_lshl_add_u64 v[146:147], s[22:23], 0, v[140:141]
	s_mov_b32 m0, s41
	s_nop 0
	global_load_lds_dwordx4 v[146:147], off
	s_waitcnt vmcnt(8)
	s_waitcnt lgkmcnt(0)
	s_barrier
	s_setprio 1
	s_waitcnt lgkmcnt(0)
	v_mfma_f32_16x16x32_bf16 v[126:129], v[142:145], v[204:207], v[126:129]
	v_mfma_f32_16x16x32_bf16 v[126:129], v[158:161], v[208:211], v[126:129]
	v_mfma_f32_16x16x32_bf16 v[122:125], v[176:179], v[208:211], v[122:125]
	v_mfma_f32_16x16x32_bf16 v[122:125], v[168:171], v[204:207], v[122:125]
	v_mfma_f32_16x16x32_bf16 v[106:109], v[168:171], v[212:215], v[106:109]
	v_mfma_f32_16x16x32_bf16 v[106:109], v[176:179], v[216:219], v[106:109]
	v_mfma_f32_16x16x32_bf16 v[110:113], v[158:161], v[216:219], v[110:113]
	v_mfma_f32_16x16x32_bf16 v[110:113], v[142:145], v[212:215], v[110:113]
	v_mfma_f32_16x16x32_bf16 v[94:97], v[142:145], v[220:223], v[94:97]
	v_mfma_f32_16x16x32_bf16 v[94:97], v[158:161], v[224:227], v[94:97]
	v_mfma_f32_16x16x32_bf16 v[90:93], v[176:179], v[224:227], v[90:93]
	v_mfma_f32_16x16x32_bf16 v[90:93], v[168:171], v[220:223], v[90:93]
	v_mfma_f32_16x16x32_bf16 v[74:77], v[168:171], v[228:231], v[74:77]
	v_mfma_f32_16x16x32_bf16 v[74:77], v[176:179], v[232:235], v[74:77]
	v_mfma_f32_16x16x32_bf16 v[78:81], v[158:161], v[232:235], v[78:81]
	v_mfma_f32_16x16x32_bf16 v[78:81], v[142:145], v[228:231], v[78:81]
	v_mfma_f32_16x16x32_bf16 v[70:73], v[180:183], v[228:231], v[70:73]
	v_mfma_f32_16x16x32_bf16 v[70:73], v[184:187], v[232:235], v[70:73]
	v_mfma_f32_16x16x32_bf16 v[66:69], v[192:195], v[232:235], v[66:69]
	v_mfma_f32_16x16x32_bf16 v[66:69], v[188:191], v[228:231], v[66:69]
	v_mfma_f32_16x16x32_bf16 v[82:85], v[188:191], v[220:223], v[82:85]
	v_mfma_f32_16x16x32_bf16 v[82:85], v[192:195], v[224:227], v[82:85]
	v_mfma_f32_16x16x32_bf16 v[86:89], v[184:187], v[224:227], v[86:89]
	v_mfma_f32_16x16x32_bf16 v[86:89], v[180:183], v[220:223], v[86:89]
	v_mfma_f32_16x16x32_bf16 v[102:105], v[180:183], v[212:215], v[102:105]
	v_mfma_f32_16x16x32_bf16 v[102:105], v[184:187], v[216:219], v[102:105]
	v_mfma_f32_16x16x32_bf16 v[98:101], v[192:195], v[216:219], v[98:101]
	v_mfma_f32_16x16x32_bf16 v[98:101], v[188:191], v[212:215], v[98:101]
	v_mfma_f32_16x16x32_bf16 v[114:117], v[188:191], v[204:207], v[114:117]
	v_mfma_f32_16x16x32_bf16 v[114:117], v[192:195], v[208:211], v[114:117]
	v_mfma_f32_16x16x32_bf16 v[118:121], v[184:187], v[208:211], v[118:121]
	v_mfma_f32_16x16x32_bf16 v[118:121], v[180:183], v[204:207], v[118:121]
	s_setprio 0
	s_barrier
	s_add_i32 s49, s38, s28
	v_lshl_add_u64 v[146:147], s[24:25], 0, v[132:133]
	s_mov_b32 m0, s49
	ds_read_b128 v[204:207], v156 offset:16384
	ds_read_b128 v[208:211], v156 offset:17408
	ds_read_b128 v[212:215], v156 offset:18432
	ds_read_b128 v[216:219], v156 offset:19456
	ds_read_b128 v[220:223], v156 offset:20480
	ds_read_b128 v[224:227], v156 offset:21504
	ds_read_b128 v[228:231], v156 offset:22528
	ds_read_b128 v[232:235], v156 offset:23552
	global_load_lds_dwordx4 v[146:147], off
	s_add_i32 m0, s49, 0x2000
	s_add_u32 s50, s24, 0x100000
	v_lshl_add_u64 v[172:173], s[24:25], 0, v[136:137]
	s_addc_u32 s51, s25, 0
	s_add_i32 s49, s39, s28
	global_load_lds_dwordx4 v[172:173], off
	v_lshl_add_u64 v[196:197], s[50:51], 0, v[132:133]
	s_mov_b32 m0, s49
	v_lshl_add_u64 v[236:237], s[26:27], 0, v[134:135]
	global_load_lds_dwordx4 v[196:197], off
	v_lshl_add_u64 v[196:197], s[50:51], 0, v[136:137]
	s_add_i32 m0, s49, 0x2000
	s_nop 0
	global_load_lds_dwordx4 v[196:197], off
	v_lshl_add_u64 v[196:197], s[26:27], 0, v[130:131]
	s_mov_b32 m0, s30
	s_nop 0
	global_load_lds_dwordx4 v[196:197], off
	s_mov_b32 m0, s31
	s_nop 0
	global_load_lds_dwordx4 v[236:237], off
	s_waitcnt vmcnt(8)
	s_waitcnt lgkmcnt(0)
	s_barrier
	s_setprio 1
	s_waitcnt lgkmcnt(0)
	v_mfma_f32_16x16x32_bf16 v[62:65], v[142:145], v[204:207], v[62:65]
	v_mfma_f32_16x16x32_bf16 v[62:65], v[158:161], v[208:211], v[62:65]
	v_mfma_f32_16x16x32_bf16 v[58:61], v[176:179], v[208:211], v[58:61]
	v_mfma_f32_16x16x32_bf16 v[58:61], v[168:171], v[204:207], v[58:61]
	v_mfma_f32_16x16x32_bf16 v[42:45], v[168:171], v[212:215], v[42:45]
	v_mfma_f32_16x16x32_bf16 v[42:45], v[176:179], v[216:219], v[42:45]
	v_mfma_f32_16x16x32_bf16 v[46:49], v[158:161], v[216:219], v[46:49]
	v_mfma_f32_16x16x32_bf16 v[46:49], v[142:145], v[212:215], v[46:49]
	v_mfma_f32_16x16x32_bf16 v[30:33], v[142:145], v[220:223], v[30:33]
	v_mfma_f32_16x16x32_bf16 v[30:33], v[158:161], v[224:227], v[30:33]
	v_mfma_f32_16x16x32_bf16 v[26:29], v[176:179], v[224:227], v[26:29]
	v_mfma_f32_16x16x32_bf16 v[26:29], v[168:171], v[220:223], v[26:29]
	v_mfma_f32_16x16x32_bf16 v[10:13], v[168:171], v[228:231], v[10:13]
	v_mfma_f32_16x16x32_bf16 v[10:13], v[176:179], v[232:235], v[10:13]
	v_mfma_f32_16x16x32_bf16 v[14:17], v[158:161], v[232:235], v[14:17]
	v_mfma_f32_16x16x32_bf16 v[14:17], v[142:145], v[228:231], v[14:17]
	v_mfma_f32_16x16x32_bf16 v[6:9], v[180:183], v[228:231], v[6:9]
	v_mfma_f32_16x16x32_bf16 v[6:9], v[184:187], v[232:235], v[6:9]
	v_mfma_f32_16x16x32_bf16 v[2:5], v[192:195], v[232:235], v[2:5]
	v_mfma_f32_16x16x32_bf16 v[2:5], v[188:191], v[228:231], v[2:5]
	v_mfma_f32_16x16x32_bf16 v[18:21], v[188:191], v[220:223], v[18:21]
	v_mfma_f32_16x16x32_bf16 v[18:21], v[192:195], v[224:227], v[18:21]
	v_mfma_f32_16x16x32_bf16 v[22:25], v[184:187], v[224:227], v[22:25]
	v_mfma_f32_16x16x32_bf16 v[22:25], v[180:183], v[220:223], v[22:25]
	v_mfma_f32_16x16x32_bf16 v[38:41], v[180:183], v[212:215], v[38:41]
	v_mfma_f32_16x16x32_bf16 v[38:41], v[184:187], v[216:219], v[38:41]
	v_mfma_f32_16x16x32_bf16 v[34:37], v[192:195], v[216:219], v[34:37]
	v_mfma_f32_16x16x32_bf16 v[34:37], v[188:191], v[212:215], v[34:37]
	v_mfma_f32_16x16x32_bf16 v[50:53], v[188:191], v[204:207], v[50:53]
	v_mfma_f32_16x16x32_bf16 v[50:53], v[192:195], v[208:211], v[50:53]
	v_mfma_f32_16x16x32_bf16 v[54:57], v[184:187], v[208:211], v[54:57]
	v_mfma_f32_16x16x32_bf16 v[54:57], v[180:183], v[204:207], v[54:57]
	s_setprio 0
	s_barrier
	s_add_i32 s49, 0, 0x18000
	v_add_u32_e32 v157, s49, v152
	s_add_i32 s50, 0, 0x1c000
	ds_read_b128 v[142:145], v157
	ds_read_b128 v[158:161], v157 offset:1024
	ds_read_b128 v[168:171], v157 offset:2048
	ds_read_b128 v[176:179], v157 offset:3072
	v_add_u32_e32 v157, s50, v152
	ds_read_b128 v[180:183], v157
	ds_read_b128 v[184:187], v157 offset:1024
	ds_read_b128 v[188:191], v157 offset:2048
	ds_read_b128 v[192:195], v157 offset:3072
	s_add_u32 s26, s26, 0x100000
	s_addc_u32 s27, s27, 0
	s_mov_b32 m0, s33
	v_lshl_add_u64 v[238:239], s[26:27], 0, v[130:131]
	ds_read_b128 v[204:207], v156 offset:32768
	ds_read_b128 v[208:211], v156 offset:33792
	ds_read_b128 v[212:215], v156 offset:34816
	ds_read_b128 v[216:219], v156 offset:35840
	ds_read_b128 v[220:223], v156 offset:36864
	ds_read_b128 v[224:227], v156 offset:37888
	ds_read_b128 v[228:231], v156 offset:38912
	ds_read_b128 v[232:235], v156 offset:39936
	global_load_lds_dwordx4 v[238:239], off
	v_lshl_add_u64 v[238:239], s[26:27], 0, v[134:135]
	s_mov_b32 m0, s34
	s_nop 0
	global_load_lds_dwordx4 v[238:239], off
	s_waitcnt vmcnt(8)
	s_waitcnt lgkmcnt(0)
	s_barrier
	s_setprio 1
	s_waitcnt lgkmcnt(0)
	v_mfma_f32_16x16x32_bf16 v[126:129], v[142:145], v[204:207], v[126:129]
	v_mfma_f32_16x16x32_bf16 v[126:129], v[158:161], v[208:211], v[126:129]
	v_mfma_f32_16x16x32_bf16 v[122:125], v[176:179], v[208:211], v[122:125]
	v_mfma_f32_16x16x32_bf16 v[122:125], v[168:171], v[204:207], v[122:125]
	v_mfma_f32_16x16x32_bf16 v[106:109], v[168:171], v[212:215], v[106:109]
	v_mfma_f32_16x16x32_bf16 v[106:109], v[176:179], v[216:219], v[106:109]
	v_mfma_f32_16x16x32_bf16 v[110:113], v[158:161], v[216:219], v[110:113]
	v_mfma_f32_16x16x32_bf16 v[110:113], v[142:145], v[212:215], v[110:113]
	v_mfma_f32_16x16x32_bf16 v[94:97], v[142:145], v[220:223], v[94:97]
	v_mfma_f32_16x16x32_bf16 v[94:97], v[158:161], v[224:227], v[94:97]
	v_mfma_f32_16x16x32_bf16 v[90:93], v[176:179], v[224:227], v[90:93]
	v_mfma_f32_16x16x32_bf16 v[90:93], v[168:171], v[220:223], v[90:93]
	v_mfma_f32_16x16x32_bf16 v[74:77], v[168:171], v[228:231], v[74:77]
	v_mfma_f32_16x16x32_bf16 v[74:77], v[176:179], v[232:235], v[74:77]
	v_mfma_f32_16x16x32_bf16 v[78:81], v[158:161], v[232:235], v[78:81]
	v_mfma_f32_16x16x32_bf16 v[78:81], v[142:145], v[228:231], v[78:81]
	v_mfma_f32_16x16x32_bf16 v[70:73], v[180:183], v[228:231], v[70:73]
	v_mfma_f32_16x16x32_bf16 v[70:73], v[184:187], v[232:235], v[70:73]
	v_mfma_f32_16x16x32_bf16 v[66:69], v[192:195], v[232:235], v[66:69]
	v_mfma_f32_16x16x32_bf16 v[66:69], v[188:191], v[228:231], v[66:69]
	v_mfma_f32_16x16x32_bf16 v[82:85], v[188:191], v[220:223], v[82:85]
	v_mfma_f32_16x16x32_bf16 v[82:85], v[192:195], v[224:227], v[82:85]
	v_mfma_f32_16x16x32_bf16 v[86:89], v[184:187], v[224:227], v[86:89]
	v_mfma_f32_16x16x32_bf16 v[86:89], v[180:183], v[220:223], v[86:89]
	v_mfma_f32_16x16x32_bf16 v[102:105], v[180:183], v[212:215], v[102:105]
	v_mfma_f32_16x16x32_bf16 v[102:105], v[184:187], v[216:219], v[102:105]
	v_mfma_f32_16x16x32_bf16 v[98:101], v[192:195], v[216:219], v[98:101]
	v_mfma_f32_16x16x32_bf16 v[98:101], v[188:191], v[212:215], v[98:101]
	v_mfma_f32_16x16x32_bf16 v[114:117], v[188:191], v[204:207], v[114:117]
	v_mfma_f32_16x16x32_bf16 v[114:117], v[192:195], v[208:211], v[114:117]
	v_mfma_f32_16x16x32_bf16 v[118:121], v[184:187], v[208:211], v[118:121]
	v_mfma_f32_16x16x32_bf16 v[118:121], v[180:183], v[204:207], v[118:121]
	s_setprio 0
	s_barrier
	s_add_i32 s26, s49, s28
	v_lshl_add_u64 v[146:147], v[146:147], 0, s[14:15]
	s_mov_b32 m0, s26
	ds_read_b128 v[204:207], v156 offset:49152
	ds_read_b128 v[208:211], v156 offset:50176
	ds_read_b128 v[212:215], v156 offset:51200
	ds_read_b128 v[216:219], v156 offset:52224
	ds_read_b128 v[220:223], v156 offset:53248
	ds_read_b128 v[224:227], v156 offset:54272
	ds_read_b128 v[228:231], v156 offset:55296
	ds_read_b128 v[232:235], v156 offset:56320
	global_load_lds_dwordx4 v[146:147], off
	s_add_i32 m0, s26, 0x2000
	s_add_u32 s24, s24, 0x100080
	v_lshl_add_u64 v[146:147], v[172:173], 0, s[14:15]
	s_addc_u32 s25, s25, 0
	s_add_i32 s26, s50, s28
	global_load_lds_dwordx4 v[146:147], off
	v_lshl_add_u64 v[146:147], s[24:25], 0, v[132:133]
	s_mov_b32 m0, s26
	s_nop 0
	global_load_lds_dwordx4 v[146:147], off
	v_lshl_add_u64 v[146:147], s[24:25], 0, v[136:137]
	s_add_i32 m0, s26, 0x2000
	s_nop 0
	global_load_lds_dwordx4 v[146:147], off
	v_lshl_add_u64 v[146:147], v[196:197], 0, s[14:15]
	s_mov_b32 m0, s36
	s_nop 0
	global_load_lds_dwordx4 v[146:147], off
	v_lshl_add_u64 v[146:147], v[236:237], 0, s[14:15]
	s_mov_b32 m0, s37
	s_nop 0
	global_load_lds_dwordx4 v[146:147], off
	s_waitcnt vmcnt(8)
	s_waitcnt lgkmcnt(0)
	s_barrier
	s_setprio 1
	s_waitcnt lgkmcnt(0)
	v_mfma_f32_16x16x32_bf16 v[62:65], v[142:145], v[204:207], v[62:65]
	v_mfma_f32_16x16x32_bf16 v[62:65], v[158:161], v[208:211], v[62:65]
	v_mfma_f32_16x16x32_bf16 v[58:61], v[176:179], v[208:211], v[58:61]
	v_mfma_f32_16x16x32_bf16 v[58:61], v[168:171], v[204:207], v[58:61]
	v_mfma_f32_16x16x32_bf16 v[42:45], v[168:171], v[212:215], v[42:45]
	v_mfma_f32_16x16x32_bf16 v[42:45], v[176:179], v[216:219], v[42:45]
	v_mfma_f32_16x16x32_bf16 v[46:49], v[158:161], v[216:219], v[46:49]
	v_mfma_f32_16x16x32_bf16 v[46:49], v[142:145], v[212:215], v[46:49]
	v_mfma_f32_16x16x32_bf16 v[30:33], v[142:145], v[220:223], v[30:33]
	v_mfma_f32_16x16x32_bf16 v[30:33], v[158:161], v[224:227], v[30:33]
	v_mfma_f32_16x16x32_bf16 v[26:29], v[176:179], v[224:227], v[26:29]
	v_mfma_f32_16x16x32_bf16 v[26:29], v[168:171], v[220:223], v[26:29]
	v_mfma_f32_16x16x32_bf16 v[10:13], v[168:171], v[228:231], v[10:13]
	v_mfma_f32_16x16x32_bf16 v[10:13], v[176:179], v[232:235], v[10:13]
	v_mfma_f32_16x16x32_bf16 v[14:17], v[158:161], v[232:235], v[14:17]
	v_mfma_f32_16x16x32_bf16 v[14:17], v[142:145], v[228:231], v[14:17]
	v_mfma_f32_16x16x32_bf16 v[6:9], v[180:183], v[228:231], v[6:9]
	v_mfma_f32_16x16x32_bf16 v[6:9], v[184:187], v[232:235], v[6:9]
	v_mfma_f32_16x16x32_bf16 v[2:5], v[192:195], v[232:235], v[2:5]
	v_mfma_f32_16x16x32_bf16 v[2:5], v[188:191], v[228:231], v[2:5]
	v_mfma_f32_16x16x32_bf16 v[18:21], v[188:191], v[220:223], v[18:21]
	v_mfma_f32_16x16x32_bf16 v[18:21], v[192:195], v[224:227], v[18:21]
	v_mfma_f32_16x16x32_bf16 v[22:25], v[184:187], v[224:227], v[22:25]
	v_mfma_f32_16x16x32_bf16 v[22:25], v[180:183], v[220:223], v[22:25]
	v_mfma_f32_16x16x32_bf16 v[38:41], v[180:183], v[212:215], v[38:41]
	v_mfma_f32_16x16x32_bf16 v[38:41], v[184:187], v[216:219], v[38:41]
	v_mfma_f32_16x16x32_bf16 v[34:37], v[192:195], v[216:219], v[34:37]
	v_mfma_f32_16x16x32_bf16 v[34:37], v[188:191], v[212:215], v[34:37]
	v_mfma_f32_16x16x32_bf16 v[50:53], v[188:191], v[204:207], v[50:53]
	v_mfma_f32_16x16x32_bf16 v[50:53], v[192:195], v[208:211], v[50:53]
	v_mfma_f32_16x16x32_bf16 v[54:57], v[184:187], v[208:211], v[54:57]
	v_mfma_f32_16x16x32_bf16 v[54:57], v[180:183], v[204:207], v[54:57]
	s_setprio 0
	s_barrier
	s_add_i32 s48, s48, 2
	s_add_u32 s22, s22, 0x100
	s_addc_u32 s23, s23, 0
	s_add_u32 s46, s46, 0x100
	s_addc_u32 s47, s47, 0
	s_cmp_gt_u32 s48, 61
	s_cbranch_scc0 .LBB0_2230
	s_and_b64 vcc, exec, s[16:17]
	s_cbranch_vccz .LBB0_2233
	s_barrier

.LBB0_2240:
	s_add_i32 s20, s24, 0x100
	s_and_b64 s[18:19], s[18:19], exec
	s_cselect_b32 s19, 0, s20
	s_cselect_b32 s18, 0, 0
	s_add_u32 s20, s8, s19
	ds_read_b128 v[144:147], v139
	ds_read_b128 v[150:153], v139 offset:1024
	ds_read_b128 v[154:157], v139 offset:2048
	ds_read_b128 v[158:161], v139 offset:3072
	ds_read_b128 v[168:171], v140
	ds_read_b128 v[176:179], v140 offset:1024
	ds_read_b128 v[180:183], v140 offset:2048
	ds_read_b128 v[184:187], v140 offset:3072
	s_addc_u32 s21, s9, s18
	s_add_u32 s22, s10, s19
	s_addc_u32 s23, s11, s18
	s_add_u32 s28, s12, s24
	s_addc_u32 s29, s13, 0
	s_add_u32 s24, s22, 0x100000
	s_addc_u32 s25, s23, 0
	s_add_u32 s18, s20, 0x100000
	s_addc_u32 s19, s21, 0
	s_add_u32 s26, s22, 0x100080
	s_addc_u32 s27, s23, 0
	v_lshl_add_u64 v[172:173], s[28:29], 0, v[130:131]
	s_mov_b32 m0, s38
	v_lshl_add_u64 v[172:173], v[172:173], 0, s[14:15]
	ds_read_b128 v[188:191], v141
	ds_read_b128 v[192:195], v141 offset:1024
	ds_read_b128 v[204:207], v141 offset:2048
	ds_read_b128 v[208:211], v141 offset:3072
	ds_read_b128 v[212:215], v141 offset:4096
	ds_read_b128 v[216:219], v141 offset:5120
	ds_read_b128 v[220:223], v141 offset:6144
	ds_read_b128 v[224:227], v141 offset:7168
	global_load_lds_dwordx4 v[172:173], off
	v_lshl_add_u64 v[172:173], s[28:29], 0, v[134:135]
	v_lshl_add_u64 v[172:173], v[172:173], 0, s[14:15]
	s_mov_b32 m0, s39
	s_nop 0
	global_load_lds_dwordx4 v[172:173], off
	s_waitcnt vmcnt(8)
	s_waitcnt lgkmcnt(0)
	s_barrier
	s_setprio 1
	s_waitcnt lgkmcnt(0)
	v_mfma_f32_16x16x32_bf16 v[126:129], v[144:147], v[188:191], v[126:129]
	v_mfma_f32_16x16x32_bf16 v[126:129], v[150:153], v[192:195], v[126:129]
	v_mfma_f32_16x16x32_bf16 v[122:125], v[158:161], v[192:195], v[122:125]
	v_mfma_f32_16x16x32_bf16 v[122:125], v[154:157], v[188:191], v[122:125]
	v_mfma_f32_16x16x32_bf16 v[114:117], v[154:157], v[204:207], v[114:117]
	v_mfma_f32_16x16x32_bf16 v[114:117], v[158:161], v[208:211], v[114:117]
	v_mfma_f32_16x16x32_bf16 v[118:121], v[150:153], v[208:211], v[118:121]
	v_mfma_f32_16x16x32_bf16 v[118:121], v[144:147], v[204:207], v[118:121]
	v_mfma_f32_16x16x32_bf16 v[102:105], v[144:147], v[212:215], v[102:105]
	v_mfma_f32_16x16x32_bf16 v[102:105], v[150:153], v[216:219], v[102:105]
	v_mfma_f32_16x16x32_bf16 v[98:101], v[158:161], v[216:219], v[98:101]
	v_mfma_f32_16x16x32_bf16 v[98:101], v[154:157], v[212:215], v[98:101]
	v_mfma_f32_16x16x32_bf16 v[82:85], v[154:157], v[220:223], v[82:85]
	v_mfma_f32_16x16x32_bf16 v[82:85], v[158:161], v[224:227], v[82:85]
	v_mfma_f32_16x16x32_bf16 v[86:89], v[150:153], v[224:227], v[86:89]
	v_mfma_f32_16x16x32_bf16 v[86:89], v[144:147], v[220:223], v[86:89]
	v_mfma_f32_16x16x32_bf16 v[70:73], v[168:171], v[220:223], v[70:73]
	v_mfma_f32_16x16x32_bf16 v[70:73], v[176:179], v[224:227], v[70:73]
	v_mfma_f32_16x16x32_bf16 v[66:69], v[184:187], v[224:227], v[66:69]
	v_mfma_f32_16x16x32_bf16 v[66:69], v[180:183], v[220:223], v[66:69]
	v_mfma_f32_16x16x32_bf16 v[74:77], v[180:183], v[212:215], v[74:77]
	v_mfma_f32_16x16x32_bf16 v[74:77], v[184:187], v[216:219], v[74:77]
	v_mfma_f32_16x16x32_bf16 v[78:81], v[176:179], v[216:219], v[78:81]
	v_mfma_f32_16x16x32_bf16 v[78:81], v[168:171], v[212:215], v[78:81]
	v_mfma_f32_16x16x32_bf16 v[94:97], v[168:171], v[204:207], v[94:97]
	v_mfma_f32_16x16x32_bf16 v[94:97], v[176:179], v[208:211], v[94:97]
	v_mfma_f32_16x16x32_bf16 v[90:93], v[184:187], v[208:211], v[90:93]
	v_mfma_f32_16x16x32_bf16 v[90:93], v[180:183], v[204:207], v[90:93]
	v_mfma_f32_16x16x32_bf16 v[106:109], v[180:183], v[188:191], v[106:109]
	v_mfma_f32_16x16x32_bf16 v[106:109], v[184:187], v[192:195], v[106:109]
	v_mfma_f32_16x16x32_bf16 v[110:113], v[176:179], v[192:195], v[110:113]
	v_mfma_f32_16x16x32_bf16 v[110:113], v[168:171], v[188:191], v[110:113]
	s_setprio 0
	s_barrier
	s_mov_b32 m0, s40
	v_lshl_add_u64 v[172:173], s[22:23], 0, v[132:133]
	ds_read_b128 v[188:191], v141 offset:16384
	ds_read_b128 v[192:195], v141 offset:17408
	ds_read_b128 v[204:207], v141 offset:18432
	ds_read_b128 v[208:211], v141 offset:19456
	ds_read_b128 v[212:215], v141 offset:20480
	ds_read_b128 v[216:219], v141 offset:21504
	ds_read_b128 v[220:223], v141 offset:22528
	ds_read_b128 v[224:227], v141 offset:23552
	global_load_lds_dwordx4 v[172:173], off
	v_lshl_add_u64 v[196:197], s[22:23], 0, v[136:137]
	s_mov_b32 m0, s41
	v_lshl_add_u64 v[228:229], s[24:25], 0, v[132:133]
	global_load_lds_dwordx4 v[196:197], off
	s_mov_b32 m0, s42
	v_lshl_add_u64 v[230:231], s[20:21], 0, v[134:135]
	global_load_lds_dwordx4 v[228:229], off
	v_lshl_add_u64 v[228:229], s[24:25], 0, v[136:137]
	s_mov_b32 m0, s43
	s_nop 0
	global_load_lds_dwordx4 v[228:229], off
	v_lshl_add_u64 v[228:229], s[20:21], 0, v[130:131]
	s_mov_b32 m0, s7
	s_nop 0
	global_load_lds_dwordx4 v[228:229], off
	s_mov_b32 m0, s31
	s_nop 0
	global_load_lds_dwordx4 v[230:231], off
	s_waitcnt vmcnt(8)
	s_waitcnt lgkmcnt(0)
	s_barrier
	s_setprio 1
	s_waitcnt lgkmcnt(0)
	v_mfma_f32_16x16x32_bf16 v[62:65], v[144:147], v[188:191], v[62:65]
	v_mfma_f32_16x16x32_bf16 v[62:65], v[150:153], v[192:195], v[62:65]
	v_mfma_f32_16x16x32_bf16 v[58:61], v[158:161], v[192:195], v[58:61]
	v_mfma_f32_16x16x32_bf16 v[58:61], v[154:157], v[188:191], v[58:61]
	v_mfma_f32_16x16x32_bf16 v[50:53], v[154:157], v[204:207], v[50:53]
	v_mfma_f32_16x16x32_bf16 v[50:53], v[158:161], v[208:211], v[50:53]
	v_mfma_f32_16x16x32_bf16 v[54:57], v[150:153], v[208:211], v[54:57]
	v_mfma_f32_16x16x32_bf16 v[54:57], v[144:147], v[204:207], v[54:57]
	v_mfma_f32_16x16x32_bf16 v[38:41], v[144:147], v[212:215], v[38:41]
	v_mfma_f32_16x16x32_bf16 v[38:41], v[150:153], v[216:219], v[38:41]
	v_mfma_f32_16x16x32_bf16 v[34:37], v[158:161], v[216:219], v[34:37]
	v_mfma_f32_16x16x32_bf16 v[34:37], v[154:157], v[212:215], v[34:37]
	v_mfma_f32_16x16x32_bf16 v[18:21], v[154:157], v[220:223], v[18:21]
	v_mfma_f32_16x16x32_bf16 v[18:21], v[158:161], v[224:227], v[18:21]
	v_mfma_f32_16x16x32_bf16 v[22:25], v[150:153], v[224:227], v[22:25]
	v_mfma_f32_16x16x32_bf16 v[22:25], v[144:147], v[220:223], v[22:25]
	v_mfma_f32_16x16x32_bf16 v[6:9], v[168:171], v[220:223], v[6:9]
	v_mfma_f32_16x16x32_bf16 v[6:9], v[176:179], v[224:227], v[6:9]
	v_mfma_f32_16x16x32_bf16 v[2:5], v[184:187], v[224:227], v[2:5]
	v_mfma_f32_16x16x32_bf16 v[2:5], v[180:183], v[220:223], v[2:5]
	v_mfma_f32_16x16x32_bf16 v[10:13], v[180:183], v[212:215], v[10:13]
	v_mfma_f32_16x16x32_bf16 v[10:13], v[184:187], v[216:219], v[10:13]
	v_mfma_f32_16x16x32_bf16 v[14:17], v[176:179], v[216:219], v[14:17]
	v_mfma_f32_16x16x32_bf16 v[14:17], v[168:171], v[212:215], v[14:17]
	v_mfma_f32_16x16x32_bf16 v[30:33], v[168:171], v[204:207], v[30:33]
	v_mfma_f32_16x16x32_bf16 v[30:33], v[176:179], v[208:211], v[30:33]
	v_mfma_f32_16x16x32_bf16 v[26:29], v[184:187], v[208:211], v[26:29]
	v_mfma_f32_16x16x32_bf16 v[26:29], v[180:183], v[204:207], v[26:29]
	v_mfma_f32_16x16x32_bf16 v[42:45], v[180:183], v[188:191], v[42:45]
	v_mfma_f32_16x16x32_bf16 v[42:45], v[184:187], v[192:195], v[42:45]
	v_mfma_f32_16x16x32_bf16 v[46:49], v[176:179], v[192:195], v[46:49]
	v_mfma_f32_16x16x32_bf16 v[46:49], v[168:171], v[188:191], v[46:49]
	s_setprio 0
	s_barrier
	ds_read_b128 v[144:147], v142
	ds_read_b128 v[150:153], v142 offset:1024
	ds_read_b128 v[154:157], v142 offset:2048
	ds_read_b128 v[158:161], v142 offset:3072
	ds_read_b128 v[168:171], v143
	ds_read_b128 v[176:179], v143 offset:1024
	ds_read_b128 v[180:183], v143 offset:2048
	ds_read_b128 v[184:187], v143 offset:3072
	s_mov_b32 m0, s33
	v_lshl_add_u64 v[232:233], s[18:19], 0, v[130:131]
	ds_read_b128 v[188:191], v141 offset:32768
	ds_read_b128 v[192:195], v141 offset:33792
	ds_read_b128 v[204:207], v141 offset:34816
	ds_read_b128 v[208:211], v141 offset:35840
	ds_read_b128 v[212:215], v141 offset:36864
	ds_read_b128 v[216:219], v141 offset:37888
	ds_read_b128 v[220:223], v141 offset:38912
	ds_read_b128 v[224:227], v141 offset:39936
	global_load_lds_dwordx4 v[232:233], off
	v_lshl_add_u64 v[232:233], s[18:19], 0, v[134:135]
	s_mov_b32 m0, s34
	s_nop 0
	global_load_lds_dwordx4 v[232:233], off
	s_waitcnt vmcnt(8)
	s_waitcnt lgkmcnt(0)
	s_barrier
	s_setprio 1
	s_waitcnt lgkmcnt(0)
	v_mfma_f32_16x16x32_bf16 v[126:129], v[144:147], v[188:191], v[126:129]
	v_mfma_f32_16x16x32_bf16 v[126:129], v[150:153], v[192:195], v[126:129]
	v_mfma_f32_16x16x32_bf16 v[122:125], v[158:161], v[192:195], v[122:125]
	v_mfma_f32_16x16x32_bf16 v[122:125], v[154:157], v[188:191], v[122:125]
	v_mfma_f32_16x16x32_bf16 v[114:117], v[154:157], v[204:207], v[114:117]
	v_mfma_f32_16x16x32_bf16 v[114:117], v[158:161], v[208:211], v[114:117]
	v_mfma_f32_16x16x32_bf16 v[118:121], v[150:153], v[208:211], v[118:121]
	v_mfma_f32_16x16x32_bf16 v[118:121], v[144:147], v[204:207], v[118:121]
	v_mfma_f32_16x16x32_bf16 v[102:105], v[144:147], v[212:215], v[102:105]
	v_mfma_f32_16x16x32_bf16 v[102:105], v[150:153], v[216:219], v[102:105]
	v_mfma_f32_16x16x32_bf16 v[98:101], v[158:161], v[216:219], v[98:101]
	v_mfma_f32_16x16x32_bf16 v[98:101], v[154:157], v[212:215], v[98:101]
	v_mfma_f32_16x16x32_bf16 v[82:85], v[154:157], v[220:223], v[82:85]
	v_mfma_f32_16x16x32_bf16 v[82:85], v[158:161], v[224:227], v[82:85]
	v_mfma_f32_16x16x32_bf16 v[86:89], v[150:153], v[224:227], v[86:89]
	v_mfma_f32_16x16x32_bf16 v[86:89], v[144:147], v[220:223], v[86:89]
	v_mfma_f32_16x16x32_bf16 v[70:73], v[168:171], v[220:223], v[70:73]
	v_mfma_f32_16x16x32_bf16 v[70:73], v[176:179], v[224:227], v[70:73]
	v_mfma_f32_16x16x32_bf16 v[66:69], v[184:187], v[224:227], v[66:69]
	v_mfma_f32_16x16x32_bf16 v[66:69], v[180:183], v[220:223], v[66:69]
	v_mfma_f32_16x16x32_bf16 v[74:77], v[180:183], v[212:215], v[74:77]
	v_mfma_f32_16x16x32_bf16 v[74:77], v[184:187], v[216:219], v[74:77]
	v_mfma_f32_16x16x32_bf16 v[78:81], v[176:179], v[216:219], v[78:81]
	v_mfma_f32_16x16x32_bf16 v[78:81], v[168:171], v[212:215], v[78:81]
	v_mfma_f32_16x16x32_bf16 v[94:97], v[168:171], v[204:207], v[94:97]
	v_mfma_f32_16x16x32_bf16 v[94:97], v[176:179], v[208:211], v[94:97]
	v_mfma_f32_16x16x32_bf16 v[90:93], v[184:187], v[208:211], v[90:93]
	v_mfma_f32_16x16x32_bf16 v[90:93], v[180:183], v[204:207], v[90:93]
	v_mfma_f32_16x16x32_bf16 v[106:109], v[180:183], v[188:191], v[106:109]
	v_mfma_f32_16x16x32_bf16 v[106:109], v[184:187], v[192:195], v[106:109]
	v_mfma_f32_16x16x32_bf16 v[110:113], v[176:179], v[192:195], v[110:113]
	v_mfma_f32_16x16x32_bf16 v[110:113], v[168:171], v[188:191], v[110:113]
	s_setprio 0
	s_barrier
	s_mov_b32 m0, s44
	v_lshl_add_u64 v[172:173], v[172:173], 0, s[14:15]
	ds_read_b128 v[188:191], v141 offset:49152
	ds_read_b128 v[192:195], v141 offset:50176
	ds_read_b128 v[204:207], v141 offset:51200
	ds_read_b128 v[208:211], v141 offset:52224
	ds_read_b128 v[212:215], v141 offset:53248
	ds_read_b128 v[216:219], v141 offset:54272
	ds_read_b128 v[220:223], v141 offset:55296
	ds_read_b128 v[224:227], v141 offset:56320
	global_load_lds_dwordx4 v[172:173], off
	v_lshl_add_u64 v[172:173], v[196:197], 0, s[14:15]
	s_mov_b32 m0, s45
	s_nop 0
	global_load_lds_dwordx4 v[172:173], off
	v_lshl_add_u64 v[172:173], s[26:27], 0, v[132:133]
	s_mov_b32 m0, s46
	s_nop 0
	global_load_lds_dwordx4 v[172:173], off
	v_lshl_add_u64 v[172:173], s[26:27], 0, v[136:137]
	s_mov_b32 m0, s47
	s_nop 0
	global_load_lds_dwordx4 v[172:173], off
	v_lshl_add_u64 v[172:173], v[228:229], 0, s[14:15]
	s_mov_b32 m0, s36
	s_nop 0
	global_load_lds_dwordx4 v[172:173], off
	v_lshl_add_u64 v[172:173], v[230:231], 0, s[14:15]
	s_mov_b32 m0, s37
	s_nop 0
	global_load_lds_dwordx4 v[172:173], off
	s_waitcnt vmcnt(8)
	s_waitcnt lgkmcnt(0)
	s_barrier
	s_setprio 1
	s_waitcnt lgkmcnt(0)
	v_mfma_f32_16x16x32_bf16 v[62:65], v[144:147], v[188:191], v[62:65]
	v_mfma_f32_16x16x32_bf16 v[62:65], v[150:153], v[192:195], v[62:65]
	v_mfma_f32_16x16x32_bf16 v[58:61], v[158:161], v[192:195], v[58:61]
	v_mfma_f32_16x16x32_bf16 v[58:61], v[154:157], v[188:191], v[58:61]
	v_mfma_f32_16x16x32_bf16 v[50:53], v[154:157], v[204:207], v[50:53]
	v_mfma_f32_16x16x32_bf16 v[50:53], v[158:161], v[208:211], v[50:53]
	v_mfma_f32_16x16x32_bf16 v[54:57], v[150:153], v[208:211], v[54:57]
	v_mfma_f32_16x16x32_bf16 v[54:57], v[144:147], v[204:207], v[54:57]
	v_mfma_f32_16x16x32_bf16 v[38:41], v[144:147], v[212:215], v[38:41]
	v_mfma_f32_16x16x32_bf16 v[38:41], v[150:153], v[216:219], v[38:41]
	v_mfma_f32_16x16x32_bf16 v[34:37], v[158:161], v[216:219], v[34:37]
	v_mfma_f32_16x16x32_bf16 v[34:37], v[154:157], v[212:215], v[34:37]
	v_mfma_f32_16x16x32_bf16 v[18:21], v[154:157], v[220:223], v[18:21]
	v_mfma_f32_16x16x32_bf16 v[18:21], v[158:161], v[224:227], v[18:21]
	v_mfma_f32_16x16x32_bf16 v[22:25], v[150:153], v[224:227], v[22:25]
	v_mfma_f32_16x16x32_bf16 v[22:25], v[144:147], v[220:223], v[22:25]
	v_mfma_f32_16x16x32_bf16 v[6:9], v[168:171], v[220:223], v[6:9]
	v_mfma_f32_16x16x32_bf16 v[6:9], v[176:179], v[224:227], v[6:9]
	v_mfma_f32_16x16x32_bf16 v[2:5], v[184:187], v[224:227], v[2:5]
	v_mfma_f32_16x16x32_bf16 v[2:5], v[180:183], v[220:223], v[2:5]
	v_mfma_f32_16x16x32_bf16 v[10:13], v[180:183], v[212:215], v[10:13]
	v_mfma_f32_16x16x32_bf16 v[10:13], v[184:187], v[216:219], v[10:13]
	v_mfma_f32_16x16x32_bf16 v[14:17], v[176:179], v[216:219], v[14:17]
	v_mfma_f32_16x16x32_bf16 v[14:17], v[168:171], v[212:215], v[14:17]
	v_mfma_f32_16x16x32_bf16 v[30:33], v[168:171], v[204:207], v[30:33]
	v_mfma_f32_16x16x32_bf16 v[30:33], v[176:179], v[208:211], v[30:33]
	v_mfma_f32_16x16x32_bf16 v[26:29], v[184:187], v[208:211], v[26:29]
	v_mfma_f32_16x16x32_bf16 v[26:29], v[180:183], v[204:207], v[26:29]
	v_mfma_f32_16x16x32_bf16 v[42:45], v[180:183], v[188:191], v[42:45]
	v_mfma_f32_16x16x32_bf16 v[42:45], v[184:187], v[192:195], v[42:45]
	v_mfma_f32_16x16x32_bf16 v[46:49], v[176:179], v[192:195], v[46:49]
	v_mfma_f32_16x16x32_bf16 v[46:49], v[168:171], v[188:191], v[46:49]
	s_setprio 0
	s_barrier
	s_andn2_b64 vcc, exec, s[16:17]
	s_mov_b64 s[18:19], -1
	s_mov_b64 s[16:17], 0
	s_movk_i32 s24, 0x100
	s_cbranch_vccz .LBB0_2240
	s_lshl_b32 s7, s30, 21
	v_readlane_b32 s0, v249, 29
	v_lshl_or_b32 v130, s6, 8, v148
	v_mov_b32_e32 v139, 0
	s_add_u32 s8, s0, s7
	v_readlane_b32 s0, v249, 31
	v_or_b32_e32 v130, s35, v130
	v_cvt_pk_bf16_f32 v70, v70, v71
	v_cvt_pk_bf16_f32 v71, v72, v73
	v_cvt_pk_bf16_f32 v72, v66, v67
	v_add_u32_e32 v66, 0x80, v138
	v_mov_b32_e32 v67, v139
	s_addc_u32 s9, s0, 0
	v_ashrrev_i32_e32 v131, 31, v130
	v_lshlrev_b64 v[132:133], 13, v[138:139]
	v_cvt_pk_bf16_f32 v110, v110, v111
	v_cvt_pk_bf16_f32 v111, v112, v113
	v_cvt_pk_bf16_f32 v112, v106, v107
	v_or_b32_e32 v106, 16, v138
	v_mov_b32_e32 v107, v139
	v_lshlrev_b64 v[66:67], 13, v[66:67]
	v_cvt_pk_bf16_f32 v46, v46, v47
	v_cvt_pk_bf16_f32 v47, v48, v49
	v_cvt_pk_bf16_f32 v48, v42, v43
	v_add_u32_e32 v42, 0x90, v138
	v_mov_b32_e32 v43, v139
	v_lshl_add_u64 v[132:133], s[8:9], 0, v[132:133]
	v_lshlrev_b64 v[130:131], 1, v[130:131]
	v_lshlrev_b64 v[106:107], 13, v[106:107]
	v_cvt_pk_bf16_f32 v94, v94, v95
	v_cvt_pk_bf16_f32 v95, v96, v97
	v_cvt_pk_bf16_f32 v96, v90, v91
	v_or_b32_e32 v90, 32, v138
	v_mov_b32_e32 v91, v139
	v_lshl_add_u64 v[66:67], s[8:9], 0, v[66:67]
	v_lshlrev_b64 v[42:43], 13, v[42:43]
	v_cvt_pk_bf16_f32 v30, v30, v31
	v_cvt_pk_bf16_f32 v31, v32, v33
	v_cvt_pk_bf16_f32 v32, v26, v27
	v_add_u32_e32 v26, 0xa0, v138
	v_mov_b32_e32 v27, v139
	v_lshl_add_u64 v[132:133], v[132:133], 0, v[130:131]
	v_cvt_pk_bf16_f32 v113, v108, v109
	v_lshl_add_u64 v[106:107], s[8:9], 0, v[106:107]
	v_lshlrev_b64 v[90:91], 13, v[90:91]
	v_cvt_pk_bf16_f32 v78, v78, v79
	v_cvt_pk_bf16_f32 v79, v80, v81
	v_cvt_pk_bf16_f32 v80, v74, v75
	v_or_b32_e32 v74, 48, v138
	v_mov_b32_e32 v75, v139
	v_lshl_add_u64 v[66:67], v[66:67], 0, v[130:131]
	v_cvt_pk_bf16_f32 v49, v44, v45
	v_lshl_add_u64 v[42:43], s[8:9], 0, v[42:43]
	v_lshlrev_b64 v[26:27], 13, v[26:27]
	v_add_u32_e32 v138, 0xb0, v138
	global_store_dwordx4 v[132:133], v[110:113], off offset:256
	v_cvt_pk_bf16_f32 v97, v92, v93
	v_lshl_add_u64 v[90:91], s[8:9], 0, v[90:91]
	v_lshl_add_u64 v[110:111], v[106:107], 0, v[130:131]
	v_lshlrev_b64 v[74:75], 13, v[74:75]
	global_store_dwordx4 v[66:67], v[46:49], off offset:256
	v_cvt_pk_bf16_f32 v33, v28, v29
	v_lshl_add_u64 v[26:27], s[8:9], 0, v[26:27]
	v_lshl_add_u64 v[46:47], v[42:43], 0, v[130:131]
	v_cvt_pk_bf16_f32 v14, v14, v15
	v_cvt_pk_bf16_f32 v15, v16, v17
	v_cvt_pk_bf16_f32 v16, v10, v11
	v_lshlrev_b64 v[10:11], 13, v[138:139]
	global_store_dwordx4 v[110:111], v[94:97], off offset:256
	v_cvt_pk_bf16_f32 v81, v76, v77
	v_lshl_add_u64 v[74:75], s[8:9], 0, v[74:75]
	v_lshl_add_u64 v[94:95], v[90:91], 0, v[130:131]
	global_store_dwordx4 v[46:47], v[30:33], off offset:256
	v_cvt_pk_bf16_f32 v17, v12, v13
	v_lshl_add_u64 v[10:11], s[8:9], 0, v[10:11]
	v_lshl_add_u64 v[30:31], v[26:27], 0, v[130:131]
	v_cvt_pk_bf16_f32 v126, v126, v127
	v_cvt_pk_bf16_f32 v127, v128, v129
	v_cvt_pk_bf16_f32 v128, v122, v123
	v_cvt_pk_bf16_f32 v129, v124, v125
	v_cvt_pk_bf16_f32 v106, v118, v119
	v_cvt_pk_bf16_f32 v107, v120, v121
	v_cvt_pk_bf16_f32 v108, v114, v115
	v_cvt_pk_bf16_f32 v109, v116, v117
	v_cvt_pk_bf16_f32 v90, v102, v103
	v_cvt_pk_bf16_f32 v91, v104, v105
	v_cvt_pk_bf16_f32 v92, v98, v99
	v_cvt_pk_bf16_f32 v93, v100, v101
	global_store_dwordx4 v[94:95], v[78:81], off offset:256
	v_cvt_pk_bf16_f32 v76, v82, v83
	v_cvt_pk_bf16_f32 v77, v84, v85
	v_lshl_add_u64 v[78:79], v[74:75], 0, v[130:131]
	v_cvt_pk_bf16_f32 v74, v86, v87
	v_cvt_pk_bf16_f32 v75, v88, v89
	v_cvt_pk_bf16_f32 v73, v68, v69
	v_cvt_pk_bf16_f32 v62, v62, v63
	v_cvt_pk_bf16_f32 v63, v64, v65
	v_cvt_pk_bf16_f32 v64, v58, v59
	v_cvt_pk_bf16_f32 v65, v60, v61
	v_cvt_pk_bf16_f32 v42, v54, v55
	v_cvt_pk_bf16_f32 v43, v56, v57
	v_cvt_pk_bf16_f32 v44, v50, v51
	v_cvt_pk_bf16_f32 v45, v52, v53
	v_cvt_pk_bf16_f32 v26, v38, v39
	v_cvt_pk_bf16_f32 v27, v40, v41
	v_cvt_pk_bf16_f32 v28, v34, v35
	v_cvt_pk_bf16_f32 v29, v36, v37
	global_store_dwordx4 v[30:31], v[14:17], off offset:256
	v_cvt_pk_bf16_f32 v12, v18, v19
	v_cvt_pk_bf16_f32 v13, v20, v21
	v_lshl_add_u64 v[14:15], v[10:11], 0, v[130:131]
	v_cvt_pk_bf16_f32 v10, v22, v23
	v_cvt_pk_bf16_f32 v11, v24, v25
	v_cvt_pk_bf16_f32 v6, v6, v7
	v_cvt_pk_bf16_f32 v7, v8, v9
	v_cvt_pk_bf16_f32 v8, v2, v3
	v_cvt_pk_bf16_f32 v9, v4, v5
	global_store_dwordx4 v[132:133], v[126:129], off
	global_store_dwordx4 v[110:111], v[106:109], off
	global_store_dwordx4 v[94:95], v[90:93], off
	global_store_dwordx4 v[78:79], v[74:77], off
	global_store_dwordx4 v[78:79], v[70:73], off offset:256
	global_store_dwordx4 v[66:67], v[62:65], off
	global_store_dwordx4 v[46:47], v[42:45], off
	global_store_dwordx4 v[30:31], v[26:29], off
	global_store_dwordx4 v[14:15], v[10:13], off
	global_store_dwordx4 v[14:15], v[6:9], off offset:256
	s_waitcnt vmcnt(0)
	s_cmpk_lt_u32 s3, 0x100
	s_cbranch_scc0 .LBB0_2243
	s_barrier

.LBB0_2373:
	s_add_u32 s60, s20, 0xfff00000
	s_addc_u32 s61, s21, -1
	s_mov_b32 m0, s35
	ds_read_b128 v[142:145], v148
	global_load_lds_dwordx4 v130, s[60:61]
	s_mov_b32 m0, s36
	ds_read_b128 v[154:157], v148 offset:1024
	global_load_lds_dwordx4 v134, s[60:61]
	s_mov_b32 m0, s40
	ds_read_b128 v[158:161], v148 offset:2048
	global_load_lds_dwordx4 v138, s[20:21]
	s_mov_b32 m0, s41
	ds_read_b128 v[168:171], v148 offset:3072
	global_load_lds_dwordx4 v140, s[20:21]
	ds_read_b128 v[176:179], v149
	ds_read_b128 v[180:183], v149 offset:1024
	ds_read_b128 v[184:187], v149 offset:2048
	ds_read_b128 v[188:191], v149 offset:3072
	s_add_u32 s22, s20, 0xfff00080
	s_addc_u32 s23, s21, -1
	s_cmp_eq_u32 s57, 60
	s_cselect_b32 s25, s52, s23
	s_cselect_b32 s24, s53, s22
	s_cselect_b32 s23, s7, s56
	s_cselect_b32 s22, s54, s55
	ds_read_b128 v[192:195], v150
	ds_read_b128 v[204:207], v150 offset:1024
	ds_read_b128 v[208:211], v150 offset:2048
	ds_read_b128 v[212:215], v150 offset:3072
	ds_read_b128 v[216:219], v150 offset:4096
	ds_read_b128 v[220:223], v150 offset:5120
	ds_read_b128 v[224:227], v150 offset:6144
	ds_read_b128 v[228:231], v150 offset:7168
	s_waitcnt vmcnt(8)
	s_waitcnt lgkmcnt(0)
	s_barrier
	s_setprio 1
	s_waitcnt lgkmcnt(0)
	v_mfma_f32_16x16x32_bf16 v[126:129], v[142:145], v[192:195], v[126:129]
	v_mfma_f32_16x16x32_bf16 v[126:129], v[154:157], v[204:207], v[126:129]
	v_mfma_f32_16x16x32_bf16 v[122:125], v[168:171], v[204:207], v[122:125]
	v_mfma_f32_16x16x32_bf16 v[122:125], v[158:161], v[192:195], v[122:125]
	v_mfma_f32_16x16x32_bf16 v[106:109], v[158:161], v[208:211], v[106:109]
	v_mfma_f32_16x16x32_bf16 v[106:109], v[168:171], v[212:215], v[106:109]
	v_mfma_f32_16x16x32_bf16 v[110:113], v[154:157], v[212:215], v[110:113]
	v_mfma_f32_16x16x32_bf16 v[110:113], v[142:145], v[208:211], v[110:113]
	v_mfma_f32_16x16x32_bf16 v[94:97], v[142:145], v[216:219], v[94:97]
	v_mfma_f32_16x16x32_bf16 v[94:97], v[154:157], v[220:223], v[94:97]
	v_mfma_f32_16x16x32_bf16 v[90:93], v[168:171], v[220:223], v[90:93]
	v_mfma_f32_16x16x32_bf16 v[90:93], v[158:161], v[216:219], v[90:93]
	v_mfma_f32_16x16x32_bf16 v[74:77], v[158:161], v[224:227], v[74:77]
	v_mfma_f32_16x16x32_bf16 v[74:77], v[168:171], v[228:231], v[74:77]
	v_mfma_f32_16x16x32_bf16 v[78:81], v[154:157], v[228:231], v[78:81]
	v_mfma_f32_16x16x32_bf16 v[78:81], v[142:145], v[224:227], v[78:81]
	v_mfma_f32_16x16x32_bf16 v[70:73], v[176:179], v[224:227], v[70:73]
	v_mfma_f32_16x16x32_bf16 v[70:73], v[180:183], v[228:231], v[70:73]
	v_mfma_f32_16x16x32_bf16 v[66:69], v[188:191], v[228:231], v[66:69]
	v_mfma_f32_16x16x32_bf16 v[66:69], v[184:187], v[224:227], v[66:69]
	v_mfma_f32_16x16x32_bf16 v[82:85], v[184:187], v[216:219], v[82:85]
	v_mfma_f32_16x16x32_bf16 v[82:85], v[188:191], v[220:223], v[82:85]
	v_mfma_f32_16x16x32_bf16 v[86:89], v[180:183], v[220:223], v[86:89]
	v_mfma_f32_16x16x32_bf16 v[86:89], v[176:179], v[216:219], v[86:89]
	v_mfma_f32_16x16x32_bf16 v[102:105], v[176:179], v[208:211], v[102:105]
	v_mfma_f32_16x16x32_bf16 v[102:105], v[180:183], v[212:215], v[102:105]
	v_mfma_f32_16x16x32_bf16 v[98:101], v[188:191], v[212:215], v[98:101]
	v_mfma_f32_16x16x32_bf16 v[98:101], v[184:187], v[208:211], v[98:101]
	v_mfma_f32_16x16x32_bf16 v[114:117], v[184:187], v[192:195], v[114:117]
	v_mfma_f32_16x16x32_bf16 v[114:117], v[188:191], v[204:207], v[114:117]
	v_mfma_f32_16x16x32_bf16 v[118:121], v[180:183], v[204:207], v[118:121]
	v_mfma_f32_16x16x32_bf16 v[118:121], v[176:179], v[192:195], v[118:121]
	s_setprio 0
	s_barrier
	s_mov_b32 m0, s42
	s_add_u32 s60, s22, 0x100000
	global_load_lds_dwordx4 v132, s[22:23]
	s_mov_b32 m0, s43
	s_addc_u32 s61, s23, 0
	global_load_lds_dwordx4 v136, s[22:23]
	s_mov_b32 m0, s44
	ds_read_b128 v[192:195], v150 offset:16384
	global_load_lds_dwordx4 v132, s[60:61]
	s_mov_b32 m0, s45
	ds_read_b128 v[204:207], v150 offset:17408
	global_load_lds_dwordx4 v136, s[60:61]
	ds_read_b128 v[208:211], v150 offset:18432
	ds_read_b128 v[212:215], v150 offset:19456
	ds_read_b128 v[216:219], v150 offset:20480
	ds_read_b128 v[220:223], v150 offset:21504
	ds_read_b128 v[224:227], v150 offset:22528
	ds_read_b128 v[228:231], v150 offset:23552
	s_waitcnt vmcnt(6)
	s_waitcnt lgkmcnt(0)
	s_barrier
	s_setprio 1
	s_waitcnt lgkmcnt(0)
	v_mfma_f32_16x16x32_bf16 v[62:65], v[142:145], v[192:195], v[62:65]
	v_mfma_f32_16x16x32_bf16 v[62:65], v[154:157], v[204:207], v[62:65]
	v_mfma_f32_16x16x32_bf16 v[58:61], v[168:171], v[204:207], v[58:61]
	v_mfma_f32_16x16x32_bf16 v[58:61], v[158:161], v[192:195], v[58:61]
	v_mfma_f32_16x16x32_bf16 v[42:45], v[158:161], v[208:211], v[42:45]
	v_mfma_f32_16x16x32_bf16 v[42:45], v[168:171], v[212:215], v[42:45]
	v_mfma_f32_16x16x32_bf16 v[46:49], v[154:157], v[212:215], v[46:49]
	v_mfma_f32_16x16x32_bf16 v[46:49], v[142:145], v[208:211], v[46:49]
	v_mfma_f32_16x16x32_bf16 v[30:33], v[142:145], v[216:219], v[30:33]
	v_mfma_f32_16x16x32_bf16 v[30:33], v[154:157], v[220:223], v[30:33]
	v_mfma_f32_16x16x32_bf16 v[26:29], v[168:171], v[220:223], v[26:29]
	v_mfma_f32_16x16x32_bf16 v[26:29], v[158:161], v[216:219], v[26:29]
	v_mfma_f32_16x16x32_bf16 v[10:13], v[158:161], v[224:227], v[10:13]
	v_mfma_f32_16x16x32_bf16 v[10:13], v[168:171], v[228:231], v[10:13]
	v_mfma_f32_16x16x32_bf16 v[14:17], v[154:157], v[228:231], v[14:17]
	v_mfma_f32_16x16x32_bf16 v[14:17], v[142:145], v[224:227], v[14:17]
	v_mfma_f32_16x16x32_bf16 v[6:9], v[176:179], v[224:227], v[6:9]
	v_mfma_f32_16x16x32_bf16 v[6:9], v[180:183], v[228:231], v[6:9]
	v_mfma_f32_16x16x32_bf16 v[2:5], v[188:191], v[228:231], v[2:5]
	v_mfma_f32_16x16x32_bf16 v[2:5], v[184:187], v[224:227], v[2:5]
	v_mfma_f32_16x16x32_bf16 v[18:21], v[184:187], v[216:219], v[18:21]
	v_mfma_f32_16x16x32_bf16 v[18:21], v[188:191], v[220:223], v[18:21]
	v_mfma_f32_16x16x32_bf16 v[22:25], v[180:183], v[220:223], v[22:25]
	v_mfma_f32_16x16x32_bf16 v[22:25], v[176:179], v[216:219], v[22:25]
	v_mfma_f32_16x16x32_bf16 v[38:41], v[176:179], v[208:211], v[38:41]
	v_mfma_f32_16x16x32_bf16 v[38:41], v[180:183], v[212:215], v[38:41]
	v_mfma_f32_16x16x32_bf16 v[34:37], v[188:191], v[212:215], v[34:37]
	v_mfma_f32_16x16x32_bf16 v[34:37], v[184:187], v[208:211], v[34:37]
	v_mfma_f32_16x16x32_bf16 v[50:53], v[184:187], v[192:195], v[50:53]
	v_mfma_f32_16x16x32_bf16 v[50:53], v[188:191], v[204:207], v[50:53]
	v_mfma_f32_16x16x32_bf16 v[54:57], v[180:183], v[204:207], v[54:57]
	v_mfma_f32_16x16x32_bf16 v[54:57], v[176:179], v[192:195], v[54:57]
	s_setprio 0
	s_barrier
	s_mov_b32 m0, s29
	ds_read_b128 v[142:145], v151
	global_load_lds_dwordx4 v130, s[24:25]
	s_mov_b32 m0, s30
	ds_read_b128 v[154:157], v151 offset:1024
	global_load_lds_dwordx4 v134, s[24:25]
	s_add_u32 s24, s24, 0x100000
	s_addc_u32 s25, s25, 0
	s_mov_b32 m0, s31
	ds_read_b128 v[158:161], v151 offset:2048
	global_load_lds_dwordx4 v130, s[24:25]
	s_mov_b32 m0, s33
	ds_read_b128 v[168:171], v151 offset:3072
	global_load_lds_dwordx4 v134, s[24:25]
	ds_read_b128 v[176:179], v152
	ds_read_b128 v[180:183], v152 offset:1024
	ds_read_b128 v[184:187], v152 offset:2048
	ds_read_b128 v[188:191], v152 offset:3072
	ds_read_b128 v[192:195], v150 offset:32768
	ds_read_b128 v[204:207], v150 offset:33792
	ds_read_b128 v[208:211], v150 offset:34816
	ds_read_b128 v[212:215], v150 offset:35840
	ds_read_b128 v[216:219], v150 offset:36864
	ds_read_b128 v[220:223], v150 offset:37888
	ds_read_b128 v[224:227], v150 offset:38912
	ds_read_b128 v[228:231], v150 offset:39936
	s_waitcnt vmcnt(8)
	s_waitcnt lgkmcnt(0)
	s_barrier
	s_setprio 1
	s_waitcnt lgkmcnt(0)
	v_mfma_f32_16x16x32_bf16 v[126:129], v[142:145], v[192:195], v[126:129]
	v_mfma_f32_16x16x32_bf16 v[126:129], v[154:157], v[204:207], v[126:129]
	v_mfma_f32_16x16x32_bf16 v[122:125], v[168:171], v[204:207], v[122:125]
	v_mfma_f32_16x16x32_bf16 v[122:125], v[158:161], v[192:195], v[122:125]
	v_mfma_f32_16x16x32_bf16 v[106:109], v[158:161], v[208:211], v[106:109]
	v_mfma_f32_16x16x32_bf16 v[106:109], v[168:171], v[212:215], v[106:109]
	v_mfma_f32_16x16x32_bf16 v[110:113], v[154:157], v[212:215], v[110:113]
	v_mfma_f32_16x16x32_bf16 v[110:113], v[142:145], v[208:211], v[110:113]
	v_mfma_f32_16x16x32_bf16 v[94:97], v[142:145], v[216:219], v[94:97]
	v_mfma_f32_16x16x32_bf16 v[94:97], v[154:157], v[220:223], v[94:97]
	v_mfma_f32_16x16x32_bf16 v[90:93], v[168:171], v[220:223], v[90:93]
	v_mfma_f32_16x16x32_bf16 v[90:93], v[158:161], v[216:219], v[90:93]
	v_mfma_f32_16x16x32_bf16 v[74:77], v[158:161], v[224:227], v[74:77]
	v_mfma_f32_16x16x32_bf16 v[74:77], v[168:171], v[228:231], v[74:77]
	v_mfma_f32_16x16x32_bf16 v[78:81], v[154:157], v[228:231], v[78:81]
	v_mfma_f32_16x16x32_bf16 v[78:81], v[142:145], v[224:227], v[78:81]
	v_mfma_f32_16x16x32_bf16 v[70:73], v[176:179], v[224:227], v[70:73]
	v_mfma_f32_16x16x32_bf16 v[70:73], v[180:183], v[228:231], v[70:73]
	v_mfma_f32_16x16x32_bf16 v[66:69], v[188:191], v[228:231], v[66:69]
	v_mfma_f32_16x16x32_bf16 v[66:69], v[184:187], v[224:227], v[66:69]
	v_mfma_f32_16x16x32_bf16 v[82:85], v[184:187], v[216:219], v[82:85]
	v_mfma_f32_16x16x32_bf16 v[82:85], v[188:191], v[220:223], v[82:85]
	v_mfma_f32_16x16x32_bf16 v[86:89], v[180:183], v[220:223], v[86:89]
	v_mfma_f32_16x16x32_bf16 v[86:89], v[176:179], v[216:219], v[86:89]
	v_mfma_f32_16x16x32_bf16 v[102:105], v[176:179], v[208:211], v[102:105]
	v_mfma_f32_16x16x32_bf16 v[102:105], v[180:183], v[212:215], v[102:105]
	v_mfma_f32_16x16x32_bf16 v[98:101], v[188:191], v[212:215], v[98:101]
	v_mfma_f32_16x16x32_bf16 v[98:101], v[184:187], v[208:211], v[98:101]
	v_mfma_f32_16x16x32_bf16 v[114:117], v[184:187], v[192:195], v[114:117]
	v_mfma_f32_16x16x32_bf16 v[114:117], v[188:191], v[204:207], v[114:117]
	v_mfma_f32_16x16x32_bf16 v[118:121], v[180:183], v[204:207], v[118:121]
	v_mfma_f32_16x16x32_bf16 v[118:121], v[176:179], v[192:195], v[118:121]
	s_setprio 0
	s_barrier
	s_mov_b32 m0, s46
	s_add_u32 s22, s22, 0x80
	s_addc_u32 s23, s23, 0
	global_load_lds_dwordx4 v132, s[22:23]
	s_mov_b32 m0, s47
	ds_read_b128 v[192:195], v150 offset:49152
	global_load_lds_dwordx4 v136, s[22:23]
	s_mov_b32 m0, s48
	s_add_u32 s22, s22, 0x100000
	s_addc_u32 s23, s23, 0
	global_load_lds_dwordx4 v132, s[22:23]
	s_mov_b32 m0, s49
	ds_read_b128 v[204:207], v150 offset:50176
	global_load_lds_dwordx4 v136, s[22:23]
	ds_read_b128 v[208:211], v150 offset:51200
	ds_read_b128 v[212:215], v150 offset:52224
	ds_read_b128 v[216:219], v150 offset:53248
	ds_read_b128 v[220:223], v150 offset:54272
	ds_read_b128 v[224:227], v150 offset:55296
	ds_read_b128 v[228:231], v150 offset:56320
	s_waitcnt vmcnt(6)
	s_waitcnt lgkmcnt(0)
	s_barrier
	s_setprio 1
	s_waitcnt lgkmcnt(0)
	v_mfma_f32_16x16x32_bf16 v[62:65], v[142:145], v[192:195], v[62:65]
	v_mfma_f32_16x16x32_bf16 v[62:65], v[154:157], v[204:207], v[62:65]
	v_mfma_f32_16x16x32_bf16 v[58:61], v[168:171], v[204:207], v[58:61]
	v_mfma_f32_16x16x32_bf16 v[58:61], v[158:161], v[192:195], v[58:61]
	v_mfma_f32_16x16x32_bf16 v[42:45], v[158:161], v[208:211], v[42:45]
	v_mfma_f32_16x16x32_bf16 v[42:45], v[168:171], v[212:215], v[42:45]
	v_mfma_f32_16x16x32_bf16 v[46:49], v[154:157], v[212:215], v[46:49]
	v_mfma_f32_16x16x32_bf16 v[46:49], v[142:145], v[208:211], v[46:49]
	v_mfma_f32_16x16x32_bf16 v[30:33], v[142:145], v[216:219], v[30:33]
	v_mfma_f32_16x16x32_bf16 v[30:33], v[154:157], v[220:223], v[30:33]
	v_mfma_f32_16x16x32_bf16 v[26:29], v[168:171], v[220:223], v[26:29]
	v_mfma_f32_16x16x32_bf16 v[26:29], v[158:161], v[216:219], v[26:29]
	v_mfma_f32_16x16x32_bf16 v[10:13], v[158:161], v[224:227], v[10:13]
	v_mfma_f32_16x16x32_bf16 v[10:13], v[168:171], v[228:231], v[10:13]
	v_mfma_f32_16x16x32_bf16 v[14:17], v[154:157], v[228:231], v[14:17]
	v_mfma_f32_16x16x32_bf16 v[14:17], v[142:145], v[224:227], v[14:17]
	v_mfma_f32_16x16x32_bf16 v[6:9], v[176:179], v[224:227], v[6:9]
	v_mfma_f32_16x16x32_bf16 v[6:9], v[180:183], v[228:231], v[6:9]
	v_mfma_f32_16x16x32_bf16 v[2:5], v[188:191], v[228:231], v[2:5]
	v_mfma_f32_16x16x32_bf16 v[2:5], v[184:187], v[224:227], v[2:5]
	v_mfma_f32_16x16x32_bf16 v[18:21], v[184:187], v[216:219], v[18:21]
	v_mfma_f32_16x16x32_bf16 v[18:21], v[188:191], v[220:223], v[18:21]
	v_mfma_f32_16x16x32_bf16 v[22:25], v[180:183], v[220:223], v[22:25]
	v_mfma_f32_16x16x32_bf16 v[22:25], v[176:179], v[216:219], v[22:25]
	v_mfma_f32_16x16x32_bf16 v[38:41], v[176:179], v[208:211], v[38:41]
	v_mfma_f32_16x16x32_bf16 v[38:41], v[180:183], v[212:215], v[38:41]
	v_mfma_f32_16x16x32_bf16 v[34:37], v[188:191], v[212:215], v[34:37]
	v_mfma_f32_16x16x32_bf16 v[34:37], v[184:187], v[208:211], v[34:37]
	v_mfma_f32_16x16x32_bf16 v[50:53], v[184:187], v[192:195], v[50:53]
	v_mfma_f32_16x16x32_bf16 v[50:53], v[188:191], v[204:207], v[50:53]
	v_mfma_f32_16x16x32_bf16 v[54:57], v[180:183], v[204:207], v[54:57]
	v_mfma_f32_16x16x32_bf16 v[54:57], v[176:179], v[192:195], v[54:57]
	s_setprio 0
	s_barrier
	s_add_i32 s57, s57, 2
	s_add_u32 s20, s20, 0x100
	s_addc_u32 s21, s21, 0
	s_add_u32 s55, s55, 0x100
	s_addc_u32 s56, s56, 0
	s_cmp_gt_u32 s57, 61
	s_cbranch_scc0 .LBB0_2373
	s_and_b64 vcc, exec, s[16:17]
	s_cbranch_vccz .LBB0_2376
	s_barrier

.LBB0_2618:
	s_add_u32 s64, s28, 0xffd50000
	s_addc_u32 s65, s29, -1
	s_mov_b32 m0, s44
	ds_read_b128 v[142:145], v156
	global_load_lds_dwordx4 v130, s[64:65]
	s_mov_b32 m0, s45
	ds_read_b128 v[168:171], v156 offset:1024
	global_load_lds_dwordx4 v134, s[64:65]
	s_mov_b32 m0, s46
	ds_read_b128 v[172:175], v156 offset:2048
	global_load_lds_dwordx4 v138, s[28:29]
	s_mov_b32 m0, s47
	ds_read_b128 v[176:179], v156 offset:3072
	global_load_lds_dwordx4 v140, s[28:29]
	ds_read_b128 v[180:183], v157
	ds_read_b128 v[184:187], v157 offset:1024
	ds_read_b128 v[188:191], v157 offset:2048
	ds_read_b128 v[192:195], v157 offset:3072
	s_add_u32 s30, s28, 0xffd50080
	s_addc_u32 s31, s29, -1
	s_cmpk_eq_i32 s62, 0xa8
	s_cselect_b32 s35, s25, s31
	s_cselect_b32 s34, s24, s30
	s_cselect_b32 s31, s23, s61
	s_cselect_b32 s30, s22, s60
	ds_read_b128 v[196:199], v158
	ds_read_b128 v[200:203], v158 offset:1024
	ds_read_b128 v[204:207], v158 offset:2048
	ds_read_b128 v[208:211], v158 offset:3072
	ds_read_b128 v[212:215], v158 offset:4096
	ds_read_b128 v[216:219], v158 offset:5120
	ds_read_b128 v[220:223], v158 offset:6144
	ds_read_b128 v[224:227], v158 offset:7168
	s_waitcnt vmcnt(8)
	s_waitcnt lgkmcnt(0)
	s_barrier
	s_setprio 1
	s_waitcnt lgkmcnt(0)
	v_mfma_f32_16x16x32_bf16 v[126:129], v[142:145], v[196:199], v[126:129]
	v_mfma_f32_16x16x32_bf16 v[126:129], v[168:171], v[200:203], v[126:129]
	v_mfma_f32_16x16x32_bf16 v[122:125], v[176:179], v[200:203], v[122:125]
	v_mfma_f32_16x16x32_bf16 v[122:125], v[172:175], v[196:199], v[122:125]
	v_mfma_f32_16x16x32_bf16 v[106:109], v[172:175], v[204:207], v[106:109]
	v_mfma_f32_16x16x32_bf16 v[106:109], v[176:179], v[208:211], v[106:109]
	v_mfma_f32_16x16x32_bf16 v[110:113], v[168:171], v[208:211], v[110:113]
	v_mfma_f32_16x16x32_bf16 v[110:113], v[142:145], v[204:207], v[110:113]
	v_mfma_f32_16x16x32_bf16 v[94:97], v[142:145], v[212:215], v[94:97]
	v_mfma_f32_16x16x32_bf16 v[94:97], v[168:171], v[216:219], v[94:97]
	v_mfma_f32_16x16x32_bf16 v[90:93], v[176:179], v[216:219], v[90:93]
	v_mfma_f32_16x16x32_bf16 v[90:93], v[172:175], v[212:215], v[90:93]
	v_mfma_f32_16x16x32_bf16 v[74:77], v[172:175], v[220:223], v[74:77]
	v_mfma_f32_16x16x32_bf16 v[74:77], v[176:179], v[224:227], v[74:77]
	v_mfma_f32_16x16x32_bf16 v[78:81], v[168:171], v[224:227], v[78:81]
	v_mfma_f32_16x16x32_bf16 v[78:81], v[142:145], v[220:223], v[78:81]
	v_mfma_f32_16x16x32_bf16 v[70:73], v[180:183], v[220:223], v[70:73]
	v_mfma_f32_16x16x32_bf16 v[70:73], v[184:187], v[224:227], v[70:73]
	v_mfma_f32_16x16x32_bf16 v[66:69], v[192:195], v[224:227], v[66:69]
	v_mfma_f32_16x16x32_bf16 v[66:69], v[188:191], v[220:223], v[66:69]
	v_mfma_f32_16x16x32_bf16 v[82:85], v[188:191], v[212:215], v[82:85]
	v_mfma_f32_16x16x32_bf16 v[82:85], v[192:195], v[216:219], v[82:85]
	v_mfma_f32_16x16x32_bf16 v[86:89], v[184:187], v[216:219], v[86:89]
	v_mfma_f32_16x16x32_bf16 v[86:89], v[180:183], v[212:215], v[86:89]
	v_mfma_f32_16x16x32_bf16 v[102:105], v[180:183], v[204:207], v[102:105]
	v_mfma_f32_16x16x32_bf16 v[102:105], v[184:187], v[208:211], v[102:105]
	v_mfma_f32_16x16x32_bf16 v[98:101], v[192:195], v[208:211], v[98:101]
	v_mfma_f32_16x16x32_bf16 v[98:101], v[188:191], v[204:207], v[98:101]
	v_mfma_f32_16x16x32_bf16 v[114:117], v[188:191], v[196:199], v[114:117]
	v_mfma_f32_16x16x32_bf16 v[114:117], v[192:195], v[200:203], v[114:117]
	v_mfma_f32_16x16x32_bf16 v[118:121], v[184:187], v[200:203], v[118:121]
	v_mfma_f32_16x16x32_bf16 v[118:121], v[180:183], v[196:199], v[118:121]
	s_setprio 0
	s_barrier
	s_mov_b32 m0, s48
	s_add_u32 s64, s30, 0x2b0000
	global_load_lds_dwordx4 v132, s[30:31]
	s_mov_b32 m0, s49
	s_addc_u32 s65, s31, 0
	global_load_lds_dwordx4 v136, s[30:31]
	s_mov_b32 m0, s50
	ds_read_b128 v[196:199], v158 offset:16384
	global_load_lds_dwordx4 v132, s[64:65]
	s_mov_b32 m0, s51
	ds_read_b128 v[200:203], v158 offset:17408
	global_load_lds_dwordx4 v136, s[64:65]
	ds_read_b128 v[204:207], v158 offset:18432
	ds_read_b128 v[208:211], v158 offset:19456
	ds_read_b128 v[212:215], v158 offset:20480
	ds_read_b128 v[216:219], v158 offset:21504
	ds_read_b128 v[220:223], v158 offset:22528
	ds_read_b128 v[224:227], v158 offset:23552
	s_waitcnt vmcnt(6)
	s_waitcnt lgkmcnt(0)
	s_barrier
	s_setprio 1
	s_waitcnt lgkmcnt(0)
	v_mfma_f32_16x16x32_bf16 v[62:65], v[142:145], v[196:199], v[62:65]
	v_mfma_f32_16x16x32_bf16 v[62:65], v[168:171], v[200:203], v[62:65]
	v_mfma_f32_16x16x32_bf16 v[58:61], v[176:179], v[200:203], v[58:61]
	v_mfma_f32_16x16x32_bf16 v[58:61], v[172:175], v[196:199], v[58:61]
	v_mfma_f32_16x16x32_bf16 v[42:45], v[172:175], v[204:207], v[42:45]
	v_mfma_f32_16x16x32_bf16 v[42:45], v[176:179], v[208:211], v[42:45]
	v_mfma_f32_16x16x32_bf16 v[46:49], v[168:171], v[208:211], v[46:49]
	v_mfma_f32_16x16x32_bf16 v[46:49], v[142:145], v[204:207], v[46:49]
	v_mfma_f32_16x16x32_bf16 v[30:33], v[142:145], v[212:215], v[30:33]
	v_mfma_f32_16x16x32_bf16 v[30:33], v[168:171], v[216:219], v[30:33]
	v_mfma_f32_16x16x32_bf16 v[26:29], v[176:179], v[216:219], v[26:29]
	v_mfma_f32_16x16x32_bf16 v[26:29], v[172:175], v[212:215], v[26:29]
	v_mfma_f32_16x16x32_bf16 v[10:13], v[172:175], v[220:223], v[10:13]
	v_mfma_f32_16x16x32_bf16 v[10:13], v[176:179], v[224:227], v[10:13]
	v_mfma_f32_16x16x32_bf16 v[14:17], v[168:171], v[224:227], v[14:17]
	v_mfma_f32_16x16x32_bf16 v[14:17], v[142:145], v[220:223], v[14:17]
	v_mfma_f32_16x16x32_bf16 v[6:9], v[180:183], v[220:223], v[6:9]
	v_mfma_f32_16x16x32_bf16 v[6:9], v[184:187], v[224:227], v[6:9]
	v_mfma_f32_16x16x32_bf16 v[2:5], v[192:195], v[224:227], v[2:5]
	v_mfma_f32_16x16x32_bf16 v[2:5], v[188:191], v[220:223], v[2:5]
	v_mfma_f32_16x16x32_bf16 v[18:21], v[188:191], v[212:215], v[18:21]
	v_mfma_f32_16x16x32_bf16 v[18:21], v[192:195], v[216:219], v[18:21]
	v_mfma_f32_16x16x32_bf16 v[22:25], v[184:187], v[216:219], v[22:25]
	v_mfma_f32_16x16x32_bf16 v[22:25], v[180:183], v[212:215], v[22:25]
	v_mfma_f32_16x16x32_bf16 v[38:41], v[180:183], v[204:207], v[38:41]
	v_mfma_f32_16x16x32_bf16 v[38:41], v[184:187], v[208:211], v[38:41]
	v_mfma_f32_16x16x32_bf16 v[34:37], v[192:195], v[208:211], v[34:37]
	v_mfma_f32_16x16x32_bf16 v[34:37], v[188:191], v[204:207], v[34:37]
	v_mfma_f32_16x16x32_bf16 v[50:53], v[188:191], v[196:199], v[50:53]
	v_mfma_f32_16x16x32_bf16 v[50:53], v[192:195], v[200:203], v[50:53]
	v_mfma_f32_16x16x32_bf16 v[54:57], v[184:187], v[200:203], v[54:57]
	v_mfma_f32_16x16x32_bf16 v[54:57], v[180:183], v[196:199], v[54:57]
	s_setprio 0
	s_barrier
	s_mov_b32 m0, s39
	ds_read_b128 v[142:145], v159
	global_load_lds_dwordx4 v130, s[34:35]
	s_mov_b32 m0, s40
	ds_read_b128 v[168:171], v159 offset:1024
	global_load_lds_dwordx4 v134, s[34:35]
	s_add_u32 s34, s34, 0x2b0000
	s_addc_u32 s35, s35, 0
	s_mov_b32 m0, s41
	ds_read_b128 v[172:175], v159 offset:2048
	global_load_lds_dwordx4 v130, s[34:35]
	s_mov_b32 m0, s42
	ds_read_b128 v[176:179], v159 offset:3072
	global_load_lds_dwordx4 v134, s[34:35]
	ds_read_b128 v[180:183], v160
	ds_read_b128 v[184:187], v160 offset:1024
	ds_read_b128 v[188:191], v160 offset:2048
	ds_read_b128 v[192:195], v160 offset:3072
	ds_read_b128 v[196:199], v158 offset:32768
	ds_read_b128 v[200:203], v158 offset:33792
	ds_read_b128 v[204:207], v158 offset:34816
	ds_read_b128 v[208:211], v158 offset:35840
	ds_read_b128 v[212:215], v158 offset:36864
	ds_read_b128 v[216:219], v158 offset:37888
	ds_read_b128 v[220:223], v158 offset:38912
	ds_read_b128 v[224:227], v158 offset:39936
	s_waitcnt vmcnt(8)
	s_waitcnt lgkmcnt(0)
	s_barrier
	s_setprio 1
	s_waitcnt lgkmcnt(0)
	v_mfma_f32_16x16x32_bf16 v[126:129], v[142:145], v[196:199], v[126:129]
	v_mfma_f32_16x16x32_bf16 v[126:129], v[168:171], v[200:203], v[126:129]
	v_mfma_f32_16x16x32_bf16 v[122:125], v[176:179], v[200:203], v[122:125]
	v_mfma_f32_16x16x32_bf16 v[122:125], v[172:175], v[196:199], v[122:125]
	v_mfma_f32_16x16x32_bf16 v[106:109], v[172:175], v[204:207], v[106:109]
	v_mfma_f32_16x16x32_bf16 v[106:109], v[176:179], v[208:211], v[106:109]
	v_mfma_f32_16x16x32_bf16 v[110:113], v[168:171], v[208:211], v[110:113]
	v_mfma_f32_16x16x32_bf16 v[110:113], v[142:145], v[204:207], v[110:113]
	v_mfma_f32_16x16x32_bf16 v[94:97], v[142:145], v[212:215], v[94:97]
	v_mfma_f32_16x16x32_bf16 v[94:97], v[168:171], v[216:219], v[94:97]
	v_mfma_f32_16x16x32_bf16 v[90:93], v[176:179], v[216:219], v[90:93]
	v_mfma_f32_16x16x32_bf16 v[90:93], v[172:175], v[212:215], v[90:93]
	v_mfma_f32_16x16x32_bf16 v[74:77], v[172:175], v[220:223], v[74:77]
	v_mfma_f32_16x16x32_bf16 v[74:77], v[176:179], v[224:227], v[74:77]
	v_mfma_f32_16x16x32_bf16 v[78:81], v[168:171], v[224:227], v[78:81]
	v_mfma_f32_16x16x32_bf16 v[78:81], v[142:145], v[220:223], v[78:81]
	v_mfma_f32_16x16x32_bf16 v[70:73], v[180:183], v[220:223], v[70:73]
	v_mfma_f32_16x16x32_bf16 v[70:73], v[184:187], v[224:227], v[70:73]
	v_mfma_f32_16x16x32_bf16 v[66:69], v[192:195], v[224:227], v[66:69]
	v_mfma_f32_16x16x32_bf16 v[66:69], v[188:191], v[220:223], v[66:69]
	v_mfma_f32_16x16x32_bf16 v[82:85], v[188:191], v[212:215], v[82:85]
	v_mfma_f32_16x16x32_bf16 v[82:85], v[192:195], v[216:219], v[82:85]
	v_mfma_f32_16x16x32_bf16 v[86:89], v[184:187], v[216:219], v[86:89]
	v_mfma_f32_16x16x32_bf16 v[86:89], v[180:183], v[212:215], v[86:89]
	v_mfma_f32_16x16x32_bf16 v[102:105], v[180:183], v[204:207], v[102:105]
	v_mfma_f32_16x16x32_bf16 v[102:105], v[184:187], v[208:211], v[102:105]
	v_mfma_f32_16x16x32_bf16 v[98:101], v[192:195], v[208:211], v[98:101]
	v_mfma_f32_16x16x32_bf16 v[98:101], v[188:191], v[204:207], v[98:101]
	v_mfma_f32_16x16x32_bf16 v[114:117], v[188:191], v[196:199], v[114:117]
	v_mfma_f32_16x16x32_bf16 v[114:117], v[192:195], v[200:203], v[114:117]
	v_mfma_f32_16x16x32_bf16 v[118:121], v[184:187], v[200:203], v[118:121]
	v_mfma_f32_16x16x32_bf16 v[118:121], v[180:183], v[196:199], v[118:121]
	s_setprio 0
	s_barrier
	s_mov_b32 m0, s52
	s_add_u32 s30, s30, 0x80
	s_addc_u32 s31, s31, 0
	global_load_lds_dwordx4 v132, s[30:31]
	s_mov_b32 m0, s53
	ds_read_b128 v[196:199], v158 offset:49152
	global_load_lds_dwordx4 v136, s[30:31]
	s_mov_b32 m0, s54
	s_add_u32 s30, s30, 0x2b0000
	s_addc_u32 s31, s31, 0
	global_load_lds_dwordx4 v132, s[30:31]
	s_mov_b32 m0, s55
	ds_read_b128 v[200:203], v158 offset:50176
	global_load_lds_dwordx4 v136, s[30:31]
	ds_read_b128 v[204:207], v158 offset:51200
	ds_read_b128 v[208:211], v158 offset:52224
	ds_read_b128 v[212:215], v158 offset:53248
	ds_read_b128 v[216:219], v158 offset:54272
	ds_read_b128 v[220:223], v158 offset:55296
	ds_read_b128 v[224:227], v158 offset:56320
	s_waitcnt vmcnt(6)
	s_waitcnt lgkmcnt(0)
	s_barrier
	s_setprio 1
	s_waitcnt lgkmcnt(0)
	v_mfma_f32_16x16x32_bf16 v[62:65], v[142:145], v[196:199], v[62:65]
	v_mfma_f32_16x16x32_bf16 v[62:65], v[168:171], v[200:203], v[62:65]
	v_mfma_f32_16x16x32_bf16 v[58:61], v[176:179], v[200:203], v[58:61]
	v_mfma_f32_16x16x32_bf16 v[58:61], v[172:175], v[196:199], v[58:61]
	v_mfma_f32_16x16x32_bf16 v[42:45], v[172:175], v[204:207], v[42:45]
	v_mfma_f32_16x16x32_bf16 v[42:45], v[176:179], v[208:211], v[42:45]
	v_mfma_f32_16x16x32_bf16 v[46:49], v[168:171], v[208:211], v[46:49]
	v_mfma_f32_16x16x32_bf16 v[46:49], v[142:145], v[204:207], v[46:49]
	v_mfma_f32_16x16x32_bf16 v[30:33], v[142:145], v[212:215], v[30:33]
	v_mfma_f32_16x16x32_bf16 v[30:33], v[168:171], v[216:219], v[30:33]
	v_mfma_f32_16x16x32_bf16 v[26:29], v[176:179], v[216:219], v[26:29]
	v_mfma_f32_16x16x32_bf16 v[26:29], v[172:175], v[212:215], v[26:29]
	v_mfma_f32_16x16x32_bf16 v[10:13], v[172:175], v[220:223], v[10:13]
	v_mfma_f32_16x16x32_bf16 v[10:13], v[176:179], v[224:227], v[10:13]
	v_mfma_f32_16x16x32_bf16 v[14:17], v[168:171], v[224:227], v[14:17]
	v_mfma_f32_16x16x32_bf16 v[14:17], v[142:145], v[220:223], v[14:17]
	v_mfma_f32_16x16x32_bf16 v[6:9], v[180:183], v[220:223], v[6:9]
	v_mfma_f32_16x16x32_bf16 v[6:9], v[184:187], v[224:227], v[6:9]
	v_mfma_f32_16x16x32_bf16 v[2:5], v[192:195], v[224:227], v[2:5]
	v_mfma_f32_16x16x32_bf16 v[2:5], v[188:191], v[220:223], v[2:5]
	v_mfma_f32_16x16x32_bf16 v[18:21], v[188:191], v[212:215], v[18:21]
	v_mfma_f32_16x16x32_bf16 v[18:21], v[192:195], v[216:219], v[18:21]
	v_mfma_f32_16x16x32_bf16 v[22:25], v[184:187], v[216:219], v[22:25]
	v_mfma_f32_16x16x32_bf16 v[22:25], v[180:183], v[212:215], v[22:25]
	v_mfma_f32_16x16x32_bf16 v[38:41], v[180:183], v[204:207], v[38:41]
	v_mfma_f32_16x16x32_bf16 v[38:41], v[184:187], v[208:211], v[38:41]
	v_mfma_f32_16x16x32_bf16 v[34:37], v[192:195], v[208:211], v[34:37]
	v_mfma_f32_16x16x32_bf16 v[34:37], v[188:191], v[204:207], v[34:37]
	v_mfma_f32_16x16x32_bf16 v[50:53], v[188:191], v[196:199], v[50:53]
	v_mfma_f32_16x16x32_bf16 v[50:53], v[192:195], v[200:203], v[50:53]
	v_mfma_f32_16x16x32_bf16 v[54:57], v[184:187], v[200:203], v[54:57]
	v_mfma_f32_16x16x32_bf16 v[54:57], v[180:183], v[196:199], v[54:57]
	s_setprio 0
	s_barrier
	s_add_i32 s62, s62, 2
	s_add_u32 s28, s28, 0x100
	s_addc_u32 s29, s29, 0
	s_add_u32 s60, s60, 0x100
	s_addc_u32 s61, s61, 0
	s_cmpk_gt_u32 s62, 0xa9
	s_cbranch_scc0 .LBB0_2618
	s_and_b64 vcc, exec, s[12:13]
	s_cbranch_vccz .LBB0_2621
	s_barrier

.LBB0_2632:
	ds_read_b128 v[150:153], v1
	ds_read_b128 v[154:157], v1 offset:1024
	ds_read_b128 v[158:161], v1 offset:2048
	ds_read_b128 v[166:169], v1 offset:3072
	ds_read_b128 v[170:173], v139
	ds_read_b128 v[174:177], v139 offset:1024
	ds_read_b128 v[178:181], v139 offset:2048
	ds_read_b128 v[182:185], v139 offset:3072
	s_add_i32 s38, s13, 2
	s_add_u32 s12, s10, 0xc2050080
	s_addc_u32 s14, s11, -1
	s_cmp_lg_u32 s26, s13
	s_cselect_b32 s12, s12, 0
	s_cselect_b32 s13, s14, 0
	s_add_u32 s14, s4, s12
	s_addc_u32 s15, s5, s13
	s_add_u32 s12, s6, s12
	s_addc_u32 s13, s7, s13
	s_mov_b32 m0, s27
	v_lshl_add_u64 v[162:163], v[140:141], 0, s[10:11]
	ds_read_b128 v[186:189], v144
	ds_read_b128 v[190:193], v144 offset:1024
	ds_read_b128 v[194:197], v144 offset:2048
	ds_read_b128 v[198:201], v144 offset:3072
	ds_read_b128 v[202:205], v144 offset:4096
	ds_read_b128 v[206:209], v144 offset:5120
	ds_read_b128 v[210:213], v144 offset:6144
	ds_read_b128 v[214:217], v144 offset:7168
	global_load_lds_dwordx4 v[162:163], off
	v_lshl_add_u64 v[162:163], v[142:143], 0, s[10:11]
	s_mov_b32 m0, s28
	s_nop 0
	global_load_lds_dwordx4 v[162:163], off
	s_waitcnt vmcnt(8)
	s_waitcnt lgkmcnt(0)
	s_barrier
	s_setprio 1
	s_waitcnt lgkmcnt(0)
	v_mfma_f32_16x16x32_bf16 v[126:129], v[150:153], v[186:189], v[126:129]
	v_mfma_f32_16x16x32_bf16 v[126:129], v[154:157], v[190:193], v[126:129]
	v_mfma_f32_16x16x32_bf16 v[122:125], v[166:169], v[190:193], v[122:125]
	v_mfma_f32_16x16x32_bf16 v[122:125], v[158:161], v[186:189], v[122:125]
	v_mfma_f32_16x16x32_bf16 v[114:117], v[158:161], v[194:197], v[114:117]
	v_mfma_f32_16x16x32_bf16 v[114:117], v[166:169], v[198:201], v[114:117]
	v_mfma_f32_16x16x32_bf16 v[118:121], v[154:157], v[198:201], v[118:121]
	v_mfma_f32_16x16x32_bf16 v[118:121], v[150:153], v[194:197], v[118:121]
	v_mfma_f32_16x16x32_bf16 v[102:105], v[150:153], v[202:205], v[102:105]
	v_mfma_f32_16x16x32_bf16 v[102:105], v[154:157], v[206:209], v[102:105]
	v_mfma_f32_16x16x32_bf16 v[98:101], v[166:169], v[206:209], v[98:101]
	v_mfma_f32_16x16x32_bf16 v[98:101], v[158:161], v[202:205], v[98:101]
	v_mfma_f32_16x16x32_bf16 v[82:85], v[158:161], v[210:213], v[82:85]
	v_mfma_f32_16x16x32_bf16 v[82:85], v[166:169], v[214:217], v[82:85]
	v_mfma_f32_16x16x32_bf16 v[86:89], v[154:157], v[214:217], v[86:89]
	v_mfma_f32_16x16x32_bf16 v[86:89], v[150:153], v[210:213], v[86:89]
	v_mfma_f32_16x16x32_bf16 v[70:73], v[170:173], v[210:213], v[70:73]
	v_mfma_f32_16x16x32_bf16 v[70:73], v[174:177], v[214:217], v[70:73]
	v_mfma_f32_16x16x32_bf16 v[66:69], v[182:185], v[214:217], v[66:69]
	v_mfma_f32_16x16x32_bf16 v[66:69], v[178:181], v[210:213], v[66:69]
	v_mfma_f32_16x16x32_bf16 v[74:77], v[178:181], v[202:205], v[74:77]
	v_mfma_f32_16x16x32_bf16 v[74:77], v[182:185], v[206:209], v[74:77]
	v_mfma_f32_16x16x32_bf16 v[78:81], v[174:177], v[206:209], v[78:81]
	v_mfma_f32_16x16x32_bf16 v[78:81], v[170:173], v[202:205], v[78:81]
	v_mfma_f32_16x16x32_bf16 v[94:97], v[170:173], v[194:197], v[94:97]
	v_mfma_f32_16x16x32_bf16 v[94:97], v[174:177], v[198:201], v[94:97]
	v_mfma_f32_16x16x32_bf16 v[90:93], v[182:185], v[198:201], v[90:93]
	v_mfma_f32_16x16x32_bf16 v[90:93], v[178:181], v[194:197], v[90:93]
	v_mfma_f32_16x16x32_bf16 v[106:109], v[178:181], v[186:189], v[106:109]
	v_mfma_f32_16x16x32_bf16 v[106:109], v[182:185], v[190:193], v[106:109]
	v_mfma_f32_16x16x32_bf16 v[110:113], v[174:177], v[190:193], v[110:113]
	v_mfma_f32_16x16x32_bf16 v[110:113], v[170:173], v[186:189], v[110:113]
	s_setprio 0
	s_barrier
	s_mov_b32 m0, s29
	v_lshl_add_u64 v[162:163], s[12:13], 0, v[132:133]
	s_add_u32 s40, s12, 0x2b0000
	ds_read_b128 v[186:189], v144 offset:16384
	ds_read_b128 v[190:193], v144 offset:17408
	ds_read_b128 v[194:197], v144 offset:18432
	ds_read_b128 v[198:201], v144 offset:19456
	ds_read_b128 v[202:205], v144 offset:20480
	ds_read_b128 v[206:209], v144 offset:21504
	ds_read_b128 v[210:213], v144 offset:22528
	ds_read_b128 v[214:217], v144 offset:23552
	global_load_lds_dwordx4 v[162:163], off
	v_lshl_add_u64 v[218:219], s[12:13], 0, v[136:137]
	s_mov_b32 m0, s30
	s_addc_u32 s41, s13, 0
	global_load_lds_dwordx4 v[218:219], off
	v_lshl_add_u64 v[220:221], s[40:41], 0, v[132:133]
	s_mov_b32 m0, s31
	v_lshl_add_u64 v[222:223], s[14:15], 0, v[134:135]
	global_load_lds_dwordx4 v[220:221], off
	v_lshl_add_u64 v[220:221], s[40:41], 0, v[136:137]
	s_mov_b32 m0, s33
	s_nop 0
	global_load_lds_dwordx4 v[220:221], off
	v_lshl_add_u64 v[220:221], s[14:15], 0, v[130:131]
	s_mov_b32 m0, s19
	s_nop 0
	global_load_lds_dwordx4 v[220:221], off
	s_mov_b32 m0, s20
	s_nop 0
	global_load_lds_dwordx4 v[222:223], off
	s_waitcnt vmcnt(8)
	s_waitcnt lgkmcnt(0)
	s_barrier
	s_setprio 1
	s_waitcnt lgkmcnt(0)
	v_mfma_f32_16x16x32_bf16 v[62:65], v[150:153], v[186:189], v[62:65]
	v_mfma_f32_16x16x32_bf16 v[62:65], v[154:157], v[190:193], v[62:65]
	v_mfma_f32_16x16x32_bf16 v[58:61], v[166:169], v[190:193], v[58:61]
	v_mfma_f32_16x16x32_bf16 v[58:61], v[158:161], v[186:189], v[58:61]
	v_mfma_f32_16x16x32_bf16 v[50:53], v[158:161], v[194:197], v[50:53]
	v_mfma_f32_16x16x32_bf16 v[50:53], v[166:169], v[198:201], v[50:53]
	v_mfma_f32_16x16x32_bf16 v[54:57], v[154:157], v[198:201], v[54:57]
	v_mfma_f32_16x16x32_bf16 v[54:57], v[150:153], v[194:197], v[54:57]
	v_mfma_f32_16x16x32_bf16 v[38:41], v[150:153], v[202:205], v[38:41]
	v_mfma_f32_16x16x32_bf16 v[38:41], v[154:157], v[206:209], v[38:41]
	v_mfma_f32_16x16x32_bf16 v[34:37], v[166:169], v[206:209], v[34:37]
	v_mfma_f32_16x16x32_bf16 v[34:37], v[158:161], v[202:205], v[34:37]
	v_mfma_f32_16x16x32_bf16 v[18:21], v[158:161], v[210:213], v[18:21]
	v_mfma_f32_16x16x32_bf16 v[18:21], v[166:169], v[214:217], v[18:21]
	v_mfma_f32_16x16x32_bf16 v[22:25], v[154:157], v[214:217], v[22:25]
	v_mfma_f32_16x16x32_bf16 v[22:25], v[150:153], v[210:213], v[22:25]
	v_mfma_f32_16x16x32_bf16 v[6:9], v[170:173], v[210:213], v[6:9]
	v_mfma_f32_16x16x32_bf16 v[6:9], v[174:177], v[214:217], v[6:9]
	v_mfma_f32_16x16x32_bf16 v[2:5], v[182:185], v[214:217], v[2:5]
	v_mfma_f32_16x16x32_bf16 v[2:5], v[178:181], v[210:213], v[2:5]
	v_mfma_f32_16x16x32_bf16 v[10:13], v[178:181], v[202:205], v[10:13]
	v_mfma_f32_16x16x32_bf16 v[10:13], v[182:185], v[206:209], v[10:13]
	v_mfma_f32_16x16x32_bf16 v[14:17], v[174:177], v[206:209], v[14:17]
	v_mfma_f32_16x16x32_bf16 v[14:17], v[170:173], v[202:205], v[14:17]
	v_mfma_f32_16x16x32_bf16 v[30:33], v[170:173], v[194:197], v[30:33]
	v_mfma_f32_16x16x32_bf16 v[30:33], v[174:177], v[198:201], v[30:33]
	v_mfma_f32_16x16x32_bf16 v[26:29], v[182:185], v[198:201], v[26:29]
	v_mfma_f32_16x16x32_bf16 v[26:29], v[178:181], v[194:197], v[26:29]
	v_mfma_f32_16x16x32_bf16 v[42:45], v[178:181], v[186:189], v[42:45]
	v_mfma_f32_16x16x32_bf16 v[42:45], v[182:185], v[190:193], v[42:45]
	v_mfma_f32_16x16x32_bf16 v[46:49], v[174:177], v[190:193], v[46:49]
	v_mfma_f32_16x16x32_bf16 v[46:49], v[170:173], v[186:189], v[46:49]
	s_setprio 0
	s_barrier
	ds_read_b128 v[150:153], v145
	ds_read_b128 v[154:157], v145 offset:1024
	ds_read_b128 v[158:161], v145 offset:2048
	ds_read_b128 v[166:169], v145 offset:3072
	ds_read_b128 v[170:173], v146
	ds_read_b128 v[174:177], v146 offset:1024
	ds_read_b128 v[178:181], v146 offset:2048
	ds_read_b128 v[182:185], v146 offset:3072
	s_add_u32 s14, s14, 0x2b0000
	s_addc_u32 s15, s15, 0
	s_mov_b32 m0, s21
	v_lshl_add_u64 v[224:225], s[14:15], 0, v[130:131]
	ds_read_b128 v[186:189], v144 offset:32768
	ds_read_b128 v[190:193], v144 offset:33792
	ds_read_b128 v[194:197], v144 offset:34816
	ds_read_b128 v[198:201], v144 offset:35840
	ds_read_b128 v[202:205], v144 offset:36864
	ds_read_b128 v[206:209], v144 offset:37888
	ds_read_b128 v[210:213], v144 offset:38912
	ds_read_b128 v[214:217], v144 offset:39936
	global_load_lds_dwordx4 v[224:225], off
	v_lshl_add_u64 v[224:225], s[14:15], 0, v[134:135]
	s_mov_b32 m0, s22
	s_nop 0
	global_load_lds_dwordx4 v[224:225], off
	s_waitcnt vmcnt(8)
	s_waitcnt lgkmcnt(0)
	s_barrier
	s_setprio 1
	s_waitcnt lgkmcnt(0)
	v_mfma_f32_16x16x32_bf16 v[126:129], v[150:153], v[186:189], v[126:129]
	v_mfma_f32_16x16x32_bf16 v[126:129], v[154:157], v[190:193], v[126:129]
	v_mfma_f32_16x16x32_bf16 v[122:125], v[166:169], v[190:193], v[122:125]
	v_mfma_f32_16x16x32_bf16 v[122:125], v[158:161], v[186:189], v[122:125]
	v_mfma_f32_16x16x32_bf16 v[114:117], v[158:161], v[194:197], v[114:117]
	v_mfma_f32_16x16x32_bf16 v[114:117], v[166:169], v[198:201], v[114:117]
	v_mfma_f32_16x16x32_bf16 v[118:121], v[154:157], v[198:201], v[118:121]
	v_mfma_f32_16x16x32_bf16 v[118:121], v[150:153], v[194:197], v[118:121]
	v_mfma_f32_16x16x32_bf16 v[102:105], v[150:153], v[202:205], v[102:105]
	v_mfma_f32_16x16x32_bf16 v[102:105], v[154:157], v[206:209], v[102:105]
	v_mfma_f32_16x16x32_bf16 v[98:101], v[166:169], v[206:209], v[98:101]
	v_mfma_f32_16x16x32_bf16 v[98:101], v[158:161], v[202:205], v[98:101]
	v_mfma_f32_16x16x32_bf16 v[82:85], v[158:161], v[210:213], v[82:85]
	v_mfma_f32_16x16x32_bf16 v[82:85], v[166:169], v[214:217], v[82:85]
	v_mfma_f32_16x16x32_bf16 v[86:89], v[154:157], v[214:217], v[86:89]
	v_mfma_f32_16x16x32_bf16 v[86:89], v[150:153], v[210:213], v[86:89]
	v_mfma_f32_16x16x32_bf16 v[70:73], v[170:173], v[210:213], v[70:73]
	v_mfma_f32_16x16x32_bf16 v[70:73], v[174:177], v[214:217], v[70:73]
	v_mfma_f32_16x16x32_bf16 v[66:69], v[182:185], v[214:217], v[66:69]
	v_mfma_f32_16x16x32_bf16 v[66:69], v[178:181], v[210:213], v[66:69]
	v_mfma_f32_16x16x32_bf16 v[74:77], v[178:181], v[202:205], v[74:77]
	v_mfma_f32_16x16x32_bf16 v[74:77], v[182:185], v[206:209], v[74:77]
	v_mfma_f32_16x16x32_bf16 v[78:81], v[174:177], v[206:209], v[78:81]
	v_mfma_f32_16x16x32_bf16 v[78:81], v[170:173], v[202:205], v[78:81]
	v_mfma_f32_16x16x32_bf16 v[94:97], v[170:173], v[194:197], v[94:97]
	v_mfma_f32_16x16x32_bf16 v[94:97], v[174:177], v[198:201], v[94:97]
	v_mfma_f32_16x16x32_bf16 v[90:93], v[182:185], v[198:201], v[90:93]
	v_mfma_f32_16x16x32_bf16 v[90:93], v[178:181], v[194:197], v[90:93]
	v_mfma_f32_16x16x32_bf16 v[106:109], v[178:181], v[186:189], v[106:109]
	v_mfma_f32_16x16x32_bf16 v[106:109], v[182:185], v[190:193], v[106:109]
	v_mfma_f32_16x16x32_bf16 v[110:113], v[174:177], v[190:193], v[110:113]
	v_mfma_f32_16x16x32_bf16 v[110:113], v[170:173], v[186:189], v[110:113]
	s_setprio 0
	s_barrier
	s_mov_b32 m0, s34
	v_lshl_add_u64 v[162:163], v[162:163], 0, s[8:9]
	s_add_u32 s12, s12, 0x2b0080
	ds_read_b128 v[186:189], v144 offset:49152
	ds_read_b128 v[190:193], v144 offset:50176
	ds_read_b128 v[194:197], v144 offset:51200
	ds_read_b128 v[198:201], v144 offset:52224
	ds_read_b128 v[202:205], v144 offset:53248
	ds_read_b128 v[206:209], v144 offset:54272
	ds_read_b128 v[210:213], v144 offset:55296
	ds_read_b128 v[214:217], v144 offset:56320
	global_load_lds_dwordx4 v[162:163], off
	v_lshl_add_u64 v[162:163], v[218:219], 0, s[8:9]
	s_mov_b32 m0, s35
	s_addc_u32 s13, s13, 0
	global_load_lds_dwordx4 v[162:163], off
	v_lshl_add_u64 v[162:163], s[12:13], 0, v[132:133]
	s_mov_b32 m0, s36
	s_nop 0
	global_load_lds_dwordx4 v[162:163], off
	v_lshl_add_u64 v[162:163], s[12:13], 0, v[136:137]
	s_mov_b32 m0, s37
	s_nop 0
	global_load_lds_dwordx4 v[162:163], off
	v_lshl_add_u64 v[162:163], v[220:221], 0, s[8:9]
	s_mov_b32 m0, s24
	s_nop 0
	global_load_lds_dwordx4 v[162:163], off
	v_lshl_add_u64 v[162:163], v[222:223], 0, s[8:9]
	s_mov_b32 m0, s25
	s_nop 0
	global_load_lds_dwordx4 v[162:163], off
	s_waitcnt vmcnt(8)
	s_waitcnt lgkmcnt(0)
	s_barrier
	s_setprio 1
	s_waitcnt lgkmcnt(0)
	v_mfma_f32_16x16x32_bf16 v[62:65], v[150:153], v[186:189], v[62:65]
	v_mfma_f32_16x16x32_bf16 v[62:65], v[154:157], v[190:193], v[62:65]
	v_mfma_f32_16x16x32_bf16 v[58:61], v[166:169], v[190:193], v[58:61]
	v_mfma_f32_16x16x32_bf16 v[58:61], v[158:161], v[186:189], v[58:61]
	v_mfma_f32_16x16x32_bf16 v[50:53], v[158:161], v[194:197], v[50:53]
	v_mfma_f32_16x16x32_bf16 v[50:53], v[166:169], v[198:201], v[50:53]
	v_mfma_f32_16x16x32_bf16 v[54:57], v[154:157], v[198:201], v[54:57]
	v_mfma_f32_16x16x32_bf16 v[54:57], v[150:153], v[194:197], v[54:57]
	v_mfma_f32_16x16x32_bf16 v[38:41], v[150:153], v[202:205], v[38:41]
	v_mfma_f32_16x16x32_bf16 v[38:41], v[154:157], v[206:209], v[38:41]
	v_mfma_f32_16x16x32_bf16 v[34:37], v[166:169], v[206:209], v[34:37]
	v_mfma_f32_16x16x32_bf16 v[34:37], v[158:161], v[202:205], v[34:37]
	v_mfma_f32_16x16x32_bf16 v[18:21], v[158:161], v[210:213], v[18:21]
	v_mfma_f32_16x16x32_bf16 v[18:21], v[166:169], v[214:217], v[18:21]
	v_mfma_f32_16x16x32_bf16 v[22:25], v[154:157], v[214:217], v[22:25]
	v_mfma_f32_16x16x32_bf16 v[22:25], v[150:153], v[210:213], v[22:25]
	v_mfma_f32_16x16x32_bf16 v[6:9], v[170:173], v[210:213], v[6:9]
	v_mfma_f32_16x16x32_bf16 v[6:9], v[174:177], v[214:217], v[6:9]
	v_mfma_f32_16x16x32_bf16 v[2:5], v[182:185], v[214:217], v[2:5]
	v_mfma_f32_16x16x32_bf16 v[2:5], v[178:181], v[210:213], v[2:5]
	v_mfma_f32_16x16x32_bf16 v[10:13], v[178:181], v[202:205], v[10:13]
	v_mfma_f32_16x16x32_bf16 v[10:13], v[182:185], v[206:209], v[10:13]
	v_mfma_f32_16x16x32_bf16 v[14:17], v[174:177], v[206:209], v[14:17]
	v_mfma_f32_16x16x32_bf16 v[14:17], v[170:173], v[202:205], v[14:17]
	v_mfma_f32_16x16x32_bf16 v[30:33], v[170:173], v[194:197], v[30:33]
	v_mfma_f32_16x16x32_bf16 v[30:33], v[174:177], v[198:201], v[30:33]
	v_mfma_f32_16x16x32_bf16 v[26:29], v[182:185], v[198:201], v[26:29]
	v_mfma_f32_16x16x32_bf16 v[26:29], v[178:181], v[194:197], v[26:29]
	v_mfma_f32_16x16x32_bf16 v[42:45], v[178:181], v[186:189], v[42:45]
	v_mfma_f32_16x16x32_bf16 v[42:45], v[182:185], v[190:193], v[42:45]
	v_mfma_f32_16x16x32_bf16 v[46:49], v[174:177], v[190:193], v[46:49]
	v_mfma_f32_16x16x32_bf16 v[46:49], v[170:173], v[186:189], v[46:49]
	s_setprio 0
	s_barrier
	s_add_u32 s10, s10, 0x100
	s_addc_u32 s11, s11, 0
	s_cmp_ge_u32 s38, s17
	s_mov_b32 s13, s38
	s_cbranch_scc0 .LBB0_2632
	s_lshl_b32 s4, s16, 21
	v_readlane_b32 s2, v249, 29
	v_lshl_or_b32 v1, s18, 8, v148
	v_mov_b32_e32 v139, 0
	s_add_u32 s4, s2, s4
	v_readlane_b32 s2, v249, 31
	v_or_b32_e32 v130, s23, v1
	v_cvt_pk_bf16_f32 v70, v70, v71
	v_cvt_pk_bf16_f32 v71, v72, v73
	v_cvt_pk_bf16_f32 v72, v66, v67
	v_add_u32_e32 v66, 0x80, v138
	v_mov_b32_e32 v67, v139
	s_addc_u32 s5, s2, 0
	v_ashrrev_i32_e32 v131, 31, v130
	v_lshlrev_b64 v[132:133], 13, v[138:139]
	v_cvt_pk_bf16_f32 v110, v110, v111
	v_cvt_pk_bf16_f32 v111, v112, v113
	v_cvt_pk_bf16_f32 v112, v106, v107
	v_or_b32_e32 v106, 16, v138
	v_mov_b32_e32 v107, v139
	v_lshlrev_b64 v[66:67], 13, v[66:67]
	v_cvt_pk_bf16_f32 v46, v46, v47
	v_cvt_pk_bf16_f32 v47, v48, v49
	v_cvt_pk_bf16_f32 v48, v42, v43
	v_add_u32_e32 v42, 0x90, v138
	v_mov_b32_e32 v43, v139
	v_lshl_add_u64 v[132:133], s[4:5], 0, v[132:133]
	v_lshlrev_b64 v[130:131], 1, v[130:131]
	v_lshlrev_b64 v[106:107], 13, v[106:107]
	v_cvt_pk_bf16_f32 v94, v94, v95
	v_cvt_pk_bf16_f32 v95, v96, v97
	v_cvt_pk_bf16_f32 v96, v90, v91
	v_or_b32_e32 v90, 32, v138
	v_mov_b32_e32 v91, v139
	v_lshl_add_u64 v[66:67], s[4:5], 0, v[66:67]
	v_lshlrev_b64 v[42:43], 13, v[42:43]
	v_cvt_pk_bf16_f32 v30, v30, v31
	v_cvt_pk_bf16_f32 v31, v32, v33
	v_cvt_pk_bf16_f32 v32, v26, v27
	v_add_u32_e32 v26, 0xa0, v138
	v_mov_b32_e32 v27, v139
	v_lshl_add_u64 v[132:133], v[132:133], 0, v[130:131]
	v_cvt_pk_bf16_f32 v113, v108, v109
	v_lshl_add_u64 v[106:107], s[4:5], 0, v[106:107]
	v_lshlrev_b64 v[90:91], 13, v[90:91]
	v_cvt_pk_bf16_f32 v78, v78, v79
	v_cvt_pk_bf16_f32 v79, v80, v81
	v_cvt_pk_bf16_f32 v80, v74, v75
	v_or_b32_e32 v74, 48, v138
	v_mov_b32_e32 v75, v139
	v_lshl_add_u64 v[66:67], v[66:67], 0, v[130:131]
	v_cvt_pk_bf16_f32 v49, v44, v45
	v_lshl_add_u64 v[42:43], s[4:5], 0, v[42:43]
	v_lshlrev_b64 v[26:27], 13, v[26:27]
	v_add_u32_e32 v138, 0xb0, v138
	global_store_dwordx4 v[132:133], v[110:113], off offset:256
	v_cvt_pk_bf16_f32 v97, v92, v93
	v_lshl_add_u64 v[90:91], s[4:5], 0, v[90:91]
	v_lshl_add_u64 v[110:111], v[106:107], 0, v[130:131]
	v_lshlrev_b64 v[74:75], 13, v[74:75]
	global_store_dwordx4 v[66:67], v[46:49], off offset:256
	v_cvt_pk_bf16_f32 v33, v28, v29
	v_lshl_add_u64 v[26:27], s[4:5], 0, v[26:27]
	v_lshl_add_u64 v[46:47], v[42:43], 0, v[130:131]
	v_cvt_pk_bf16_f32 v14, v14, v15
	v_cvt_pk_bf16_f32 v15, v16, v17
	v_cvt_pk_bf16_f32 v16, v10, v11
	v_lshlrev_b64 v[10:11], 13, v[138:139]
	global_store_dwordx4 v[110:111], v[94:97], off offset:256
	v_cvt_pk_bf16_f32 v81, v76, v77
	v_lshl_add_u64 v[74:75], s[4:5], 0, v[74:75]
	v_lshl_add_u64 v[94:95], v[90:91], 0, v[130:131]
	global_store_dwordx4 v[46:47], v[30:33], off offset:256
	v_cvt_pk_bf16_f32 v17, v12, v13
	v_lshl_add_u64 v[10:11], s[4:5], 0, v[10:11]
	v_lshl_add_u64 v[30:31], v[26:27], 0, v[130:131]
	v_cvt_pk_bf16_f32 v126, v126, v127
	v_cvt_pk_bf16_f32 v127, v128, v129
	v_cvt_pk_bf16_f32 v128, v122, v123
	v_cvt_pk_bf16_f32 v129, v124, v125
	v_cvt_pk_bf16_f32 v106, v118, v119
	v_cvt_pk_bf16_f32 v107, v120, v121
	v_cvt_pk_bf16_f32 v108, v114, v115
	v_cvt_pk_bf16_f32 v109, v116, v117
	v_cvt_pk_bf16_f32 v90, v102, v103
	v_cvt_pk_bf16_f32 v91, v104, v105
	v_cvt_pk_bf16_f32 v92, v98, v99
	v_cvt_pk_bf16_f32 v93, v100, v101
	global_store_dwordx4 v[94:95], v[78:81], off offset:256
	v_cvt_pk_bf16_f32 v76, v82, v83
	v_cvt_pk_bf16_f32 v77, v84, v85
	v_lshl_add_u64 v[78:79], v[74:75], 0, v[130:131]
	v_cvt_pk_bf16_f32 v74, v86, v87
	v_cvt_pk_bf16_f32 v75, v88, v89
	v_cvt_pk_bf16_f32 v73, v68, v69
	v_cvt_pk_bf16_f32 v62, v62, v63
	v_cvt_pk_bf16_f32 v63, v64, v65
	v_cvt_pk_bf16_f32 v64, v58, v59
	v_cvt_pk_bf16_f32 v65, v60, v61
	v_cvt_pk_bf16_f32 v42, v54, v55
	v_cvt_pk_bf16_f32 v43, v56, v57
	v_cvt_pk_bf16_f32 v44, v50, v51
	v_cvt_pk_bf16_f32 v45, v52, v53
	v_cvt_pk_bf16_f32 v26, v38, v39
	v_cvt_pk_bf16_f32 v27, v40, v41
	v_cvt_pk_bf16_f32 v28, v34, v35
	v_cvt_pk_bf16_f32 v29, v36, v37
	global_store_dwordx4 v[30:31], v[14:17], off offset:256
	v_cvt_pk_bf16_f32 v12, v18, v19
	v_cvt_pk_bf16_f32 v13, v20, v21
	v_lshl_add_u64 v[14:15], v[10:11], 0, v[130:131]
	v_cvt_pk_bf16_f32 v10, v22, v23
	v_cvt_pk_bf16_f32 v11, v24, v25
	v_cvt_pk_bf16_f32 v6, v6, v7
	v_cvt_pk_bf16_f32 v7, v8, v9
	v_cvt_pk_bf16_f32 v8, v2, v3
	v_cvt_pk_bf16_f32 v9, v4, v5
	global_store_dwordx4 v[132:133], v[126:129], off
	global_store_dwordx4 v[110:111], v[106:109], off
	global_store_dwordx4 v[94:95], v[90:93], off
	global_store_dwordx4 v[78:79], v[74:77], off
	global_store_dwordx4 v[78:79], v[70:73], off offset:256
	global_store_dwordx4 v[66:67], v[62:65], off
	global_store_dwordx4 v[46:47], v[42:45], off
	global_store_dwordx4 v[30:31], v[26:29], off
	global_store_dwordx4 v[14:15], v[10:13], off
	global_store_dwordx4 v[14:15], v[6:9], off offset:256
	s_waitcnt vmcnt(0)
	s_cmpk_lt_u32 s3, 0x100
	s_cbranch_scc0 .LBB0_2635
	s_barrier
